# v030
# speedup vs baseline: 1.0229x; 1.0103x over previous
; #define MFMA(a, b, c) __builtin_amdgcn_mfma_f32_16x16x32_bf16((a), (b), (c), 0, 0, 0)
; template <int EPI, int MF>
; __device__ __forceinline__ void gemm_part(const u16* __restrict__ A, int lda, const u16* __restrict__ Bt, int K, int ntn, GemmEpi ep, char* smem,
;                                           int mbase, int mrows) {
;     ...
;     GEMM_ISSUE(0);
;     GEMM_ISSUE(1);
;     for (int kt = 0; kt < nk; ++kt) {
;       if (kt + 1 < nk) {
;         if (MF == 8) asm volatile("s_waitcnt vmcnt(6)" ::: "memory");
;         else asm volatile("s_waitcnt vmcnt(3)" ::: "memory");
;       } else asm volatile("s_waitcnt vmcnt(0)" ::: "memory");
;       asm volatile("s_waitcnt lgkmcnt(0)" ::: "memory");
;       __builtin_amdgcn_s_barrier();
;       const u16* a_ = sbase + (kt % 3) * STG;
;       const u16* b_ = a_ + BM * 32;
;       bf16x8 bfr[4], afc[2], afn[2];
;       const u16* ap_ = a_ + (wr * (16 * MF) + fr) * 32 + fq * 8;
; #pragma unroll
;       for (int n = 0; n < 4; ++n) bfr[n] = rd_std(b_ + (wc * 64 + n * 16 + fr) * 32 + fq * 8);
;       afc[0] = rd_std(ap_); afc[1] = rd_std(ap_ + 16 * 32);
;       __builtin_amdgcn_sched_barrier(0);
;       if (kt + 2 < nk) GEMM_ISSUE(kt + 2);
;       __builtin_amdgcn_sched_barrier(0);
; #pragma unroll
;       for (int mh = 0; mh < MF / 2; ++mh) {
;         if (mh + 1 < MF / 2) {
;           afn[0] = rd_std(ap_ + ((mh + 1) * 2) * 16 * 32);
;           afn[1] = rd_std(ap_ + ((mh + 1) * 2 + 1) * 16 * 32);
;         }
;         __builtin_amdgcn_sched_barrier(0);
; #pragma unroll
;         for (int m = 0; m < 2; ++m)
; #pragma unroll
;           for (int n = 0; n < 4; ++n) acc[mh * 2 + m][n] = MFMA(bfr[n], afc[m], acc[mh * 2 + m][n]);
;         __builtin_amdgcn_sched_barrier(0);
;         afc[0] = afn[0]; afc[1] = afn[1];
;       }
.LBB0_135:
	s_mul_i32 s12, s11, 0xab
	s_add_i32 s13, s12, 0xfeaa
	s_bfe_u32 s13, s13, 0x70009
	s_mul_i32 s13, s13, 3
	s_sub_i32 s13, s11, s13
	s_add_i32 s13, s13, 0xfffe
	s_and_b32 s13, s13, 0xff
	s_mulk_i32 s13, 0x6000
	v_add_u32_e32 v152, s13, v168
	v_add_u32_e32 v150, s13, v156
	s_bfe_u32 s12, s12, 0x70009
	s_mul_i32 s12, s12, 3
	s_sub_i32 s12, s11, s12
	s_and_b32 s12, s12, 0xff
	s_mulk_i32 s12, 0x6000
	v_add_u32_e32 v186, s12, v151
	v_lshl_add_u64 v[170:171], s[4:5], 1, v[148:149]
	v_readfirstlane_b32 s101, v186
	v_lshl_add_u64 v[172:173], v[170:171], 0, s[74:75]
	v_lshl_add_u64 v[174:175], v[170:171], 0, s[92:93]
	v_lshl_add_u64 v[176:177], v[170:171], 0, s[88:89]
	v_lshl_add_u64 v[170:171], v[170:171], 0, s[6:7]
	v_lshl_add_u64 v[178:179], s[4:5], 1, v[146:147]
	v_lshl_add_u64 v[180:181], v[178:179], 0, s[74:75]
	v_lshl_add_u64 v[178:179], v[178:179], 0, s[92:93]
	s_waitcnt vmcnt(6)
	s_waitcnt lgkmcnt(0)
	s_barrier
	s_setprio 2
	s_mov_b32 m0, s101
	s_nop 0
	global_load_lds_dwordx4 v[172:173], off
	s_add_u32 m0, m0, 0x1000
	s_nop 0
	global_load_lds_dwordx4 v[174:175], off
	s_add_u32 m0, m0, 0x1000
	s_nop 0
	global_load_lds_dwordx4 v[176:177], off
	s_add_u32 m0, m0, 0x1000
	s_nop 0
	global_load_lds_dwordx4 v[170:171], off
	s_add_u32 m0, m0, 0x1000
	s_nop 0
	global_load_lds_dwordx4 v[180:181], off
	s_add_u32 m0, m0, 0x1000
	s_nop 0
	global_load_lds_dwordx4 v[178:179], off
	s_setprio 0
	ds_read_b128 v[170:173], v152 offset:16384
	ds_read_b128 v[174:177], v152 offset:17408
	ds_read_b128 v[178:181], v152 offset:18432
	ds_read_b128 v[182:185], v152 offset:19456
	ds_read_b128 v[186:189], v150
	ds_read_b128 v[190:193], v150 offset:1024
	ds_read_b128 v[194:197], v150 offset:2048
	ds_read_b128 v[210:213], v150 offset:3072
	s_waitcnt lgkmcnt(2)
	v_mfma_f32_16x16x32_bf16 v[126:129], v[170:173], v[186:189], v[126:129]
	v_mfma_f32_16x16x32_bf16 v[122:125], v[174:177], v[186:189], v[122:125]
	v_mfma_f32_16x16x32_bf16 v[118:121], v[178:181], v[186:189], v[118:121]
	v_mfma_f32_16x16x32_bf16 v[114:117], v[182:185], v[186:189], v[114:117]
	v_mfma_f32_16x16x32_bf16 v[110:113], v[170:173], v[190:193], v[110:113]
	v_mfma_f32_16x16x32_bf16 v[106:109], v[174:177], v[190:193], v[106:109]
	v_mfma_f32_16x16x32_bf16 v[102:105], v[178:181], v[190:193], v[102:105]
	v_mfma_f32_16x16x32_bf16 v[98:101], v[182:185], v[190:193], v[98:101]
	ds_read_b128 v[186:189], v150 offset:4096
	ds_read_b128 v[190:193], v150 offset:5120
	s_waitcnt lgkmcnt(2)
	v_mfma_f32_16x16x32_bf16 v[94:97], v[170:173], v[194:197], v[94:97]
	v_mfma_f32_16x16x32_bf16 v[90:93], v[174:177], v[194:197], v[90:93]
	v_mfma_f32_16x16x32_bf16 v[86:89], v[178:181], v[194:197], v[86:89]
	v_mfma_f32_16x16x32_bf16 v[82:85], v[182:185], v[194:197], v[82:85]
	v_mfma_f32_16x16x32_bf16 v[78:81], v[170:173], v[210:213], v[78:81]
	v_mfma_f32_16x16x32_bf16 v[74:77], v[174:177], v[210:213], v[74:77]
	v_mfma_f32_16x16x32_bf16 v[70:73], v[178:181], v[210:213], v[70:73]
	v_mfma_f32_16x16x32_bf16 v[66:69], v[182:185], v[210:213], v[66:69]
	ds_read_b128 v[194:197], v150 offset:6144
	ds_read_b128 v[210:213], v150 offset:7168
	s_waitcnt lgkmcnt(2)
	v_mfma_f32_16x16x32_bf16 v[62:65], v[170:173], v[186:189], v[62:65]
	v_mfma_f32_16x16x32_bf16 v[58:61], v[174:177], v[186:189], v[58:61]
	v_mfma_f32_16x16x32_bf16 v[54:57], v[178:181], v[186:189], v[54:57]
	v_mfma_f32_16x16x32_bf16 v[50:53], v[182:185], v[186:189], v[50:53]
	v_mfma_f32_16x16x32_bf16 v[46:49], v[170:173], v[190:193], v[46:49]
	v_mfma_f32_16x16x32_bf16 v[42:45], v[174:177], v[190:193], v[42:45]
	v_mfma_f32_16x16x32_bf16 v[38:41], v[178:181], v[190:193], v[38:41]
	v_mfma_f32_16x16x32_bf16 v[34:37], v[182:185], v[190:193], v[34:37]
	s_waitcnt lgkmcnt(0)
	v_mfma_f32_16x16x32_bf16 v[30:33], v[170:173], v[194:197], v[30:33]
	v_mfma_f32_16x16x32_bf16 v[26:29], v[174:177], v[194:197], v[26:29]
	v_mfma_f32_16x16x32_bf16 v[22:25], v[178:181], v[194:197], v[22:25]
	v_mfma_f32_16x16x32_bf16 v[18:21], v[182:185], v[194:197], v[18:21]
	v_mfma_f32_16x16x32_bf16 v[14:17], v[170:173], v[210:213], v[14:17]
	v_mfma_f32_16x16x32_bf16 v[10:13], v[174:177], v[210:213], v[10:13]
	v_mfma_f32_16x16x32_bf16 v[6:9], v[178:181], v[210:213], v[6:9]
	v_mfma_f32_16x16x32_bf16 v[2:5], v[182:185], v[210:213], v[2:5]
	s_add_u32 s4, s4, 64
	s_addc_u32 s5, s5, 0
	s_add_i32 s11, s11, 1
	s_cmpk_eq_i32 s4, 0x780
	s_cbranch_scc0 .LBB0_135
	s_waitcnt vmcnt(6)
	s_waitcnt lgkmcnt(0)
	s_barrier
; #define MFMA(a, b, c) __builtin_amdgcn_mfma_f32_16x16x32_bf16((a), (b), (c), 0, 0, 0)
; template <int EPI, int MF>
; __device__ __forceinline__ void gemm_part(const u16* __restrict__ A, int lda, const u16* __restrict__ Bt, int K, int ntn, GemmEpi ep, char* smem,
;                                           int mbase, int mrows) {
;     ...
;     for (int kt = 0; kt < nk; ++kt) {
;       if (kt + 1 < nk) {
;         if (MF == 8) asm volatile("s_waitcnt vmcnt(6)" ::: "memory");
;         else asm volatile("s_waitcnt vmcnt(3)" ::: "memory");
;       } else asm volatile("s_waitcnt vmcnt(0)" ::: "memory");
;       asm volatile("s_waitcnt lgkmcnt(0)" ::: "memory");
;       __builtin_amdgcn_s_barrier();
;       const u16* a_ = sbase + (kt % 3) * STG;
;       const u16* b_ = a_ + BM * 32;
;       bf16x8 bfr[4], afc[2], afn[2];
;       const u16* ap_ = a_ + (wr * (16 * MF) + fr) * 32 + fq * 8;
; #pragma unroll
;       for (int n = 0; n < 4; ++n) bfr[n] = rd_std(b_ + (wc * 64 + n * 16 + fr) * 32 + fq * 8);
;       afc[0] = rd_std(ap_); afc[1] = rd_std(ap_ + 16 * 32);
;       __builtin_amdgcn_sched_barrier(0);
;       if (kt + 2 < nk) GEMM_ISSUE(kt + 2);
;       __builtin_amdgcn_sched_barrier(0);
; #pragma unroll
;       for (int mh = 0; mh < MF / 2; ++mh) {
;         if (mh + 1 < MF / 2) {
;           afn[0] = rd_std(ap_ + ((mh + 1) * 2) * 16 * 32);
;           afn[1] = rd_std(ap_ + ((mh + 1) * 2 + 1) * 16 * 32);
;         }
;         __builtin_amdgcn_sched_barrier(0);
; #pragma unroll
;         for (int m = 0; m < 2; ++m)
; #pragma unroll
;           for (int n = 0; n < 4; ++n) acc[mh * 2 + m][n] = MFMA(bfr[n], afc[m], acc[mh * 2 + m][n]);
;         __builtin_amdgcn_sched_barrier(0);
;         afc[0] = afn[0]; afc[1] = afn[1];
;       }
;     }
;     ...
;     __syncthreads();
; #pragma unroll
;     for (int m = 0; m < MF; ++m) {
;       if (EPI == EPI_SWIGLU || (m & 1) == 0) __builtin_amdgcn_sched_barrier(0);
;       const int row = row0 + wr * (16 * MF) + m * 16 + fr;
;       const int cb = col0 + wc * 64 + 4 * fq;
;       float rstd = 1.f;
;       if (EPI != EPI_RESID) { if (ep.rss_in) rstd = rsqrtf(ep.rss_in[row] * (1.f / DM) + 1e-6f); }
	ds_read_b128 v[146:149], v168 offset:16384
	ds_read_b128 v[170:173], v168 offset:17408
	ds_read_b128 v[174:177], v168 offset:18432
	ds_read_b128 v[178:181], v168 offset:19456
	ds_read_b128 v[182:185], v156
	ds_read_b128 v[186:189], v156 offset:1024
	ds_read_b128 v[190:193], v156 offset:2048
	ds_read_b128 v[194:197], v156 offset:3072
	s_waitcnt lgkmcnt(0)
	v_mfma_f32_16x16x32_bf16 v[126:129], v[146:149], v[182:185], v[126:129]
	v_mfma_f32_16x16x32_bf16 v[122:125], v[170:173], v[182:185], v[122:125]
	v_mfma_f32_16x16x32_bf16 v[114:117], v[178:181], v[182:185], v[114:117]
	v_mfma_f32_16x16x32_bf16 v[110:113], v[146:149], v[186:189], v[110:113]
	v_mfma_f32_16x16x32_bf16 v[106:109], v[170:173], v[186:189], v[106:109]
	v_mfma_f32_16x16x32_bf16 v[98:101], v[178:181], v[186:189], v[98:101]
	v_mfma_f32_16x16x32_bf16 v[210:213], v[174:177], v[182:185], v[118:121]
	v_mfma_f32_16x16x32_bf16 v[182:185], v[174:177], v[186:189], v[102:105]
	s_nop 2
	ds_read_b128 v[102:105], v156 offset:4096
	ds_read_b128 v[118:121], v156 offset:5120
	v_mfma_f32_16x16x32_bf16 v[94:97], v[146:149], v[190:193], v[94:97]
	v_mfma_f32_16x16x32_bf16 v[90:93], v[170:173], v[190:193], v[90:93]
	v_mfma_f32_16x16x32_bf16 v[82:85], v[178:181], v[190:193], v[82:85]
	v_mfma_f32_16x16x32_bf16 v[78:81], v[146:149], v[194:197], v[78:81]
	v_mfma_f32_16x16x32_bf16 v[74:77], v[170:173], v[194:197], v[74:77]
	v_mfma_f32_16x16x32_bf16 v[66:69], v[178:181], v[194:197], v[66:69]
	v_mfma_f32_16x16x32_bf16 v[186:189], v[174:177], v[190:193], v[86:89]
	v_mfma_f32_16x16x32_bf16 v[190:193], v[174:177], v[194:197], v[70:73]
	s_nop 2
	ds_read_b128 v[70:73], v156 offset:6144
	ds_read_b128 v[86:89], v156 offset:7168
	s_waitcnt lgkmcnt(0)
	v_mfma_f32_16x16x32_bf16 v[62:65], v[146:149], v[102:105], v[62:65]
	v_mfma_f32_16x16x32_bf16 v[58:61], v[170:173], v[102:105], v[58:61]
	v_mfma_f32_16x16x32_bf16 v[50:53], v[178:181], v[102:105], v[50:53]
	v_mfma_f32_16x16x32_bf16 v[46:49], v[146:149], v[118:121], v[46:49]
	v_mfma_f32_16x16x32_bf16 v[42:45], v[170:173], v[118:121], v[42:45]
	v_mfma_f32_16x16x32_bf16 v[34:37], v[178:181], v[118:121], v[34:37]
	v_mfma_f32_16x16x32_bf16 v[194:197], v[174:177], v[102:105], v[54:57]
	v_mfma_f32_16x16x32_bf16 v[214:217], v[174:177], v[118:121], v[38:41]
	v_mfma_f32_16x16x32_bf16 v[30:33], v[146:149], v[70:73], v[30:33]
	v_mfma_f32_16x16x32_bf16 v[26:29], v[170:173], v[70:73], v[26:29]
	v_mfma_f32_16x16x32_bf16 v[18:21], v[178:181], v[70:73], v[18:21]
	v_mfma_f32_16x16x32_bf16 v[14:17], v[146:149], v[86:89], v[14:17]
	v_mfma_f32_16x16x32_bf16 v[10:13], v[170:173], v[86:89], v[10:13]
	v_mfma_f32_16x16x32_bf16 v[146:149], v[174:177], v[86:89], v[6:9]
	v_mfma_f32_16x16x32_bf16 v[2:5], v[178:181], v[86:89], v[2:5]
	v_mfma_f32_16x16x32_bf16 v[218:221], v[174:177], v[70:73], v[22:25]
	s_waitcnt vmcnt(0)
	s_waitcnt lgkmcnt(0)
	s_barrier
	ds_read_b128 v[6:9], v168 offset:40960
	ds_read_b128 v[170:173], v168 offset:41984
	ds_read_b128 v[174:177], v168 offset:43008
	ds_read_b128 v[178:181], v168 offset:44032
	ds_read_b128 v[22:25], v156 offset:24576
	ds_read_b128 v[38:41], v156 offset:25600
	ds_read_b128 v[54:57], v156 offset:26624
	ds_read_b128 v[222:225], v156 offset:27648
	s_waitcnt lgkmcnt(0)
	v_mfma_f32_16x16x32_bf16 v[126:129], v[6:9], v[22:25], v[126:129]
	v_mfma_f32_16x16x32_bf16 v[118:121], v[170:173], v[22:25], v[122:125]
	v_mfma_f32_16x16x32_bf16 v[122:125], v[174:177], v[22:25], v[210:213]
	v_mfma_f32_16x16x32_bf16 v[114:117], v[178:181], v[22:25], v[114:117]
	v_mfma_f32_16x16x32_bf16 v[110:113], v[6:9], v[38:41], v[110:113]
	v_mfma_f32_16x16x32_bf16 v[102:105], v[170:173], v[38:41], v[106:109]
	v_mfma_f32_16x16x32_bf16 v[106:109], v[174:177], v[38:41], v[182:185]
	v_mfma_f32_16x16x32_bf16 v[98:101], v[178:181], v[38:41], v[98:101]
	ds_read_b128 v[22:25], v156 offset:28672
	s_nop 0
	ds_read_b128 v[182:185], v156 offset:29696
	v_mfma_f32_16x16x32_bf16 v[94:97], v[6:9], v[54:57], v[94:97]
	v_mfma_f32_16x16x32_bf16 v[86:89], v[170:173], v[54:57], v[90:93]
	v_mfma_f32_16x16x32_bf16 v[90:93], v[174:177], v[54:57], v[186:189]
	v_mfma_f32_16x16x32_bf16 v[82:85], v[178:181], v[54:57], v[82:85]
	v_mfma_f32_16x16x32_bf16 v[78:81], v[6:9], v[222:225], v[78:81]
	v_mfma_f32_16x16x32_bf16 v[70:73], v[170:173], v[222:225], v[74:77]
	v_mfma_f32_16x16x32_bf16 v[74:77], v[174:177], v[222:225], v[190:193]
	v_mfma_f32_16x16x32_bf16 v[66:69], v[178:181], v[222:225], v[66:69]
	ds_read_b128 v[186:189], v156 offset:30720
	s_nop 0
	ds_read_b128 v[190:193], v156 offset:31744
	s_waitcnt lgkmcnt(0)
	v_mfma_f32_16x16x32_bf16 v[62:65], v[6:9], v[22:25], v[62:65]
	v_mfma_f32_16x16x32_bf16 v[54:57], v[170:173], v[22:25], v[58:61]
	v_mfma_f32_16x16x32_bf16 v[58:61], v[174:177], v[22:25], v[194:197]
	v_mfma_f32_16x16x32_bf16 v[50:53], v[178:181], v[22:25], v[50:53]
	v_mfma_f32_16x16x32_bf16 v[46:49], v[6:9], v[182:185], v[46:49]
	v_mfma_f32_16x16x32_bf16 v[38:41], v[170:173], v[182:185], v[42:45]
	v_mfma_f32_16x16x32_bf16 v[42:45], v[174:177], v[182:185], v[214:217]
	v_mfma_f32_16x16x32_bf16 v[34:37], v[178:181], v[182:185], v[34:37]
	v_mfma_f32_16x16x32_bf16 v[30:33], v[6:9], v[186:189], v[30:33]
	v_mfma_f32_16x16x32_bf16 v[22:25], v[170:173], v[186:189], v[26:29]
	v_mfma_f32_16x16x32_bf16 v[26:29], v[174:177], v[186:189], v[218:221]
	v_mfma_f32_16x16x32_bf16 v[18:21], v[178:181], v[186:189], v[18:21]
	v_mfma_f32_16x16x32_bf16 v[14:17], v[6:9], v[190:193], v[14:17]
	v_mfma_f32_16x16x32_bf16 v[6:9], v[170:173], v[190:193], v[10:13]
	v_mfma_f32_16x16x32_bf16 v[10:13], v[174:177], v[190:193], v[146:149]
	v_mfma_f32_16x16x32_bf16 v[2:5], v[178:181], v[190:193], v[2:5]
	s_nop 1
	v_add_u32_e32 v146, s9, v154
	s_waitcnt vmcnt(0)
	s_barrier
	v_readlane_b32 s4, v252, 1
	v_readlane_b32 s5, v252, 2
	v_ashrrev_i32_e32 v147, 31, v146
	v_mov_b32_e32 v150, 1.0
	s_and_b64 vcc, exec, s[4:5]
	v_mov_b32_e32 v152, 1.0
	s_cbranch_vccz .LBB0_138
	v_lshl_add_u64 v[148:149], v[146:147], 2, s[14:15]
	global_load_dword v147, v[148:149], off
	s_waitcnt vmcnt(0)
	v_fmamk_f32 v147, v147, 0x3a800000, v142
	v_mul_f32_e32 v148, 0x4b800000, v147
	v_cmp_gt_f32_e32 vcc, s69, v147
	s_nop 1
	v_cndmask_b32_e32 v147, v147, v148, vcc
	v_rsq_f32_e32 v147, v147
	s_nop 0
	v_mul_f32_e32 v148, 0x45800000, v147
	v_cndmask_b32_e32 v152, v147, v148, vcc

; #define MFMA(a, b, c) __builtin_amdgcn_mfma_f32_16x16x32_bf16((a), (b), (c), 0, 0, 0)
; template <int EPI, int MF>
; __device__ __forceinline__ void gemm_part(const u16* __restrict__ A, int lda, const u16* __restrict__ Bt, int K, int ntn, GemmEpi ep, char* smem,
;                                           int mbase, int mrows) {
;     ...
;     GEMM_ISSUE(0);
;     GEMM_ISSUE(1);
;     for (int kt = 0; kt < nk; ++kt) {
;       if (kt + 1 < nk) {
;         if (MF == 8) asm volatile("s_waitcnt vmcnt(6)" ::: "memory");
;         else asm volatile("s_waitcnt vmcnt(3)" ::: "memory");
;       } else asm volatile("s_waitcnt vmcnt(0)" ::: "memory");
;       asm volatile("s_waitcnt lgkmcnt(0)" ::: "memory");
;       __builtin_amdgcn_s_barrier();
;       const u16* a_ = sbase + (kt % 3) * STG;
;       const u16* b_ = a_ + BM * 32;
;       bf16x8 bfr[4], afc[2], afn[2];
;       const u16* ap_ = a_ + (wr * (16 * MF) + fr) * 32 + fq * 8;
; #pragma unroll
;       for (int n = 0; n < 4; ++n) bfr[n] = rd_std(b_ + (wc * 64 + n * 16 + fr) * 32 + fq * 8);
;       afc[0] = rd_std(ap_); afc[1] = rd_std(ap_ + 16 * 32);
;       __builtin_amdgcn_sched_barrier(0);
;       if (kt + 2 < nk) GEMM_ISSUE(kt + 2);
;       __builtin_amdgcn_sched_barrier(0);
; #pragma unroll
;       for (int mh = 0; mh < MF / 2; ++mh) {
;         if (mh + 1 < MF / 2) {
;           afn[0] = rd_std(ap_ + ((mh + 1) * 2) * 16 * 32);
;           afn[1] = rd_std(ap_ + ((mh + 1) * 2 + 1) * 16 * 32);
;         }
;         __builtin_amdgcn_sched_barrier(0);
; #pragma unroll
;         for (int m = 0; m < 2; ++m)
; #pragma unroll
;           for (int n = 0; n < 4; ++n) acc[mh * 2 + m][n] = MFMA(bfr[n], afc[m], acc[mh * 2 + m][n]);
;         __builtin_amdgcn_sched_barrier(0);
;         afc[0] = afn[0]; afc[1] = afn[1];
;       }
.LBB0_205:
	s_mul_hi_u32 s17, s16, 0xaaaaaaab
	s_lshr_b32 s17, s17, 1
	s_mul_i32 s17, s17, 0x12000
	v_add_u32_e32 v146, s3, v161
	v_subrev_u32_e32 v147, s17, v164
	v_subrev_u32_e32 v148, s17, v160
	v_add_u32_e32 v170, v146, v147
	v_add_u32_e32 v190, v146, v148
	s_mul_hi_u32 s17, s15, 0xaaaaaaab
	s_add_i32 s16, s16, 1
	s_lshr_b32 s17, s17, 1
	s_mul_i32 s17, s17, 0x12000
	s_sub_i32 s17, s3, s17
	s_add_i32 s22, s17, 0xc000
	v_add_u32_e32 v178, s22, v154
	v_lshl_add_u64 v[150:151], v[136:137], 0, v[134:135]
	v_readfirstlane_b32 s101, v178
	v_lshl_add_u64 v[152:153], v[150:151], 0, s[74:75]
	v_lshl_add_u64 v[166:167], v[150:151], 0, s[56:57]
	v_lshl_add_u64 v[168:169], v[150:151], 0, s[58:59]
	v_lshl_add_u64 v[150:151], v[150:151], 0, s[86:87]
	v_lshl_add_u64 v[174:175], v[138:139], 0, v[134:135]
	v_lshl_add_u64 v[176:177], v[174:175], 0, s[74:75]
	v_lshl_add_u64 v[174:175], v[174:175], 0, s[56:57]
	s_waitcnt vmcnt(6)
	s_waitcnt lgkmcnt(0)
	s_barrier
	s_setprio 2
	s_mov_b32 m0, s101
	s_nop 0
	global_load_lds_dwordx4 v[152:153], off
	s_add_u32 m0, m0, 0x1000
	s_nop 0
	global_load_lds_dwordx4 v[166:167], off
	s_add_u32 m0, m0, 0x1000
	s_nop 0
	global_load_lds_dwordx4 v[168:169], off
	s_add_u32 m0, m0, 0x1000
	s_nop 0
	global_load_lds_dwordx4 v[150:151], off
	s_add_u32 m0, m0, 0x1000
	s_nop 0
	global_load_lds_dwordx4 v[176:177], off
	s_add_u32 m0, m0, 0x1000
	s_nop 0
	global_load_lds_dwordx4 v[174:175], off
	s_setprio 0
	ds_read_b128 v[146:149], v170 offset:16384
	ds_read_b128 v[150:153], v170 offset:17408
	ds_read_b128 v[166:169], v170 offset:18432
	ds_read_b128 v[170:173], v170 offset:19456
	ds_read_b128 v[174:177], v190
	ds_read_b128 v[178:181], v190 offset:1024
	ds_read_b128 v[182:185], v190 offset:3072
	ds_read_b128 v[186:189], v190 offset:2048
	s_waitcnt lgkmcnt(2)
	v_mfma_f32_16x16x32_bf16 v[126:129], v[146:149], v[174:177], v[126:129]
	v_mfma_f32_16x16x32_bf16 v[122:125], v[150:153], v[174:177], v[122:125]
	v_mfma_f32_16x16x32_bf16 v[118:121], v[166:169], v[174:177], v[118:121]
	v_mfma_f32_16x16x32_bf16 v[114:117], v[170:173], v[174:177], v[114:117]
	v_mfma_f32_16x16x32_bf16 v[110:113], v[146:149], v[178:181], v[110:113]
	v_mfma_f32_16x16x32_bf16 v[106:109], v[150:153], v[178:181], v[106:109]
	v_mfma_f32_16x16x32_bf16 v[102:105], v[166:169], v[178:181], v[102:105]
	v_mfma_f32_16x16x32_bf16 v[98:101], v[170:173], v[178:181], v[98:101]
	ds_read_b128 v[174:177], v190 offset:5120
	ds_read_b128 v[178:181], v190 offset:4096
	s_waitcnt lgkmcnt(2)
	v_mfma_f32_16x16x32_bf16 v[94:97], v[146:149], v[186:189], v[94:97]
	v_mfma_f32_16x16x32_bf16 v[90:93], v[150:153], v[186:189], v[90:93]
	v_mfma_f32_16x16x32_bf16 v[86:89], v[166:169], v[186:189], v[86:89]
	v_mfma_f32_16x16x32_bf16 v[82:85], v[170:173], v[186:189], v[82:85]
	v_mfma_f32_16x16x32_bf16 v[78:81], v[146:149], v[182:185], v[78:81]
	v_mfma_f32_16x16x32_bf16 v[74:77], v[150:153], v[182:185], v[74:77]
	v_mfma_f32_16x16x32_bf16 v[70:73], v[166:169], v[182:185], v[70:73]
	v_mfma_f32_16x16x32_bf16 v[66:69], v[170:173], v[182:185], v[66:69]
	ds_read_b128 v[182:185], v190 offset:7168
	ds_read_b128 v[186:189], v190 offset:6144
	s_waitcnt lgkmcnt(2)
	v_mfma_f32_16x16x32_bf16 v[62:65], v[146:149], v[178:181], v[62:65]
	v_mfma_f32_16x16x32_bf16 v[58:61], v[150:153], v[178:181], v[58:61]
	v_mfma_f32_16x16x32_bf16 v[54:57], v[166:169], v[178:181], v[54:57]
	v_mfma_f32_16x16x32_bf16 v[50:53], v[170:173], v[178:181], v[50:53]
	v_mfma_f32_16x16x32_bf16 v[46:49], v[146:149], v[174:177], v[46:49]
	v_mfma_f32_16x16x32_bf16 v[42:45], v[150:153], v[174:177], v[42:45]
	v_mfma_f32_16x16x32_bf16 v[38:41], v[166:169], v[174:177], v[38:41]
	v_mfma_f32_16x16x32_bf16 v[34:37], v[170:173], v[174:177], v[34:37]
	s_waitcnt lgkmcnt(0)
	v_mfma_f32_16x16x32_bf16 v[30:33], v[146:149], v[186:189], v[30:33]
	v_mfma_f32_16x16x32_bf16 v[26:29], v[150:153], v[186:189], v[26:29]
	v_mfma_f32_16x16x32_bf16 v[22:25], v[166:169], v[186:189], v[22:25]
	v_mfma_f32_16x16x32_bf16 v[18:21], v[170:173], v[186:189], v[18:21]
	v_mfma_f32_16x16x32_bf16 v[14:17], v[146:149], v[182:185], v[14:17]
	v_mfma_f32_16x16x32_bf16 v[10:13], v[150:153], v[182:185], v[10:13]
	v_mfma_f32_16x16x32_bf16 v[6:9], v[166:169], v[182:185], v[6:9]
	v_mfma_f32_16x16x32_bf16 v[2:5], v[170:173], v[182:185], v[2:5]
	s_addk_i32 s3, 0x6000
	s_add_i32 s14, s14, 1
	s_add_i32 s15, s15, 1
	v_lshl_add_u64 v[136:137], v[136:137], 0, 64
	v_lshl_add_u64 v[136:137], v[136:137], 0, 64
	s_cmp_eq_u32 s3, 0x204000
	v_lshl_add_u64 v[138:139], v[138:139], 0, 64
	v_lshl_add_u64 v[138:139], v[138:139], 0, 64
	s_cbranch_scc0 .LBB0_205
	s_waitcnt vmcnt(6)
	s_waitcnt lgkmcnt(0)
	s_barrier
; #define MFMA(a, b, c) __builtin_amdgcn_mfma_f32_16x16x32_bf16((a), (b), (c), 0, 0, 0)
; template <int EPI, int MF>
; __device__ __forceinline__ void gemm_part(const u16* __restrict__ A, int lda, const u16* __restrict__ Bt, int K, int ntn, GemmEpi ep, char* smem,
;                                           int mbase, int mrows) {
;     ...
;     for (int kt = 0; kt < nk; ++kt) {
;       if (kt + 1 < nk) {
;         if (MF == 8) asm volatile("s_waitcnt vmcnt(6)" ::: "memory");
;         else asm volatile("s_waitcnt vmcnt(3)" ::: "memory");
;       } else asm volatile("s_waitcnt vmcnt(0)" ::: "memory");
;       asm volatile("s_waitcnt lgkmcnt(0)" ::: "memory");
;       __builtin_amdgcn_s_barrier();
;       const u16* a_ = sbase + (kt % 3) * STG;
;       const u16* b_ = a_ + BM * 32;
;       bf16x8 bfr[4], afc[2], afn[2];
;       const u16* ap_ = a_ + (wr * (16 * MF) + fr) * 32 + fq * 8;
; #pragma unroll
;       for (int n = 0; n < 4; ++n) bfr[n] = rd_std(b_ + (wc * 64 + n * 16 + fr) * 32 + fq * 8);
;       afc[0] = rd_std(ap_); afc[1] = rd_std(ap_ + 16 * 32);
;       __builtin_amdgcn_sched_barrier(0);
;       if (kt + 2 < nk) GEMM_ISSUE(kt + 2);
;       __builtin_amdgcn_sched_barrier(0);
; #pragma unroll
;       for (int mh = 0; mh < MF / 2; ++mh) {
;         if (mh + 1 < MF / 2) {
;           afn[0] = rd_std(ap_ + ((mh + 1) * 2) * 16 * 32);
;           afn[1] = rd_std(ap_ + ((mh + 1) * 2 + 1) * 16 * 32);
;         }
;         __builtin_amdgcn_sched_barrier(0);
; #pragma unroll
;         for (int m = 0; m < 2; ++m)
; #pragma unroll
;           for (int n = 0; n < 4; ++n) acc[mh * 2 + m][n] = MFMA(bfr[n], afc[m], acc[mh * 2 + m][n]);
;         __builtin_amdgcn_sched_barrier(0);
;         afc[0] = afn[0]; afc[1] = afn[1];
;       }
	ds_read_b128 v[136:139], v165
	ds_read_b128 v[146:149], v165 offset:1024
	ds_read_b128 v[150:153], v165 offset:2048
	ds_read_b128 v[166:169], v165 offset:3072
	ds_read_b128 v[170:173], v162 offset:49152
	ds_read_b128 v[174:177], v162 offset:50176
	s_mul_hi_u32 s14, s14, 0xaaaaaaab
	s_lshr_b32 s14, s14, 1
	s_mul_i32 s14, s14, 0x12000
	s_sub_i32 s3, s3, s14
	s_add_i32 s3, s3, 0
	s_addk_i32 s3, 0x6000
	ds_read_b128 v[178:181], v162 offset:52224
	ds_read_b128 v[182:185], v162 offset:51200
	s_waitcnt lgkmcnt(0)
	v_mfma_f32_16x16x32_bf16 v[126:129], v[136:139], v[170:173], v[126:129]
	v_mfma_f32_16x16x32_bf16 v[122:125], v[146:149], v[170:173], v[122:125]
	v_mfma_f32_16x16x32_bf16 v[118:121], v[150:153], v[170:173], v[118:121]
	v_mfma_f32_16x16x32_bf16 v[114:117], v[166:169], v[170:173], v[114:117]
	v_mfma_f32_16x16x32_bf16 v[110:113], v[136:139], v[174:177], v[110:113]
	v_mfma_f32_16x16x32_bf16 v[106:109], v[146:149], v[174:177], v[106:109]
	v_mfma_f32_16x16x32_bf16 v[102:105], v[150:153], v[174:177], v[102:105]
	v_mfma_f32_16x16x32_bf16 v[98:101], v[166:169], v[174:177], v[98:101]
	ds_read_b128 v[170:173], v162 offset:54272
	ds_read_b128 v[174:177], v162 offset:53248
	v_mfma_f32_16x16x32_bf16 v[94:97], v[136:139], v[182:185], v[94:97]
	v_mfma_f32_16x16x32_bf16 v[90:93], v[146:149], v[182:185], v[90:93]
	v_mfma_f32_16x16x32_bf16 v[86:89], v[150:153], v[182:185], v[86:89]
	v_mfma_f32_16x16x32_bf16 v[82:85], v[166:169], v[182:185], v[82:85]
	v_mfma_f32_16x16x32_bf16 v[78:81], v[136:139], v[178:181], v[78:81]
	v_mfma_f32_16x16x32_bf16 v[74:77], v[146:149], v[178:181], v[74:77]
	v_mfma_f32_16x16x32_bf16 v[70:73], v[150:153], v[178:181], v[70:73]
	v_mfma_f32_16x16x32_bf16 v[66:69], v[166:169], v[178:181], v[66:69]
	ds_read_b128 v[178:181], v162 offset:56320
	ds_read_b128 v[182:185], v162 offset:55296
	s_waitcnt lgkmcnt(0)
	v_mfma_f32_16x16x32_bf16 v[62:65], v[136:139], v[174:177], v[62:65]
	v_mfma_f32_16x16x32_bf16 v[58:61], v[146:149], v[174:177], v[58:61]
	v_mfma_f32_16x16x32_bf16 v[54:57], v[150:153], v[174:177], v[54:57]
	v_mfma_f32_16x16x32_bf16 v[50:53], v[166:169], v[174:177], v[50:53]
	v_mfma_f32_16x16x32_bf16 v[46:49], v[136:139], v[170:173], v[46:49]
	v_mfma_f32_16x16x32_bf16 v[42:45], v[146:149], v[170:173], v[42:45]
	v_mfma_f32_16x16x32_bf16 v[38:41], v[150:153], v[170:173], v[38:41]
	v_mfma_f32_16x16x32_bf16 v[34:37], v[166:169], v[170:173], v[34:37]
	v_mfma_f32_16x16x32_bf16 v[30:33], v[136:139], v[182:185], v[30:33]
	v_mfma_f32_16x16x32_bf16 v[26:29], v[146:149], v[182:185], v[26:29]
	v_mfma_f32_16x16x32_bf16 v[22:25], v[150:153], v[182:185], v[22:25]
	v_mfma_f32_16x16x32_bf16 v[18:21], v[166:169], v[182:185], v[18:21]
	v_mfma_f32_16x16x32_bf16 v[14:17], v[136:139], v[178:181], v[14:17]
	v_mfma_f32_16x16x32_bf16 v[10:13], v[146:149], v[178:181], v[10:13]
	v_mfma_f32_16x16x32_bf16 v[6:9], v[150:153], v[178:181], v[6:9]
	v_mfma_f32_16x16x32_bf16 v[2:5], v[166:169], v[178:181], v[2:5]
	v_add_u32_e32 v136, s3, v161
	s_waitcnt vmcnt(0)
	v_add3_u32 v166, v136, v158, v159
	s_waitcnt lgkmcnt(0)
	s_barrier
; #define MFMA(a, b, c) __builtin_amdgcn_mfma_f32_16x16x32_bf16((a), (b), (c), 0, 0, 0)
; template <int EPI, int MF>
; __device__ __forceinline__ void gemm_part(const u16* __restrict__ A, int lda, const u16* __restrict__ Bt, int K, int ntn, GemmEpi ep, char* smem,
;                                           int mbase, int mrows) {
;     ...
;     for (int kt = 0; kt < nk; ++kt) {
;       if (kt + 1 < nk) {
;         if (MF == 8) asm volatile("s_waitcnt vmcnt(6)" ::: "memory");
;         else asm volatile("s_waitcnt vmcnt(3)" ::: "memory");
;       } else asm volatile("s_waitcnt vmcnt(0)" ::: "memory");
;       asm volatile("s_waitcnt lgkmcnt(0)" ::: "memory");
;       __builtin_amdgcn_s_barrier();
;       const u16* a_ = sbase + (kt % 3) * STG;
;       const u16* b_ = a_ + BM * 32;
;       bf16x8 bfr[4], afc[2], afn[2];
;       const u16* ap_ = a_ + (wr * (16 * MF) + fr) * 32 + fq * 8;
; #pragma unroll
;       for (int n = 0; n < 4; ++n) bfr[n] = rd_std(b_ + (wc * 64 + n * 16 + fr) * 32 + fq * 8);
;       afc[0] = rd_std(ap_); afc[1] = rd_std(ap_ + 16 * 32);
;       __builtin_amdgcn_sched_barrier(0);
;       if (kt + 2 < nk) GEMM_ISSUE(kt + 2);
;       __builtin_amdgcn_sched_barrier(0);
; #pragma unroll
;       for (int mh = 0; mh < MF / 2; ++mh) {
;         if (mh + 1 < MF / 2) {
;           afn[0] = rd_std(ap_ + ((mh + 1) * 2) * 16 * 32);
;           afn[1] = rd_std(ap_ + ((mh + 1) * 2 + 1) * 16 * 32);
;         }
;         __builtin_amdgcn_sched_barrier(0);
; #pragma unroll
;         for (int m = 0; m < 2; ++m)
; #pragma unroll
;           for (int n = 0; n < 4; ++n) acc[mh * 2 + m][n] = MFMA(bfr[n], afc[m], acc[mh * 2 + m][n]);
;         __builtin_amdgcn_sched_barrier(0);
;         afc[0] = afn[0]; afc[1] = afn[1];
;       }
;     ...
;       } else if (EPI == EPI_RESID) {
;         const float* rp = (row < MP) ? ep.res0 + (size_t)row * DM : ep.res1 + (size_t)(row - MP) * DM;
;         float ssq = 0.f;
; #pragma unroll
;         for (int n = 0; n < 4; ++n) {
;           const int col = cb + n * 16;
;           const float4 r = *(const float4*)(rp + col);
;           float4 v;
;           v.x = r.x + ep.scale * acc[m][n][0]; v.y = r.y + ep.scale * acc[m][n][1];
;           v.z = r.z + ep.scale * acc[m][n][2]; v.w = r.w + ep.scale * acc[m][n][3];
;           *(float4*)(ep.outf + (size_t)row * DM + col) = v;
;           if (ep.xcopy) {
;             bf16x4 o;
	ds_read_b128 v[136:139], v166 offset:16384
	ds_read_b128 v[146:149], v166 offset:17408
	ds_read_b128 v[150:153], v166 offset:18432
	ds_read_b128 v[166:169], v166 offset:19456
	ds_read_b128 v[170:173], v162
	ds_read_b128 v[174:177], v162 offset:1024
	ds_read_b128 v[178:181], v162 offset:3072
	ds_read_b128 v[182:185], v162 offset:2048
	s_waitcnt lgkmcnt(0)
	v_mfma_f32_16x16x32_bf16 v[126:129], v[136:139], v[170:173], v[126:129]
	v_mfma_f32_16x16x32_bf16 v[122:125], v[146:149], v[170:173], v[122:125]
	v_mfma_f32_16x16x32_bf16 v[118:121], v[150:153], v[170:173], v[118:121]
	v_mfma_f32_16x16x32_bf16 v[114:117], v[166:169], v[170:173], v[114:117]
	v_mfma_f32_16x16x32_bf16 v[110:113], v[136:139], v[174:177], v[110:113]
	v_mfma_f32_16x16x32_bf16 v[106:109], v[146:149], v[174:177], v[106:109]
	v_mfma_f32_16x16x32_bf16 v[102:105], v[150:153], v[174:177], v[102:105]
	v_mfma_f32_16x16x32_bf16 v[98:101], v[166:169], v[174:177], v[98:101]
	ds_read_b128 v[170:173], v162 offset:5120
	ds_read_b128 v[174:177], v162 offset:4096
	v_mfma_f32_16x16x32_bf16 v[94:97], v[136:139], v[182:185], v[94:97]
	v_mfma_f32_16x16x32_bf16 v[90:93], v[146:149], v[182:185], v[90:93]
	v_mfma_f32_16x16x32_bf16 v[86:89], v[150:153], v[182:185], v[86:89]
	v_mfma_f32_16x16x32_bf16 v[82:85], v[166:169], v[182:185], v[82:85]
	v_mfma_f32_16x16x32_bf16 v[78:81], v[136:139], v[178:181], v[78:81]
	v_mfma_f32_16x16x32_bf16 v[74:77], v[146:149], v[178:181], v[74:77]
	v_mfma_f32_16x16x32_bf16 v[70:73], v[150:153], v[178:181], v[70:73]
	v_mfma_f32_16x16x32_bf16 v[66:69], v[166:169], v[178:181], v[66:69]
	ds_read_b128 v[178:181], v162 offset:7168
	ds_read_b128 v[182:185], v162 offset:6144
	s_waitcnt lgkmcnt(0)
	v_mfma_f32_16x16x32_bf16 v[62:65], v[136:139], v[174:177], v[62:65]
	v_mfma_f32_16x16x32_bf16 v[58:61], v[146:149], v[174:177], v[58:61]
	v_mfma_f32_16x16x32_bf16 v[54:57], v[150:153], v[174:177], v[54:57]
	v_mfma_f32_16x16x32_bf16 v[50:53], v[166:169], v[174:177], v[50:53]
	v_mfma_f32_16x16x32_bf16 v[46:49], v[136:139], v[170:173], v[46:49]
	v_mfma_f32_16x16x32_bf16 v[42:45], v[146:149], v[170:173], v[42:45]
	v_mfma_f32_16x16x32_bf16 v[38:41], v[150:153], v[170:173], v[38:41]
	v_mfma_f32_16x16x32_bf16 v[34:37], v[166:169], v[170:173], v[34:37]
	v_mfma_f32_16x16x32_bf16 v[30:33], v[136:139], v[182:185], v[30:33]
	v_mfma_f32_16x16x32_bf16 v[26:29], v[146:149], v[182:185], v[26:29]
	v_mfma_f32_16x16x32_bf16 v[22:25], v[150:153], v[182:185], v[22:25]
	v_mfma_f32_16x16x32_bf16 v[18:21], v[166:169], v[182:185], v[18:21]
	v_mfma_f32_16x16x32_bf16 v[14:17], v[136:139], v[178:181], v[14:17]
	v_mfma_f32_16x16x32_bf16 v[10:13], v[146:149], v[178:181], v[10:13]
	v_mfma_f32_16x16x32_bf16 v[6:9], v[150:153], v[178:181], v[6:9]
	v_mfma_f32_16x16x32_bf16 v[2:5], v[166:169], v[178:181], v[2:5]
	v_add_u32_e32 v138, s2, v156
	s_waitcnt vmcnt(0)
	s_barrier
	s_mov_b32 s2, 0xffff
	v_cmp_lt_i32_e32 vcc, s2, v138
	s_and_saveexec_b64 s[2:3], vcc
	s_xor_b64 s[2:3], exec, s[2:3]
	v_add_u32_e32 v136, 0xffff0000, v138
	v_mov_b32_e32 v137, v0
	v_lshlrev_b64 v[136:137], 12, v[136:137]
	v_lshl_add_u64 v[136:137], s[18:19], 0, v[136:137]
	v_mov_b32_e32 v139, v0
	s_andn2_saveexec_b64 s[2:3], s[2:3]
	v_ashrrev_i32_e32 v139, 31, v138
	v_lshlrev_b64 v[136:137], 12, v[138:139]
	v_lshl_add_u64 v[136:137], s[8:9], 0, v[136:137]
	s_or_b64 exec, exec, s[2:3]
	v_lshlrev_b64 v[146:147], 12, v[138:139]
	v_or_b32_e32 v170, s11, v157
	v_lshl_add_u64 v[150:151], s[26:27], 0, v[146:147]
	v_lshlrev_b64 v[146:147], 11, v[138:139]
	v_lshl_add_u64 v[148:149], s[44:45], 0, v[146:147]
	v_lshlrev_b32_e32 v146, 2, v170
	v_mov_b32_e32 v147, v0
	v_lshl_add_u64 v[152:153], v[136:137], 0, v[146:147]
	global_load_dwordx4 v[166:169], v[152:153], off
	global_load_dwordx4 v[172:175], v[152:153], off offset:64
	global_load_dwordx4 v[176:179], v[152:153], off offset:128
	global_load_dwordx4 v[180:183], v[152:153], off offset:192
	v_readlane_b32 s2, v253, 24
	v_readlane_b32 s3, v253, 25
	v_lshl_add_u64 v[150:151], v[150:151], 0, v[146:147]
	s_andn2_b64 vcc, exec, s[2:3]
	v_cndmask_b32_e64 v136, 0, 1, s[2:3]
	v_cmp_ne_u32_e64 s[14:15], 1, v136
	v_lshlrev_b32_e32 v136, 1, v170
	s_waitcnt vmcnt(0)
	v_pk_fma_f32 v[126:127], v[126:127], 0.5, v[166:167] op_sel_hi:[1,0,1]
	v_pk_fma_f32 v[128:129], v[128:129], 0.5, v[168:169] op_sel_hi:[1,0,1]
	global_store_dwordx4 v[150:151], v[126:129], off
	s_cbranch_vccnz .LBB0_212
	v_mov_b32_e32 v137, v0
	v_cvt_pk_bf16_f32 v166, v126, v127
	v_cvt_pk_bf16_f32 v167, v128, v129
	v_lshl_add_u64 v[168:169], v[148:149], 0, v[136:137]
	v_lshlrev_b32_e32 v184, 1, v168
	v_bfi_b32 v184, s100, v184, v168
	v_lshrrev_b32_e32 v185, 5, v168
	v_bfi_b32 v184, 64, v185, v184
	v_mov_b32_e32 v185, v169
	global_store_dwordx2 v[184:185], v[166:167], off

; #define MFMA(a, b, c) __builtin_amdgcn_mfma_f32_16x16x32_bf16((a), (b), (c), 0, 0, 0)
; template <int EPI, int MF>
; __device__ __forceinline__ void gemm_part(const u16* __restrict__ A, int lda, const u16* __restrict__ Bt, int K, int ntn, GemmEpi ep, char* smem,
;                                           int mbase, int mrows) {
;     ...
;     GEMM_ISSUE(0);
;     GEMM_ISSUE(1);
;     for (int kt = 0; kt < nk; ++kt) {
;       if (kt + 1 < nk) {
;         if (MF == 8) asm volatile("s_waitcnt vmcnt(6)" ::: "memory");
;         else asm volatile("s_waitcnt vmcnt(3)" ::: "memory");
;       } else asm volatile("s_waitcnt vmcnt(0)" ::: "memory");
;       asm volatile("s_waitcnt lgkmcnt(0)" ::: "memory");
;       __builtin_amdgcn_s_barrier();
;       const u16* a_ = sbase + (kt % 3) * STG;
;       const u16* b_ = a_ + BM * 32;
;       bf16x8 bfr[4], afc[2], afn[2];
;       const u16* ap_ = a_ + (wr * (16 * MF) + fr) * 32 + fq * 8;
; #pragma unroll
;       for (int n = 0; n < 4; ++n) bfr[n] = rd_std(b_ + (wc * 64 + n * 16 + fr) * 32 + fq * 8);
;       afc[0] = rd_std(ap_); afc[1] = rd_std(ap_ + 16 * 32);
;       __builtin_amdgcn_sched_barrier(0);
;       if (kt + 2 < nk) GEMM_ISSUE(kt + 2);
;       __builtin_amdgcn_sched_barrier(0);
; #pragma unroll
;       for (int mh = 0; mh < MF / 2; ++mh) {
;         if (mh + 1 < MF / 2) {
;           afn[0] = rd_std(ap_ + ((mh + 1) * 2) * 16 * 32);
;           afn[1] = rd_std(ap_ + ((mh + 1) * 2 + 1) * 16 * 32);
;         }
;         __builtin_amdgcn_sched_barrier(0);
; #pragma unroll
;         for (int m = 0; m < 2; ++m)
; #pragma unroll
;           for (int n = 0; n < 4; ++n) acc[mh * 2 + m][n] = MFMA(bfr[n], afc[m], acc[mh * 2 + m][n]);
;         __builtin_amdgcn_sched_barrier(0);
;         afc[0] = afn[0]; afc[1] = afn[1];
;       }
.LBB0_414:
	s_mul_i32 s10, s9, 0xab
	s_add_i32 s11, s10, 0xfeaa
	s_bfe_u32 s11, s11, 0x70009
	s_mul_i32 s11, s11, 3
	s_sub_i32 s11, s9, s11
	s_add_i32 s11, s11, 0xfffe
	s_and_b32 s11, s11, 0xff
	s_mulk_i32 s11, 0x6000
	v_add_u32_e32 v147, s11, v159
	v_add_u32_e32 v148, s11, v158
	s_bfe_u32 s10, s10, 0x70009
	s_mul_i32 s10, s10, 3
	s_sub_i32 s10, s9, s10
	s_and_b32 s10, s10, 0xff
	s_mulk_i32 s10, 0x6000
	v_add_u32_e32 v176, s10, v149
	v_lshl_add_u64 v[160:161], s[2:3], 1, v[138:139]
	v_readfirstlane_b32 s101, v176
	v_lshl_add_u64 v[162:163], v[160:161], 0, s[74:75]
	v_lshl_add_u64 v[164:165], v[160:161], 0, s[92:93]
	v_lshl_add_u64 v[166:167], v[160:161], 0, s[88:89]
	v_lshl_add_u64 v[160:161], v[160:161], 0, s[6:7]
	v_lshl_add_u64 v[168:169], s[2:3], 1, v[136:137]
	v_lshl_add_u64 v[170:171], v[168:169], 0, s[74:75]
	v_lshl_add_u64 v[168:169], v[168:169], 0, s[92:93]
	s_waitcnt vmcnt(6)
	s_waitcnt lgkmcnt(0)
	s_barrier
	s_setprio 2
	s_mov_b32 m0, s101
	s_nop 0
	global_load_lds_dwordx4 v[162:163], off
	s_add_u32 m0, m0, 0x1000
	s_nop 0
	global_load_lds_dwordx4 v[164:165], off
	s_add_u32 m0, m0, 0x1000
	s_nop 0
	global_load_lds_dwordx4 v[166:167], off
	s_add_u32 m0, m0, 0x1000
	s_nop 0
	global_load_lds_dwordx4 v[160:161], off
	s_add_u32 m0, m0, 0x1000
	s_nop 0
	global_load_lds_dwordx4 v[170:171], off
	s_add_u32 m0, m0, 0x1000
	s_nop 0
	global_load_lds_dwordx4 v[168:169], off
	s_setprio 0
	ds_read_b128 v[160:163], v147 offset:16384
	ds_read_b128 v[164:167], v147 offset:17408
	ds_read_b128 v[168:171], v147 offset:18432
	ds_read_b128 v[172:175], v147 offset:19456
	ds_read_b128 v[176:179], v148
	ds_read_b128 v[180:183], v148 offset:1024
	ds_read_b128 v[184:187], v148 offset:3072
	ds_read_b128 v[188:191], v148 offset:2048
	s_waitcnt lgkmcnt(2)
	v_mfma_f32_16x16x32_bf16 v[126:129], v[160:163], v[176:179], v[126:129]
	v_mfma_f32_16x16x32_bf16 v[122:125], v[164:167], v[176:179], v[122:125]
	v_mfma_f32_16x16x32_bf16 v[118:121], v[168:171], v[176:179], v[118:121]
	v_mfma_f32_16x16x32_bf16 v[114:117], v[172:175], v[176:179], v[114:117]
	v_mfma_f32_16x16x32_bf16 v[110:113], v[160:163], v[180:183], v[110:113]
	v_mfma_f32_16x16x32_bf16 v[106:109], v[164:167], v[180:183], v[106:109]
	v_mfma_f32_16x16x32_bf16 v[102:105], v[168:171], v[180:183], v[102:105]
	v_mfma_f32_16x16x32_bf16 v[98:101], v[172:175], v[180:183], v[98:101]
	ds_read_b128 v[176:179], v148 offset:5120
	ds_read_b128 v[180:183], v148 offset:4096
	s_waitcnt lgkmcnt(2)
	v_mfma_f32_16x16x32_bf16 v[94:97], v[160:163], v[188:191], v[94:97]
	v_mfma_f32_16x16x32_bf16 v[90:93], v[164:167], v[188:191], v[90:93]
	v_mfma_f32_16x16x32_bf16 v[86:89], v[168:171], v[188:191], v[86:89]
	v_mfma_f32_16x16x32_bf16 v[82:85], v[172:175], v[188:191], v[82:85]
	v_mfma_f32_16x16x32_bf16 v[78:81], v[160:163], v[184:187], v[78:81]
	v_mfma_f32_16x16x32_bf16 v[74:77], v[164:167], v[184:187], v[74:77]
	v_mfma_f32_16x16x32_bf16 v[70:73], v[168:171], v[184:187], v[70:73]
	v_mfma_f32_16x16x32_bf16 v[66:69], v[172:175], v[184:187], v[66:69]
	ds_read_b128 v[184:187], v148 offset:7168
	ds_read_b128 v[188:191], v148 offset:6144
	s_waitcnt lgkmcnt(2)
	v_mfma_f32_16x16x32_bf16 v[62:65], v[160:163], v[180:183], v[62:65]
	v_mfma_f32_16x16x32_bf16 v[58:61], v[164:167], v[180:183], v[58:61]
	v_mfma_f32_16x16x32_bf16 v[54:57], v[168:171], v[180:183], v[54:57]
	v_mfma_f32_16x16x32_bf16 v[50:53], v[172:175], v[180:183], v[50:53]
	v_mfma_f32_16x16x32_bf16 v[46:49], v[160:163], v[176:179], v[46:49]
	v_mfma_f32_16x16x32_bf16 v[42:45], v[164:167], v[176:179], v[42:45]
	v_mfma_f32_16x16x32_bf16 v[38:41], v[168:171], v[176:179], v[38:41]
	v_mfma_f32_16x16x32_bf16 v[34:37], v[172:175], v[176:179], v[34:37]
	s_waitcnt lgkmcnt(0)
	v_mfma_f32_16x16x32_bf16 v[30:33], v[160:163], v[188:191], v[30:33]
	v_mfma_f32_16x16x32_bf16 v[26:29], v[164:167], v[188:191], v[26:29]
	v_mfma_f32_16x16x32_bf16 v[22:25], v[168:171], v[188:191], v[22:25]
	v_mfma_f32_16x16x32_bf16 v[18:21], v[172:175], v[188:191], v[18:21]
	v_mfma_f32_16x16x32_bf16 v[14:17], v[160:163], v[184:187], v[14:17]
	v_mfma_f32_16x16x32_bf16 v[10:13], v[164:167], v[184:187], v[10:13]
	v_mfma_f32_16x16x32_bf16 v[6:9], v[168:171], v[184:187], v[6:9]
	v_mfma_f32_16x16x32_bf16 v[2:5], v[172:175], v[184:187], v[2:5]
	s_add_u32 s2, s2, 64
	s_addc_u32 s3, s3, 0
	s_add_i32 s9, s9, 1
	s_cmpk_eq_i32 s2, 0x780
	s_cbranch_scc0 .LBB0_414
	s_waitcnt vmcnt(6)
	s_waitcnt lgkmcnt(0)
	s_barrier
; #define MFMA(a, b, c) __builtin_amdgcn_mfma_f32_16x16x32_bf16((a), (b), (c), 0, 0, 0)
; template <int EPI, int MF>
; __device__ __forceinline__ void gemm_part(const u16* __restrict__ A, int lda, const u16* __restrict__ Bt, int K, int ntn, GemmEpi ep, char* smem,
;                                           int mbase, int mrows) {
;     ...
;     for (int kt = 0; kt < nk; ++kt) {
;       if (kt + 1 < nk) {
;         if (MF == 8) asm volatile("s_waitcnt vmcnt(6)" ::: "memory");
;         else asm volatile("s_waitcnt vmcnt(3)" ::: "memory");
;       } else asm volatile("s_waitcnt vmcnt(0)" ::: "memory");
;       asm volatile("s_waitcnt lgkmcnt(0)" ::: "memory");
;       __builtin_amdgcn_s_barrier();
;       const u16* a_ = sbase + (kt % 3) * STG;
;       const u16* b_ = a_ + BM * 32;
;       bf16x8 bfr[4], afc[2], afn[2];
;       const u16* ap_ = a_ + (wr * (16 * MF) + fr) * 32 + fq * 8;
; #pragma unroll
;       for (int n = 0; n < 4; ++n) bfr[n] = rd_std(b_ + (wc * 64 + n * 16 + fr) * 32 + fq * 8);
;       afc[0] = rd_std(ap_); afc[1] = rd_std(ap_ + 16 * 32);
;       __builtin_amdgcn_sched_barrier(0);
;       if (kt + 2 < nk) GEMM_ISSUE(kt + 2);
;       __builtin_amdgcn_sched_barrier(0);
; #pragma unroll
;       for (int mh = 0; mh < MF / 2; ++mh) {
;         if (mh + 1 < MF / 2) {
;           afn[0] = rd_std(ap_ + ((mh + 1) * 2) * 16 * 32);
;           afn[1] = rd_std(ap_ + ((mh + 1) * 2 + 1) * 16 * 32);
;         }
;         __builtin_amdgcn_sched_barrier(0);
; #pragma unroll
;         for (int m = 0; m < 2; ++m)
; #pragma unroll
;           for (int n = 0; n < 4; ++n) acc[mh * 2 + m][n] = MFMA(bfr[n], afc[m], acc[mh * 2 + m][n]);
;         __builtin_amdgcn_sched_barrier(0);
;         afc[0] = afn[0]; afc[1] = afn[1];
;       }
;     }
;     ...
;     __syncthreads();
; #pragma unroll
;     for (int m = 0; m < MF; ++m) {
;       if (EPI == EPI_SWIGLU || (m & 1) == 0) __builtin_amdgcn_sched_barrier(0);
;       const int row = row0 + wr * (16 * MF) + m * 16 + fr;
;       const int cb = col0 + wc * 64 + 4 * fq;
;       float rstd = 1.f;
;       if (EPI != EPI_RESID) { if (ep.rss_in) rstd = rsqrtf(ep.rss_in[row] * (1.f / DM) + 1e-6f); }
	ds_read_b128 v[136:139], v159 offset:16384
	ds_read_b128 v[160:163], v159 offset:17408
	ds_read_b128 v[164:167], v159 offset:18432
	ds_read_b128 v[168:171], v159 offset:19456
	ds_read_b128 v[172:175], v158
	ds_read_b128 v[176:179], v158 offset:1024
	ds_read_b128 v[180:183], v158 offset:3072
	ds_read_b128 v[184:187], v158 offset:2048
	s_waitcnt lgkmcnt(0)
	v_mfma_f32_16x16x32_bf16 v[126:129], v[136:139], v[172:175], v[126:129]
	v_mfma_f32_16x16x32_bf16 v[122:125], v[160:163], v[172:175], v[122:125]
	v_mfma_f32_16x16x32_bf16 v[118:121], v[164:167], v[172:175], v[118:121]
	v_mfma_f32_16x16x32_bf16 v[114:117], v[168:171], v[172:175], v[114:117]
	v_mfma_f32_16x16x32_bf16 v[110:113], v[136:139], v[176:179], v[110:113]
	v_mfma_f32_16x16x32_bf16 v[106:109], v[160:163], v[176:179], v[106:109]
	v_mfma_f32_16x16x32_bf16 v[102:105], v[164:167], v[176:179], v[102:105]
	v_mfma_f32_16x16x32_bf16 v[98:101], v[168:171], v[176:179], v[98:101]
	ds_read_b128 v[172:175], v158 offset:5120
	ds_read_b128 v[176:179], v158 offset:4096
	v_mfma_f32_16x16x32_bf16 v[94:97], v[136:139], v[184:187], v[94:97]
	v_mfma_f32_16x16x32_bf16 v[90:93], v[160:163], v[184:187], v[90:93]
	v_mfma_f32_16x16x32_bf16 v[86:89], v[164:167], v[184:187], v[86:89]
	v_mfma_f32_16x16x32_bf16 v[82:85], v[168:171], v[184:187], v[82:85]
	v_mfma_f32_16x16x32_bf16 v[78:81], v[136:139], v[180:183], v[78:81]
	v_mfma_f32_16x16x32_bf16 v[74:77], v[160:163], v[180:183], v[74:77]
	v_mfma_f32_16x16x32_bf16 v[70:73], v[164:167], v[180:183], v[70:73]
	v_mfma_f32_16x16x32_bf16 v[66:69], v[168:171], v[180:183], v[66:69]
	ds_read_b128 v[180:183], v158 offset:7168
	ds_read_b128 v[184:187], v158 offset:6144
	s_waitcnt lgkmcnt(0)
	v_mfma_f32_16x16x32_bf16 v[62:65], v[136:139], v[176:179], v[62:65]
	v_mfma_f32_16x16x32_bf16 v[58:61], v[160:163], v[176:179], v[58:61]
	v_mfma_f32_16x16x32_bf16 v[54:57], v[164:167], v[176:179], v[54:57]
	v_mfma_f32_16x16x32_bf16 v[50:53], v[168:171], v[176:179], v[50:53]
	v_mfma_f32_16x16x32_bf16 v[46:49], v[136:139], v[172:175], v[46:49]
	v_mfma_f32_16x16x32_bf16 v[42:45], v[160:163], v[172:175], v[42:45]
	v_mfma_f32_16x16x32_bf16 v[38:41], v[164:167], v[172:175], v[38:41]
	v_mfma_f32_16x16x32_bf16 v[34:37], v[168:171], v[172:175], v[34:37]
	v_mfma_f32_16x16x32_bf16 v[30:33], v[136:139], v[184:187], v[30:33]
	v_mfma_f32_16x16x32_bf16 v[26:29], v[160:163], v[184:187], v[26:29]
	v_mfma_f32_16x16x32_bf16 v[22:25], v[164:167], v[184:187], v[22:25]
	v_mfma_f32_16x16x32_bf16 v[18:21], v[168:171], v[184:187], v[18:21]
	v_mfma_f32_16x16x32_bf16 v[14:17], v[136:139], v[180:183], v[14:17]
	v_mfma_f32_16x16x32_bf16 v[10:13], v[160:163], v[180:183], v[10:13]
	v_mfma_f32_16x16x32_bf16 v[6:9], v[164:167], v[180:183], v[6:9]
	v_mfma_f32_16x16x32_bf16 v[2:5], v[168:171], v[180:183], v[2:5]
	s_waitcnt vmcnt(0)
	s_waitcnt lgkmcnt(0)
	s_barrier
	ds_read_b128 v[136:139], v159 offset:40960
	ds_read_b128 v[160:163], v159 offset:41984
	ds_read_b128 v[164:167], v159 offset:43008
	ds_read_b128 v[168:171], v159 offset:44032
	ds_read_b128 v[172:175], v158 offset:24576
	ds_read_b128 v[176:179], v158 offset:25600
	ds_read_b128 v[180:183], v158 offset:27648
	ds_read_b128 v[184:187], v158 offset:26624
	s_waitcnt lgkmcnt(0)
	v_mfma_f32_16x16x32_bf16 v[126:129], v[136:139], v[172:175], v[126:129]
	v_mfma_f32_16x16x32_bf16 v[122:125], v[160:163], v[172:175], v[122:125]
	v_mfma_f32_16x16x32_bf16 v[118:121], v[164:167], v[172:175], v[118:121]
	v_mfma_f32_16x16x32_bf16 v[114:117], v[168:171], v[172:175], v[114:117]
	v_mfma_f32_16x16x32_bf16 v[110:113], v[136:139], v[176:179], v[110:113]
	v_mfma_f32_16x16x32_bf16 v[106:109], v[160:163], v[176:179], v[106:109]
	v_mfma_f32_16x16x32_bf16 v[102:105], v[164:167], v[176:179], v[102:105]
	v_mfma_f32_16x16x32_bf16 v[98:101], v[168:171], v[176:179], v[98:101]
	ds_read_b128 v[172:175], v158 offset:29696
	ds_read_b128 v[176:179], v158 offset:28672
	v_mfma_f32_16x16x32_bf16 v[94:97], v[136:139], v[184:187], v[94:97]
	v_mfma_f32_16x16x32_bf16 v[90:93], v[160:163], v[184:187], v[90:93]
	v_mfma_f32_16x16x32_bf16 v[86:89], v[164:167], v[184:187], v[86:89]
	v_mfma_f32_16x16x32_bf16 v[82:85], v[168:171], v[184:187], v[82:85]
	v_mfma_f32_16x16x32_bf16 v[78:81], v[136:139], v[180:183], v[78:81]
	v_mfma_f32_16x16x32_bf16 v[74:77], v[160:163], v[180:183], v[74:77]
	v_mfma_f32_16x16x32_bf16 v[70:73], v[164:167], v[180:183], v[70:73]
	v_mfma_f32_16x16x32_bf16 v[66:69], v[168:171], v[180:183], v[66:69]
	ds_read_b128 v[180:183], v158 offset:31744
	ds_read_b128 v[184:187], v158 offset:30720
	s_waitcnt lgkmcnt(0)
	v_mfma_f32_16x16x32_bf16 v[62:65], v[136:139], v[176:179], v[62:65]
	v_mfma_f32_16x16x32_bf16 v[58:61], v[160:163], v[176:179], v[58:61]
	v_mfma_f32_16x16x32_bf16 v[54:57], v[164:167], v[176:179], v[54:57]
	v_mfma_f32_16x16x32_bf16 v[50:53], v[168:171], v[176:179], v[50:53]
	v_mfma_f32_16x16x32_bf16 v[46:49], v[136:139], v[172:175], v[46:49]
	v_mfma_f32_16x16x32_bf16 v[42:45], v[160:163], v[172:175], v[42:45]
	v_mfma_f32_16x16x32_bf16 v[38:41], v[164:167], v[172:175], v[38:41]
	v_mfma_f32_16x16x32_bf16 v[34:37], v[168:171], v[172:175], v[34:37]
	v_mfma_f32_16x16x32_bf16 v[30:33], v[136:139], v[184:187], v[30:33]
	v_mfma_f32_16x16x32_bf16 v[26:29], v[160:163], v[184:187], v[26:29]
	v_mfma_f32_16x16x32_bf16 v[22:25], v[164:167], v[184:187], v[22:25]
	v_mfma_f32_16x16x32_bf16 v[18:21], v[168:171], v[184:187], v[18:21]
	v_mfma_f32_16x16x32_bf16 v[14:17], v[136:139], v[180:183], v[14:17]
	v_mfma_f32_16x16x32_bf16 v[10:13], v[160:163], v[180:183], v[10:13]
	v_mfma_f32_16x16x32_bf16 v[6:9], v[164:167], v[180:183], v[6:9]
	v_mfma_f32_16x16x32_bf16 v[2:5], v[168:171], v[180:183], v[2:5]
	v_add_u32_e32 v138, s8, v154
	s_waitcnt vmcnt(0)
	s_barrier
	v_readlane_b32 s2, v253, 30
	v_ashrrev_i32_e32 v139, 31, v138
	v_readlane_b32 s3, v253, 31
	s_and_b64 vcc, exec, s[2:3]
	v_lshl_add_u64 v[146:147], v[138:139], 2, s[66:67]
	s_cbranch_vccz .LBB0_417
	global_load_dword v136, v[146:147], off
	s_waitcnt vmcnt(0)
	v_fmamk_f32 v136, v136, 0x3a800000, v142
	v_mul_f32_e32 v137, 0x4b800000, v136
	v_cmp_gt_f32_e32 vcc, s69, v136
	s_nop 1
	v_cndmask_b32_e32 v136, v136, v137, vcc
	v_rsq_f32_e32 v136, v136
	s_nop 0
	v_mul_f32_e32 v137, 0x45800000, v136
	v_cndmask_b32_e32 v148, v136, v137, vcc
	s_branch .LBB0_418

; #define MFMA(a, b, c) __builtin_amdgcn_mfma_f32_16x16x32_bf16((a), (b), (c), 0, 0, 0)
; template <int EPI, int MF>
; __device__ __forceinline__ void gemm_part(const u16* __restrict__ A, int lda, const u16* __restrict__ Bt, int K, int ntn, GemmEpi ep, char* smem,
;                                           int mbase, int mrows) {
;     ...
;     GEMM_ISSUE(0);
;     GEMM_ISSUE(1);
;     for (int kt = 0; kt < nk; ++kt) {
;       if (kt + 1 < nk) {
;         if (MF == 8) asm volatile("s_waitcnt vmcnt(6)" ::: "memory");
;         else asm volatile("s_waitcnt vmcnt(3)" ::: "memory");
;       } else asm volatile("s_waitcnt vmcnt(0)" ::: "memory");
;       asm volatile("s_waitcnt lgkmcnt(0)" ::: "memory");
;       __builtin_amdgcn_s_barrier();
;       const u16* a_ = sbase + (kt % 3) * STG;
;       const u16* b_ = a_ + BM * 32;
;       bf16x8 bfr[4], afc[2], afn[2];
;       const u16* ap_ = a_ + (wr * (16 * MF) + fr) * 32 + fq * 8;
; #pragma unroll
;       for (int n = 0; n < 4; ++n) bfr[n] = rd_std(b_ + (wc * 64 + n * 16 + fr) * 32 + fq * 8);
;       afc[0] = rd_std(ap_); afc[1] = rd_std(ap_ + 16 * 32);
;       __builtin_amdgcn_sched_barrier(0);
;       if (kt + 2 < nk) GEMM_ISSUE(kt + 2);
;       __builtin_amdgcn_sched_barrier(0);
; #pragma unroll
;       for (int mh = 0; mh < MF / 2; ++mh) {
;         if (mh + 1 < MF / 2) {
;           afn[0] = rd_std(ap_ + ((mh + 1) * 2) * 16 * 32);
;           afn[1] = rd_std(ap_ + ((mh + 1) * 2 + 1) * 16 * 32);
;         }
;         __builtin_amdgcn_sched_barrier(0);
; #pragma unroll
;         for (int m = 0; m < 2; ++m)
; #pragma unroll
;           for (int n = 0; n < 4; ++n) acc[mh * 2 + m][n] = MFMA(bfr[n], afc[m], acc[mh * 2 + m][n]);
;         __builtin_amdgcn_sched_barrier(0);
;         afc[0] = afn[0]; afc[1] = afn[1];
;       }
.LBB0_1128:
	s_mul_hi_u32 s13, s12, 0xaaaaaaab
	s_lshr_b32 s13, s13, 1
	s_mul_i32 s13, s13, 0x12000
	v_add_u32_e32 v146, s3, v156
	v_subrev_u32_e32 v147, s13, v159
	v_subrev_u32_e32 v161, s13, v155
	v_add_u32_e32 v147, v146, v147
	v_add_u32_e32 v161, v146, v161
	s_mul_hi_u32 s13, s11, 0xaaaaaaab
	s_add_i32 s12, s12, 1
	s_lshr_b32 s13, s13, 1
	s_mul_i32 s13, s13, 0x12000
	s_sub_i32 s13, s3, s13
	s_add_i32 s14, s13, 0xc000
	v_add_u32_e32 v178, s14, v148
	v_lshl_add_u64 v[162:163], v[136:137], 0, v[134:135]
	v_readfirstlane_b32 s101, v178
	v_lshl_add_u64 v[164:165], v[162:163], 0, s[74:75]
	v_lshl_add_u64 v[166:167], v[162:163], 0, s[92:93]
	v_lshl_add_u64 v[168:169], v[162:163], 0, s[88:89]
	v_lshl_add_u64 v[162:163], v[162:163], 0, s[6:7]
	v_lshl_add_u64 v[170:171], v[138:139], 0, v[134:135]
	v_lshl_add_u64 v[172:173], v[170:171], 0, s[74:75]
	v_lshl_add_u64 v[170:171], v[170:171], 0, s[92:93]
	s_waitcnt vmcnt(6)
	s_waitcnt lgkmcnt(0)
	s_barrier
	s_setprio 2
	s_mov_b32 m0, s101
	s_nop 0
	global_load_lds_dwordx4 v[164:165], off
	s_add_u32 m0, m0, 0x1000
	s_nop 0
	global_load_lds_dwordx4 v[166:167], off
	s_add_u32 m0, m0, 0x1000
	s_nop 0
	global_load_lds_dwordx4 v[168:169], off
	s_add_u32 m0, m0, 0x1000
	s_nop 0
	global_load_lds_dwordx4 v[162:163], off
	s_add_u32 m0, m0, 0x1000
	s_nop 0
	global_load_lds_dwordx4 v[172:173], off
	s_add_u32 m0, m0, 0x1000
	s_nop 0
	global_load_lds_dwordx4 v[170:171], off
	s_setprio 0
	ds_read_b128 v[162:165], v147 offset:16384
	ds_read_b128 v[166:169], v147 offset:17408
	ds_read_b128 v[170:173], v147 offset:18432
	ds_read_b128 v[174:177], v147 offset:19456
	ds_read_b128 v[178:181], v161
	ds_read_b128 v[182:185], v161 offset:1024
	ds_read_b128 v[186:189], v161 offset:3072
	ds_read_b128 v[190:193], v161 offset:2048
	s_waitcnt lgkmcnt(2)
	v_mfma_f32_16x16x32_bf16 v[126:129], v[162:165], v[178:181], v[126:129]
	v_mfma_f32_16x16x32_bf16 v[122:125], v[166:169], v[178:181], v[122:125]
	v_mfma_f32_16x16x32_bf16 v[118:121], v[170:173], v[178:181], v[118:121]
	v_mfma_f32_16x16x32_bf16 v[114:117], v[174:177], v[178:181], v[114:117]
	v_mfma_f32_16x16x32_bf16 v[110:113], v[162:165], v[182:185], v[110:113]
	v_mfma_f32_16x16x32_bf16 v[106:109], v[166:169], v[182:185], v[106:109]
	v_mfma_f32_16x16x32_bf16 v[102:105], v[170:173], v[182:185], v[102:105]
	v_mfma_f32_16x16x32_bf16 v[98:101], v[174:177], v[182:185], v[98:101]
	ds_read_b128 v[178:181], v161 offset:5120
	ds_read_b128 v[182:185], v161 offset:4096
	s_waitcnt lgkmcnt(2)
	v_mfma_f32_16x16x32_bf16 v[94:97], v[162:165], v[190:193], v[94:97]
	v_mfma_f32_16x16x32_bf16 v[90:93], v[166:169], v[190:193], v[90:93]
	v_mfma_f32_16x16x32_bf16 v[86:89], v[170:173], v[190:193], v[86:89]
	v_mfma_f32_16x16x32_bf16 v[82:85], v[174:177], v[190:193], v[82:85]
	v_mfma_f32_16x16x32_bf16 v[78:81], v[162:165], v[186:189], v[78:81]
	v_mfma_f32_16x16x32_bf16 v[74:77], v[166:169], v[186:189], v[74:77]
	v_mfma_f32_16x16x32_bf16 v[70:73], v[170:173], v[186:189], v[70:73]
	v_mfma_f32_16x16x32_bf16 v[66:69], v[174:177], v[186:189], v[66:69]
	ds_read_b128 v[186:189], v161 offset:7168
	ds_read_b128 v[190:193], v161 offset:6144
	s_waitcnt lgkmcnt(2)
	v_mfma_f32_16x16x32_bf16 v[62:65], v[162:165], v[182:185], v[62:65]
	v_mfma_f32_16x16x32_bf16 v[58:61], v[166:169], v[182:185], v[58:61]
	v_mfma_f32_16x16x32_bf16 v[54:57], v[170:173], v[182:185], v[54:57]
	v_mfma_f32_16x16x32_bf16 v[50:53], v[174:177], v[182:185], v[50:53]
	v_mfma_f32_16x16x32_bf16 v[46:49], v[162:165], v[178:181], v[46:49]
	v_mfma_f32_16x16x32_bf16 v[42:45], v[166:169], v[178:181], v[42:45]
	v_mfma_f32_16x16x32_bf16 v[38:41], v[170:173], v[178:181], v[38:41]
	v_mfma_f32_16x16x32_bf16 v[34:37], v[174:177], v[178:181], v[34:37]
	s_waitcnt lgkmcnt(0)
	v_mfma_f32_16x16x32_bf16 v[30:33], v[162:165], v[190:193], v[30:33]
	v_mfma_f32_16x16x32_bf16 v[26:29], v[166:169], v[190:193], v[26:29]
	v_mfma_f32_16x16x32_bf16 v[22:25], v[170:173], v[190:193], v[22:25]
	v_mfma_f32_16x16x32_bf16 v[18:21], v[174:177], v[190:193], v[18:21]
	v_mfma_f32_16x16x32_bf16 v[14:17], v[162:165], v[186:189], v[14:17]
	v_mfma_f32_16x16x32_bf16 v[10:13], v[166:169], v[186:189], v[10:13]
	v_mfma_f32_16x16x32_bf16 v[6:9], v[170:173], v[186:189], v[6:9]
	v_mfma_f32_16x16x32_bf16 v[2:5], v[174:177], v[186:189], v[2:5]
	s_addk_i32 s3, 0x6000
	s_add_i32 s10, s10, 1
	s_add_i32 s11, s11, 1
	v_lshl_add_u64 v[136:137], v[136:137], 0, 64
	s_cmp_eq_u32 s3, 0xb4000
	v_lshl_add_u64 v[138:139], v[138:139], 0, 64
	v_lshl_add_u64 v[138:139], v[138:139], 0, 64
	s_cbranch_scc0 .LBB0_1128
	s_waitcnt vmcnt(6)
	s_waitcnt lgkmcnt(0)
	s_barrier
; #define MFMA(a, b, c) __builtin_amdgcn_mfma_f32_16x16x32_bf16((a), (b), (c), 0, 0, 0)
; template <int EPI, int MF>
; __device__ __forceinline__ void gemm_part(const u16* __restrict__ A, int lda, const u16* __restrict__ Bt, int K, int ntn, GemmEpi ep, char* smem,
;                                           int mbase, int mrows) {
;     ...
;     for (int kt = 0; kt < nk; ++kt) {
;       if (kt + 1 < nk) {
;         if (MF == 8) asm volatile("s_waitcnt vmcnt(6)" ::: "memory");
;         else asm volatile("s_waitcnt vmcnt(3)" ::: "memory");
;       } else asm volatile("s_waitcnt vmcnt(0)" ::: "memory");
;       asm volatile("s_waitcnt lgkmcnt(0)" ::: "memory");
;       __builtin_amdgcn_s_barrier();
;       const u16* a_ = sbase + (kt % 3) * STG;
;       const u16* b_ = a_ + BM * 32;
;       bf16x8 bfr[4], afc[2], afn[2];
;       const u16* ap_ = a_ + (wr * (16 * MF) + fr) * 32 + fq * 8;
; #pragma unroll
;       for (int n = 0; n < 4; ++n) bfr[n] = rd_std(b_ + (wc * 64 + n * 16 + fr) * 32 + fq * 8);
;       afc[0] = rd_std(ap_); afc[1] = rd_std(ap_ + 16 * 32);
;       __builtin_amdgcn_sched_barrier(0);
;       if (kt + 2 < nk) GEMM_ISSUE(kt + 2);
;       __builtin_amdgcn_sched_barrier(0);
; #pragma unroll
;       for (int mh = 0; mh < MF / 2; ++mh) {
;         if (mh + 1 < MF / 2) {
;           afn[0] = rd_std(ap_ + ((mh + 1) * 2) * 16 * 32);
;           afn[1] = rd_std(ap_ + ((mh + 1) * 2 + 1) * 16 * 32);
;         }
;         __builtin_amdgcn_sched_barrier(0);
; #pragma unroll
;         for (int m = 0; m < 2; ++m)
; #pragma unroll
;           for (int n = 0; n < 4; ++n) acc[mh * 2 + m][n] = MFMA(bfr[n], afc[m], acc[mh * 2 + m][n]);
;         __builtin_amdgcn_sched_barrier(0);
;         afc[0] = afn[0]; afc[1] = afn[1];
;       }
	ds_read_b128 v[136:139], v160 offset:16384
	ds_read_b128 v[162:165], v160 offset:17408
	ds_read_b128 v[166:169], v160 offset:18432
	ds_read_b128 v[170:173], v160 offset:19456
	ds_read_b128 v[174:177], v157
	ds_read_b128 v[178:181], v157 offset:1024
	s_mul_hi_u32 s10, s10, 0xaaaaaaab
	s_lshr_b32 s10, s10, 1
	s_mul_i32 s10, s10, 0x12000
	s_sub_i32 s3, s3, s10
	s_add_i32 s3, s3, 0
	s_addk_i32 s3, 0x6000
	ds_read_b128 v[182:185], v157 offset:3072
	ds_read_b128 v[186:189], v157 offset:2048
	s_waitcnt lgkmcnt(0)
	v_mfma_f32_16x16x32_bf16 v[126:129], v[136:139], v[174:177], v[126:129]
	v_mfma_f32_16x16x32_bf16 v[122:125], v[162:165], v[174:177], v[122:125]
	v_mfma_f32_16x16x32_bf16 v[118:121], v[166:169], v[174:177], v[118:121]
	v_mfma_f32_16x16x32_bf16 v[114:117], v[170:173], v[174:177], v[114:117]
	v_mfma_f32_16x16x32_bf16 v[110:113], v[136:139], v[178:181], v[110:113]
	v_mfma_f32_16x16x32_bf16 v[106:109], v[162:165], v[178:181], v[106:109]
	v_mfma_f32_16x16x32_bf16 v[102:105], v[166:169], v[178:181], v[102:105]
	v_mfma_f32_16x16x32_bf16 v[98:101], v[170:173], v[178:181], v[98:101]
	ds_read_b128 v[174:177], v157 offset:5120
	ds_read_b128 v[178:181], v157 offset:4096
	v_mfma_f32_16x16x32_bf16 v[94:97], v[136:139], v[186:189], v[94:97]
	v_mfma_f32_16x16x32_bf16 v[90:93], v[162:165], v[186:189], v[90:93]
	v_mfma_f32_16x16x32_bf16 v[86:89], v[166:169], v[186:189], v[86:89]
	v_mfma_f32_16x16x32_bf16 v[82:85], v[170:173], v[186:189], v[82:85]
	v_mfma_f32_16x16x32_bf16 v[78:81], v[136:139], v[182:185], v[78:81]
	v_mfma_f32_16x16x32_bf16 v[74:77], v[162:165], v[182:185], v[74:77]
	v_mfma_f32_16x16x32_bf16 v[70:73], v[166:169], v[182:185], v[70:73]
	v_mfma_f32_16x16x32_bf16 v[66:69], v[170:173], v[182:185], v[66:69]
	ds_read_b128 v[182:185], v157 offset:7168
	ds_read_b128 v[186:189], v157 offset:6144
	s_waitcnt lgkmcnt(0)
	v_mfma_f32_16x16x32_bf16 v[62:65], v[136:139], v[178:181], v[62:65]
	v_mfma_f32_16x16x32_bf16 v[58:61], v[162:165], v[178:181], v[58:61]
	v_mfma_f32_16x16x32_bf16 v[54:57], v[166:169], v[178:181], v[54:57]
	v_mfma_f32_16x16x32_bf16 v[50:53], v[170:173], v[178:181], v[50:53]
	v_mfma_f32_16x16x32_bf16 v[46:49], v[136:139], v[174:177], v[46:49]
	v_mfma_f32_16x16x32_bf16 v[42:45], v[162:165], v[174:177], v[42:45]
	v_mfma_f32_16x16x32_bf16 v[38:41], v[166:169], v[174:177], v[38:41]
	v_mfma_f32_16x16x32_bf16 v[34:37], v[170:173], v[174:177], v[34:37]
	v_mfma_f32_16x16x32_bf16 v[30:33], v[136:139], v[186:189], v[30:33]
	v_mfma_f32_16x16x32_bf16 v[26:29], v[162:165], v[186:189], v[26:29]
	v_mfma_f32_16x16x32_bf16 v[22:25], v[166:169], v[186:189], v[22:25]
	v_mfma_f32_16x16x32_bf16 v[18:21], v[170:173], v[186:189], v[18:21]
	v_mfma_f32_16x16x32_bf16 v[14:17], v[136:139], v[182:185], v[14:17]
	v_mfma_f32_16x16x32_bf16 v[10:13], v[162:165], v[182:185], v[10:13]
	v_mfma_f32_16x16x32_bf16 v[6:9], v[166:169], v[182:185], v[6:9]
	v_mfma_f32_16x16x32_bf16 v[2:5], v[170:173], v[182:185], v[2:5]
	v_add_u32_e32 v146, s3, v156
	s_waitcnt vmcnt(0)
	v_add3_u32 v147, v146, v153, v154
	s_waitcnt lgkmcnt(0)
	s_barrier
	ds_read_b128 v[136:139], v147 offset:16384
	ds_read_b128 v[162:165], v147 offset:17408
	ds_read_b128 v[166:169], v147 offset:18432
	ds_read_b128 v[170:173], v147 offset:19456
	v_lshl_add_u32 v146, v149, 1, v146
	ds_read_b128 v[174:177], v146
	ds_read_b128 v[178:181], v146 offset:1024
	ds_read_b128 v[182:185], v146 offset:3072
	ds_read_b128 v[186:189], v146 offset:2048
	s_waitcnt lgkmcnt(0)
	v_mfma_f32_16x16x32_bf16 v[126:129], v[136:139], v[174:177], v[126:129]
	v_mfma_f32_16x16x32_bf16 v[122:125], v[162:165], v[174:177], v[122:125]
	v_mfma_f32_16x16x32_bf16 v[118:121], v[166:169], v[174:177], v[118:121]
	v_mfma_f32_16x16x32_bf16 v[114:117], v[170:173], v[174:177], v[114:117]
	v_mfma_f32_16x16x32_bf16 v[110:113], v[136:139], v[178:181], v[110:113]
	v_mfma_f32_16x16x32_bf16 v[106:109], v[162:165], v[178:181], v[106:109]
	v_mfma_f32_16x16x32_bf16 v[102:105], v[166:169], v[178:181], v[102:105]
	v_mfma_f32_16x16x32_bf16 v[98:101], v[170:173], v[178:181], v[98:101]
	ds_read_b128 v[174:177], v146 offset:5120
	ds_read_b128 v[178:181], v146 offset:4096
	v_mfma_f32_16x16x32_bf16 v[94:97], v[136:139], v[186:189], v[94:97]
	v_mfma_f32_16x16x32_bf16 v[90:93], v[162:165], v[186:189], v[90:93]
	v_mfma_f32_16x16x32_bf16 v[86:89], v[166:169], v[186:189], v[86:89]
	v_mfma_f32_16x16x32_bf16 v[82:85], v[170:173], v[186:189], v[82:85]
	v_mfma_f32_16x16x32_bf16 v[78:81], v[136:139], v[182:185], v[78:81]
	v_mfma_f32_16x16x32_bf16 v[74:77], v[162:165], v[182:185], v[74:77]
	v_mfma_f32_16x16x32_bf16 v[70:73], v[166:169], v[182:185], v[70:73]
	v_mfma_f32_16x16x32_bf16 v[66:69], v[170:173], v[182:185], v[66:69]
	ds_read_b128 v[182:185], v146 offset:7168
	ds_read_b128 v[186:189], v146 offset:6144
	s_waitcnt lgkmcnt(0)
	v_mfma_f32_16x16x32_bf16 v[62:65], v[136:139], v[178:181], v[62:65]
	v_mfma_f32_16x16x32_bf16 v[58:61], v[162:165], v[178:181], v[58:61]
	v_mfma_f32_16x16x32_bf16 v[54:57], v[166:169], v[178:181], v[54:57]
	v_mfma_f32_16x16x32_bf16 v[50:53], v[170:173], v[178:181], v[50:53]
	v_mfma_f32_16x16x32_bf16 v[46:49], v[136:139], v[174:177], v[46:49]
	v_mfma_f32_16x16x32_bf16 v[42:45], v[162:165], v[174:177], v[42:45]
	v_mfma_f32_16x16x32_bf16 v[38:41], v[166:169], v[174:177], v[38:41]
	v_mfma_f32_16x16x32_bf16 v[34:37], v[170:173], v[174:177], v[34:37]
	v_mfma_f32_16x16x32_bf16 v[30:33], v[136:139], v[186:189], v[30:33]
	v_mfma_f32_16x16x32_bf16 v[26:29], v[162:165], v[186:189], v[26:29]
	v_mfma_f32_16x16x32_bf16 v[22:25], v[166:169], v[186:189], v[22:25]
	v_mfma_f32_16x16x32_bf16 v[18:21], v[170:173], v[186:189], v[18:21]
	v_mfma_f32_16x16x32_bf16 v[14:17], v[136:139], v[182:185], v[14:17]
	v_mfma_f32_16x16x32_bf16 v[10:13], v[162:165], v[182:185], v[10:13]
	v_mfma_f32_16x16x32_bf16 v[6:9], v[166:169], v[182:185], v[6:9]
	v_mfma_f32_16x16x32_bf16 v[2:5], v[170:173], v[182:185], v[2:5]
	v_add_u32_e32 v136, s2, v151
	s_waitcnt vmcnt(0)
	s_barrier
; template <int EPI, int MF>
; __device__ __forceinline__ void gemm_part(const u16* __restrict__ A, int lda, const u16* __restrict__ Bt, int K, int ntn, GemmEpi ep, char* smem,
;                                           int mbase, int mrows) {
;     ...
;       } else if (EPI == EPI_RESID) {
;         const float* rp = (row < MP) ? ep.res0 + (size_t)row * DM : ep.res1 + (size_t)(row - MP) * DM;
;         float ssq = 0.f;
; #pragma unroll
;         for (int n = 0; n < 4; ++n) {
;           const int col = cb + n * 16;
;           const float4 r = *(const float4*)(rp + col);
;           float4 v;
;           v.x = r.x + ep.scale * acc[m][n][0]; v.y = r.y + ep.scale * acc[m][n][1];
;           v.z = r.z + ep.scale * acc[m][n][2]; v.w = r.w + ep.scale * acc[m][n][3];
;           *(float4*)(ep.outf + (size_t)row * DM + col) = v;
;           if (ep.xcopy) {
;             bf16x4 o;
;             o[0] = (short)f2bf(v.x); o[1] = (short)f2bf(v.y); o[2] = (short)f2bf(v.z); o[3] = (short)f2bf(v.w);
;             *(bf16x4*)(ep.xcopy + (size_t)row * DM + col) = o;
;           }
;           ssq += v.x * v.x + v.y * v.y + v.z * v.z + v.w * v.w;
;         }
;         if (ep.rss_out) {
;           ssq += __shfl_xor(ssq, 16);
;           ssq += __shfl_xor(ssq, 32);
;           if (fq == 0) atomicAdd(ep.rss_out + row, ssq);
;         }
	s_mov_b32 s2, 0xffff
	v_cmp_lt_i32_e64 s[12:13], s2, v136
	s_and_saveexec_b64 s[2:3], s[12:13]
	s_xor_b64 s[2:3], exec, s[2:3]
	v_add_u32_e32 v138, 0xffff0000, v136
	v_mov_b32_e32 v139, v0
	v_lshlrev_b64 v[138:139], 12, v[138:139]
	v_lshl_add_u64 v[146:147], s[72:73], 0, v[138:139]
	v_mov_b32_e32 v137, v0
	s_andn2_saveexec_b64 s[2:3], s[2:3]
	v_ashrrev_i32_e32 v137, 31, v136
	v_lshlrev_b64 v[138:139], 12, v[136:137]
	v_lshl_add_u64 v[146:147], s[26:27], 0, v[138:139]
	s_or_b64 exec, exec, s[2:3]
	v_lshlrev_b64 v[138:139], 12, v[136:137]
	v_or_b32_e32 v161, s9, v152
	v_lshl_add_u64 v[162:163], s[26:27], 0, v[138:139]
	v_lshlrev_b64 v[138:139], 11, v[136:137]
	v_lshl_add_u64 v[166:167], s[28:29], 0, v[138:139]
	v_lshlrev_b32_e32 v138, 2, v161
	v_mov_b32_e32 v139, v0
	v_lshl_add_u64 v[146:147], v[146:147], 0, v[138:139]
	v_lshl_add_u64 v[168:169], v[162:163], 0, v[138:139]
	global_load_dwordx4 v[162:165], v[146:147], off
	global_load_dwordx4 v[172:175], v[146:147], off offset:64
	global_load_dwordx4 v[176:179], v[146:147], off offset:128
	global_load_dwordx4 v[180:183], v[146:147], off offset:192
	s_waitcnt vmcnt(0)
	v_pk_add_f32 v[162:163], v[126:127], v[162:163]
	v_pk_add_f32 v[164:165], v[128:129], v[164:165]
	v_lshlrev_b32_e32 v126, 1, v161
	v_mov_b32_e32 v127, v0
	v_cvt_pk_bf16_f32 v129, v164, v165
	v_cvt_pk_bf16_f32 v128, v162, v163
	v_lshl_add_u64 v[166:167], v[166:167], 0, v[126:127]
	global_store_dwordx4 v[168:169], v[162:165], off
	v_lshlrev_b32_e32 v184, 1, v166
	v_bfi_b32 v184, s100, v184, v166
	v_lshrrev_b32_e32 v185, 5, v166
	v_bfi_b32 v184, 64, v185, v184
	v_mov_b32_e32 v185, v167
	global_store_dwordx2 v[184:185], v[128:129], off
	v_pk_mul_f32 v[128:129], v[162:163], v[162:163]
	v_pk_mul_f32 v[170:171], v[164:165], v[164:165]
	s_nop 0
	s_nop 0
	v_pk_add_f32 v[122:123], v[122:123], v[172:173]
	v_pk_add_f32 v[124:125], v[124:125], v[174:175]
	v_cvt_pk_bf16_f32 v162, v122, v123
	v_cvt_pk_bf16_f32 v163, v124, v125
	global_store_dwordx4 v[168:169], v[122:125], off offset:64
	v_lshlrev_b32_e32 v184, 1, v166
	v_bfi_b32 v184, s100, v184, v166
	v_lshrrev_b32_e32 v185, 5, v166
	v_bfi_b32 v184, 64, v185, v184
	v_mov_b32_e32 v185, v167
	global_store_dwordx2 v[184:185], v[162:163], off offset:32
	v_pk_mul_f32 v[162:163], v[122:123], v[122:123]
	v_pk_mul_f32 v[164:165], v[124:125], v[124:125]
	s_nop 0
	s_nop 0
	v_pk_add_f32 v[118:119], v[118:119], v[176:177]
	v_pk_add_f32 v[120:121], v[120:121], v[178:179]
	v_cvt_pk_bf16_f32 v122, v118, v119
	v_cvt_pk_bf16_f32 v123, v120, v121
	global_store_dwordx4 v[168:169], v[118:121], off offset:128
	v_lshlrev_b32_e32 v184, 1, v166
	v_bfi_b32 v184, s100, v184, v166
	v_lshrrev_b32_e32 v185, 5, v166
	v_bfi_b32 v184, 64, v185, v184
	v_mov_b32_e32 v185, v167
	global_store_dwordx2 v[184:185], v[122:123], off offset:128
	v_pk_mul_f32 v[122:123], v[118:119], v[118:119]
	v_pk_mul_f32 v[124:125], v[120:121], v[120:121]
	s_nop 0
	s_nop 0
	v_pk_add_f32 v[114:115], v[114:115], v[180:181]
	v_pk_add_f32 v[116:117], v[116:117], v[182:183]
	v_cvt_pk_bf16_f32 v118, v114, v115
	v_cvt_pk_bf16_f32 v119, v116, v117
	global_store_dwordx4 v[168:169], v[114:117], off offset:192
	v_lshlrev_b32_e32 v184, 1, v166
	v_bfi_b32 v184, s100, v184, v166
	v_lshrrev_b32_e32 v185, 5, v166
	v_bfi_b32 v184, 64, v185, v184
	v_mov_b32_e32 v185, v167
	global_store_dwordx2 v[184:185], v[118:119], off offset:160
	v_add_f32_e32 v118, v128, v129
	v_add_f32_e32 v119, v162, v163
	v_pk_mul_f32 v[114:115], v[114:115], v[114:115]
	v_add_f32_e32 v118, v170, v118
	v_add_f32_e32 v119, v164, v119
	v_pk_mul_f32 v[116:117], v[116:117], v[116:117]
	v_add_f32_e32 v118, v171, v118
	v_add_f32_e32 v119, v165, v119
	v_add_f32_e32 v114, v114, v115
	v_add_f32_e32 v118, v118, v119
	v_add_f32_e32 v119, v122, v123
	v_add_f32_e32 v114, v116, v114
	v_and_b32_e32 v116, 64, v141
	v_add_f32_e32 v119, v124, v119
	v_xor_b32_e32 v115, 16, v141
	v_add_u32_e32 v116, 64, v116
	v_add_f32_e32 v119, v125, v119
	v_cmp_lt_i32_e64 s[12:13], v115, v116
	v_add_f32_e32 v118, v118, v119
	v_add_f32_e32 v114, v117, v114
	v_cndmask_b32_e64 v115, v141, v115, s[12:13]
	v_add_f32_e32 v114, v118, v114
	v_lshlrev_b32_e32 v118, 2, v115
	ds_bpermute_b32 v115, v118, v114
	s_waitcnt lgkmcnt(0)
	v_add_f32_e32 v114, v114, v115
	v_xor_b32_e32 v115, 32, v141
	v_cmp_lt_i32_e64 s[12:13], v115, v116
	s_nop 1
	v_cndmask_b32_e64 v115, v141, v115, s[12:13]
	v_lshlrev_b32_e32 v119, 2, v115
	ds_bpermute_b32 v115, v119, v114
	s_and_saveexec_b64 s[2:3], vcc
	s_cbranch_execz .LBB0_1135
	v_readlane_b32 s10, v252, 9
	v_readlane_b32 s11, v252, 10
	s_waitcnt lgkmcnt(0)
	v_add_f32_e32 v114, v114, v115
	v_lshl_add_u64 v[116:117], v[136:137], 2, s[10:11]
	global_atomic_add_f32 v[116:117], v114, off

; #define MFMA(a, b, c) __builtin_amdgcn_mfma_f32_16x16x32_bf16((a), (b), (c), 0, 0, 0)
; template <int EPI, int MF>
; __device__ __forceinline__ void gemm_part(const u16* __restrict__ A, int lda, const u16* __restrict__ Bt, int K, int ntn, GemmEpi ep, char* smem,
;                                           int mbase, int mrows) {
;     ...
;     GEMM_ISSUE(0);
;     GEMM_ISSUE(1);
;     for (int kt = 0; kt < nk; ++kt) {
;       if (kt + 1 < nk) {
;         if (MF == 8) asm volatile("s_waitcnt vmcnt(6)" ::: "memory");
;         else asm volatile("s_waitcnt vmcnt(3)" ::: "memory");
;       } else asm volatile("s_waitcnt vmcnt(0)" ::: "memory");
;       asm volatile("s_waitcnt lgkmcnt(0)" ::: "memory");
;       __builtin_amdgcn_s_barrier();
;       const u16* a_ = sbase + (kt % 3) * STG;
;       const u16* b_ = a_ + BM * 32;
;       bf16x8 bfr[4], afc[2], afn[2];
;       const u16* ap_ = a_ + (wr * (16 * MF) + fr) * 32 + fq * 8;
; #pragma unroll
;       for (int n = 0; n < 4; ++n) bfr[n] = rd_std(b_ + (wc * 64 + n * 16 + fr) * 32 + fq * 8);
;       afc[0] = rd_std(ap_); afc[1] = rd_std(ap_ + 16 * 32);
;       __builtin_amdgcn_sched_barrier(0);
;       if (kt + 2 < nk) GEMM_ISSUE(kt + 2);
;       __builtin_amdgcn_sched_barrier(0);
; #pragma unroll
;       for (int mh = 0; mh < MF / 2; ++mh) {
;         if (mh + 1 < MF / 2) {
;           afn[0] = rd_std(ap_ + ((mh + 1) * 2) * 16 * 32);
;           afn[1] = rd_std(ap_ + ((mh + 1) * 2 + 1) * 16 * 32);
;         }
;         __builtin_amdgcn_sched_barrier(0);
; #pragma unroll
;         for (int m = 0; m < 2; ++m)
; #pragma unroll
;           for (int n = 0; n < 4; ++n) acc[mh * 2 + m][n] = MFMA(bfr[n], afc[m], acc[mh * 2 + m][n]);
;         __builtin_amdgcn_sched_barrier(0);
;         afc[0] = afn[0]; afc[1] = afn[1];
;       }
.LBB0_1202:
	s_mul_i32 s12, s5, 0xab
	s_add_i32 s13, s12, 0xfeaa
	s_bfe_u32 s13, s13, 0x70009
	s_mul_i32 s13, s13, 3
	s_sub_i32 s13, s5, s13
	s_add_i32 s13, s13, 0xfffe
	s_and_b32 s13, s13, 0xff
	s_mulk_i32 s13, 0x6000
	v_add_u32_e32 v192, s13, v212
	v_add_u32_e32 v175, s13, v210
	s_bfe_u32 s12, s12, 0x70009
	s_mul_i32 s12, s12, 3
	s_sub_i32 s12, s5, s12
	s_and_b32 s12, s12, 0xff
	s_mulk_i32 s12, 0x6000
	v_add_u32_e32 v234, s12, v194
	v_lshl_add_u64 v[180:181], s[2:3], 1, v[178:179]
	v_readfirstlane_b32 s101, v234
	v_lshl_add_u64 v[182:183], v[180:181], 0, s[74:75]
	v_lshl_add_u64 v[184:185], v[180:181], 0, s[92:93]
	v_lshl_add_u64 v[186:187], v[180:181], 0, s[88:89]
	v_lshl_add_u64 v[180:181], v[180:181], 0, s[6:7]
	v_lshl_add_u64 v[188:189], s[2:3], 1, v[176:177]
	v_lshl_add_u64 v[190:191], v[188:189], 0, s[74:75]
	v_lshl_add_u64 v[188:189], v[188:189], 0, s[92:93]
	s_waitcnt vmcnt(6)
	s_waitcnt lgkmcnt(0)
	s_barrier
	s_setprio 2
	s_mov_b32 m0, s101
	s_nop 0
	global_load_lds_dwordx4 v[182:183], off
	s_add_u32 m0, m0, 0x1000
	s_nop 0
	global_load_lds_dwordx4 v[184:185], off
	s_add_u32 m0, m0, 0x1000
	s_nop 0
	global_load_lds_dwordx4 v[186:187], off
	s_add_u32 m0, m0, 0x1000
	s_nop 0
	global_load_lds_dwordx4 v[180:181], off
	s_add_u32 m0, m0, 0x1000
	s_nop 0
	global_load_lds_dwordx4 v[190:191], off
	s_add_u32 m0, m0, 0x1000
	s_nop 0
	global_load_lds_dwordx4 v[188:189], off
	s_setprio 0
	ds_read_b128 v[180:183], v192 offset:16384
	ds_read_b128 v[184:187], v192 offset:17408
	ds_read_b128 v[188:191], v192 offset:18432
	ds_read_b128 v[230:233], v192 offset:19456
	ds_read_b128 v[234:237], v175
	ds_read_b128 v[238:241], v175 offset:1024
	ds_read_b128 v[242:245], v175 offset:3072
	ds_read_b128 v[246:249], v175 offset:2048
	s_waitcnt lgkmcnt(2)
	v_mfma_f32_16x16x32_bf16 v[126:129], v[180:183], v[234:237], v[126:129]
	v_mfma_f32_16x16x32_bf16 v[122:125], v[184:187], v[234:237], v[122:125]
	v_mfma_f32_16x16x32_bf16 v[118:121], v[188:191], v[234:237], v[118:121]
	v_mfma_f32_16x16x32_bf16 v[114:117], v[230:233], v[234:237], v[114:117]
	v_mfma_f32_16x16x32_bf16 v[110:113], v[180:183], v[238:241], v[110:113]
	v_mfma_f32_16x16x32_bf16 v[106:109], v[184:187], v[238:241], v[106:109]
	v_mfma_f32_16x16x32_bf16 v[102:105], v[188:191], v[238:241], v[102:105]
	v_mfma_f32_16x16x32_bf16 v[98:101], v[230:233], v[238:241], v[98:101]
	ds_read_b128 v[234:237], v175 offset:5120
	ds_read_b128 v[238:241], v175 offset:4096
	s_waitcnt lgkmcnt(2)
	v_mfma_f32_16x16x32_bf16 v[94:97], v[180:183], v[246:249], v[94:97]
	v_mfma_f32_16x16x32_bf16 v[90:93], v[184:187], v[246:249], v[90:93]
	v_mfma_f32_16x16x32_bf16 v[86:89], v[188:191], v[246:249], v[86:89]
	v_mfma_f32_16x16x32_bf16 v[82:85], v[230:233], v[246:249], v[82:85]
	v_mfma_f32_16x16x32_bf16 v[78:81], v[180:183], v[242:245], v[78:81]
	v_mfma_f32_16x16x32_bf16 v[74:77], v[184:187], v[242:245], v[74:77]
	v_mfma_f32_16x16x32_bf16 v[70:73], v[188:191], v[242:245], v[70:73]
	v_mfma_f32_16x16x32_bf16 v[66:69], v[230:233], v[242:245], v[66:69]
	ds_read_b128 v[242:245], v175 offset:7168
	ds_read_b128 v[246:249], v175 offset:6144
	s_waitcnt lgkmcnt(2)
	v_mfma_f32_16x16x32_bf16 v[62:65], v[180:183], v[238:241], v[62:65]
	v_mfma_f32_16x16x32_bf16 v[58:61], v[184:187], v[238:241], v[58:61]
	v_mfma_f32_16x16x32_bf16 v[54:57], v[188:191], v[238:241], v[54:57]
	v_mfma_f32_16x16x32_bf16 v[50:53], v[230:233], v[238:241], v[50:53]
	v_mfma_f32_16x16x32_bf16 v[46:49], v[180:183], v[234:237], v[46:49]
	v_mfma_f32_16x16x32_bf16 v[42:45], v[184:187], v[234:237], v[42:45]
	v_mfma_f32_16x16x32_bf16 v[38:41], v[188:191], v[234:237], v[38:41]
	v_mfma_f32_16x16x32_bf16 v[34:37], v[230:233], v[234:237], v[34:37]
	s_waitcnt lgkmcnt(0)
	v_mfma_f32_16x16x32_bf16 v[30:33], v[180:183], v[246:249], v[30:33]
	v_mfma_f32_16x16x32_bf16 v[26:29], v[184:187], v[246:249], v[26:29]
	v_mfma_f32_16x16x32_bf16 v[22:25], v[188:191], v[246:249], v[22:25]
	v_mfma_f32_16x16x32_bf16 v[18:21], v[230:233], v[246:249], v[18:21]
	v_mfma_f32_16x16x32_bf16 v[14:17], v[180:183], v[242:245], v[14:17]
	v_mfma_f32_16x16x32_bf16 v[10:13], v[184:187], v[242:245], v[10:13]
	v_mfma_f32_16x16x32_bf16 v[6:9], v[188:191], v[242:245], v[6:9]
	v_mfma_f32_16x16x32_bf16 v[2:5], v[230:233], v[242:245], v[2:5]
	s_add_u32 s2, s2, 64
	s_addc_u32 s3, s3, 0
	s_add_i32 s5, s5, 1
	s_cmpk_eq_i32 s2, 0x780
	s_cbranch_scc0 .LBB0_1202
	s_waitcnt vmcnt(6)
	s_waitcnt lgkmcnt(0)
	s_barrier
; #define MFMA(a, b, c) __builtin_amdgcn_mfma_f32_16x16x32_bf16((a), (b), (c), 0, 0, 0)
; template <int EPI, int MF>
; __device__ __forceinline__ void gemm_part(const u16* __restrict__ A, int lda, const u16* __restrict__ Bt, int K, int ntn, GemmEpi ep, char* smem,
;                                           int mbase, int mrows) {
;     ...
;     for (int kt = 0; kt < nk; ++kt) {
;       if (kt + 1 < nk) {
;         if (MF == 8) asm volatile("s_waitcnt vmcnt(6)" ::: "memory");
;         else asm volatile("s_waitcnt vmcnt(3)" ::: "memory");
;       } else asm volatile("s_waitcnt vmcnt(0)" ::: "memory");
;       asm volatile("s_waitcnt lgkmcnt(0)" ::: "memory");
;       __builtin_amdgcn_s_barrier();
;       const u16* a_ = sbase + (kt % 3) * STG;
;       const u16* b_ = a_ + BM * 32;
;       bf16x8 bfr[4], afc[2], afn[2];
;       const u16* ap_ = a_ + (wr * (16 * MF) + fr) * 32 + fq * 8;
; #pragma unroll
;       for (int n = 0; n < 4; ++n) bfr[n] = rd_std(b_ + (wc * 64 + n * 16 + fr) * 32 + fq * 8);
;       afc[0] = rd_std(ap_); afc[1] = rd_std(ap_ + 16 * 32);
;       __builtin_amdgcn_sched_barrier(0);
;       if (kt + 2 < nk) GEMM_ISSUE(kt + 2);
;       __builtin_amdgcn_sched_barrier(0);
; #pragma unroll
;       for (int mh = 0; mh < MF / 2; ++mh) {
;         if (mh + 1 < MF / 2) {
;           afn[0] = rd_std(ap_ + ((mh + 1) * 2) * 16 * 32);
;           afn[1] = rd_std(ap_ + ((mh + 1) * 2 + 1) * 16 * 32);
;         }
;         __builtin_amdgcn_sched_barrier(0);
; #pragma unroll
;         for (int m = 0; m < 2; ++m)
; #pragma unroll
;           for (int n = 0; n < 4; ++n) acc[mh * 2 + m][n] = MFMA(bfr[n], afc[m], acc[mh * 2 + m][n]);
;         __builtin_amdgcn_sched_barrier(0);
;         afc[0] = afn[0]; afc[1] = afn[1];
;       }
;     }
;     ...
;     __syncthreads();
; #pragma unroll
;     for (int m = 0; m < MF; ++m) {
;       if (EPI == EPI_SWIGLU || (m & 1) == 0) __builtin_amdgcn_sched_barrier(0);
;       const int row = row0 + wr * (16 * MF) + m * 16 + fr;
;       const int cb = col0 + wc * 64 + 4 * fq;
;       float rstd = 1.f;
;       if (EPI != EPI_RESID) { if (ep.rss_in) rstd = rsqrtf(ep.rss_in[row] * (1.f / DM) + 1e-6f); }
	ds_read_b128 v[176:179], v212 offset:16384
	ds_read_b128 v[180:183], v212 offset:17408
	ds_read_b128 v[184:187], v212 offset:18432
	ds_read_b128 v[188:191], v212 offset:19456
	ds_read_b128 v[230:233], v210
	ds_read_b128 v[234:237], v210 offset:1024
	ds_read_b128 v[238:241], v210 offset:3072
	ds_read_b128 v[242:245], v210 offset:2048
	s_waitcnt lgkmcnt(0)
	v_mfma_f32_16x16x32_bf16 v[126:129], v[176:179], v[230:233], v[126:129]
	v_mfma_f32_16x16x32_bf16 v[122:125], v[180:183], v[230:233], v[122:125]
	v_mfma_f32_16x16x32_bf16 v[118:121], v[184:187], v[230:233], v[118:121]
	v_mfma_f32_16x16x32_bf16 v[114:117], v[188:191], v[230:233], v[114:117]
	v_mfma_f32_16x16x32_bf16 v[110:113], v[176:179], v[234:237], v[110:113]
	v_mfma_f32_16x16x32_bf16 v[106:109], v[180:183], v[234:237], v[106:109]
	v_mfma_f32_16x16x32_bf16 v[102:105], v[184:187], v[234:237], v[102:105]
	v_mfma_f32_16x16x32_bf16 v[98:101], v[188:191], v[234:237], v[98:101]
	ds_read_b128 v[230:233], v210 offset:5120
	ds_read_b128 v[234:237], v210 offset:4096
	v_mfma_f32_16x16x32_bf16 v[94:97], v[176:179], v[242:245], v[94:97]
	v_mfma_f32_16x16x32_bf16 v[90:93], v[180:183], v[242:245], v[90:93]
	v_mfma_f32_16x16x32_bf16 v[86:89], v[184:187], v[242:245], v[86:89]
	v_mfma_f32_16x16x32_bf16 v[82:85], v[188:191], v[242:245], v[82:85]
	v_mfma_f32_16x16x32_bf16 v[78:81], v[176:179], v[238:241], v[78:81]
	v_mfma_f32_16x16x32_bf16 v[74:77], v[180:183], v[238:241], v[74:77]
	v_mfma_f32_16x16x32_bf16 v[70:73], v[184:187], v[238:241], v[70:73]
	v_mfma_f32_16x16x32_bf16 v[66:69], v[188:191], v[238:241], v[66:69]
	ds_read_b128 v[238:241], v210 offset:7168
	ds_read_b128 v[242:245], v210 offset:6144
	s_waitcnt lgkmcnt(0)
	v_mfma_f32_16x16x32_bf16 v[62:65], v[176:179], v[234:237], v[62:65]
	v_mfma_f32_16x16x32_bf16 v[58:61], v[180:183], v[234:237], v[58:61]
	v_mfma_f32_16x16x32_bf16 v[54:57], v[184:187], v[234:237], v[54:57]
	v_mfma_f32_16x16x32_bf16 v[50:53], v[188:191], v[234:237], v[50:53]
	v_mfma_f32_16x16x32_bf16 v[46:49], v[176:179], v[230:233], v[46:49]
	v_mfma_f32_16x16x32_bf16 v[42:45], v[180:183], v[230:233], v[42:45]
	v_mfma_f32_16x16x32_bf16 v[38:41], v[184:187], v[230:233], v[38:41]
	v_mfma_f32_16x16x32_bf16 v[34:37], v[188:191], v[230:233], v[34:37]
	v_mfma_f32_16x16x32_bf16 v[30:33], v[176:179], v[242:245], v[30:33]
	v_mfma_f32_16x16x32_bf16 v[26:29], v[180:183], v[242:245], v[26:29]
	v_mfma_f32_16x16x32_bf16 v[22:25], v[184:187], v[242:245], v[22:25]
	v_mfma_f32_16x16x32_bf16 v[18:21], v[188:191], v[242:245], v[18:21]
	v_mfma_f32_16x16x32_bf16 v[14:17], v[176:179], v[238:241], v[14:17]
	v_mfma_f32_16x16x32_bf16 v[10:13], v[180:183], v[238:241], v[10:13]
	v_mfma_f32_16x16x32_bf16 v[6:9], v[184:187], v[238:241], v[6:9]
	v_mfma_f32_16x16x32_bf16 v[2:5], v[188:191], v[238:241], v[2:5]
	s_waitcnt vmcnt(0)
	s_waitcnt lgkmcnt(0)
	s_barrier
	ds_read_b128 v[176:179], v212 offset:40960
	ds_read_b128 v[180:183], v212 offset:41984
	ds_read_b128 v[184:187], v212 offset:43008
	ds_read_b128 v[188:191], v212 offset:44032
	ds_read_b128 v[230:233], v210 offset:24576
	ds_read_b128 v[234:237], v210 offset:25600
	ds_read_b128 v[238:241], v210 offset:27648
	ds_read_b128 v[242:245], v210 offset:26624
	s_waitcnt lgkmcnt(0)
	v_mfma_f32_16x16x32_bf16 v[126:129], v[176:179], v[230:233], v[126:129]
	v_mfma_f32_16x16x32_bf16 v[122:125], v[180:183], v[230:233], v[122:125]
	v_mfma_f32_16x16x32_bf16 v[118:121], v[184:187], v[230:233], v[118:121]
	v_mfma_f32_16x16x32_bf16 v[114:117], v[188:191], v[230:233], v[114:117]
	v_mfma_f32_16x16x32_bf16 v[110:113], v[176:179], v[234:237], v[110:113]
	v_mfma_f32_16x16x32_bf16 v[106:109], v[180:183], v[234:237], v[106:109]
	v_mfma_f32_16x16x32_bf16 v[102:105], v[184:187], v[234:237], v[102:105]
	v_mfma_f32_16x16x32_bf16 v[98:101], v[188:191], v[234:237], v[98:101]
	ds_read_b128 v[230:233], v210 offset:29696
	ds_read_b128 v[234:237], v210 offset:28672
	v_mfma_f32_16x16x32_bf16 v[94:97], v[176:179], v[242:245], v[94:97]
	v_mfma_f32_16x16x32_bf16 v[90:93], v[180:183], v[242:245], v[90:93]
	v_mfma_f32_16x16x32_bf16 v[86:89], v[184:187], v[242:245], v[86:89]
	v_mfma_f32_16x16x32_bf16 v[82:85], v[188:191], v[242:245], v[82:85]
	v_mfma_f32_16x16x32_bf16 v[78:81], v[176:179], v[238:241], v[78:81]
	v_mfma_f32_16x16x32_bf16 v[74:77], v[180:183], v[238:241], v[74:77]
	v_mfma_f32_16x16x32_bf16 v[70:73], v[184:187], v[238:241], v[70:73]
	v_mfma_f32_16x16x32_bf16 v[66:69], v[188:191], v[238:241], v[66:69]
	ds_read_b128 v[238:241], v210 offset:31744
	ds_read_b128 v[242:245], v210 offset:30720
	s_waitcnt lgkmcnt(0)
	v_mfma_f32_16x16x32_bf16 v[62:65], v[176:179], v[234:237], v[62:65]
	v_mfma_f32_16x16x32_bf16 v[58:61], v[180:183], v[234:237], v[58:61]
	v_mfma_f32_16x16x32_bf16 v[54:57], v[184:187], v[234:237], v[54:57]
	v_mfma_f32_16x16x32_bf16 v[50:53], v[188:191], v[234:237], v[50:53]
	v_mfma_f32_16x16x32_bf16 v[46:49], v[176:179], v[230:233], v[46:49]
	v_mfma_f32_16x16x32_bf16 v[42:45], v[180:183], v[230:233], v[42:45]
	v_mfma_f32_16x16x32_bf16 v[38:41], v[184:187], v[230:233], v[38:41]
	v_mfma_f32_16x16x32_bf16 v[34:37], v[188:191], v[230:233], v[34:37]
	v_mfma_f32_16x16x32_bf16 v[30:33], v[176:179], v[242:245], v[30:33]
	v_mfma_f32_16x16x32_bf16 v[26:29], v[180:183], v[242:245], v[26:29]
	v_mfma_f32_16x16x32_bf16 v[22:25], v[184:187], v[242:245], v[22:25]
	v_mfma_f32_16x16x32_bf16 v[18:21], v[188:191], v[242:245], v[18:21]
	v_mfma_f32_16x16x32_bf16 v[14:17], v[176:179], v[238:241], v[14:17]
	v_mfma_f32_16x16x32_bf16 v[10:13], v[180:183], v[238:241], v[10:13]
	v_mfma_f32_16x16x32_bf16 v[6:9], v[184:187], v[238:241], v[6:9]
	v_mfma_f32_16x16x32_bf16 v[2:5], v[188:191], v[238:241], v[2:5]
	v_add_u32_e32 v178, s9, v197
	s_waitcnt vmcnt(0)
	s_barrier
	v_readlane_b32 s2, v253, 30
	v_ashrrev_i32_e32 v179, 31, v178
	v_readlane_b32 s3, v253, 31
	s_and_b64 vcc, exec, s[2:3]
	v_lshl_add_u64 v[180:181], v[178:179], 2, s[66:67]
	s_cbranch_vccz .LBB0_1205
	global_load_dword v175, v[180:181], off
	s_waitcnt vmcnt(0)
	v_fmamk_f32 v175, v175, 0x3a800000, v142
	v_mul_f32_e32 v176, 0x4b800000, v175
	v_cmp_gt_f32_e32 vcc, s69, v175
	s_nop 1
	v_cndmask_b32_e32 v175, v175, v176, vcc
	v_rsq_f32_e32 v175, v175
	s_nop 0
	v_mul_f32_e32 v176, 0x45800000, v175
	v_cndmask_b32_e32 v182, v175, v176, vcc
	s_branch .LBB0_1206

; #define MFMA(a, b, c) __builtin_amdgcn_mfma_f32_16x16x32_bf16((a), (b), (c), 0, 0, 0)
; template <int EPI, int MF>
; __device__ __forceinline__ void gemm_part(const u16* __restrict__ A, int lda, const u16* __restrict__ Bt, int K, int ntn, GemmEpi ep, char* smem,
;                                           int mbase, int mrows) {
;     ...
;     GEMM_ISSUE(0);
;     GEMM_ISSUE(1);
;     for (int kt = 0; kt < nk; ++kt) {
;       if (kt + 1 < nk) {
;         if (MF == 8) asm volatile("s_waitcnt vmcnt(6)" ::: "memory");
;         else asm volatile("s_waitcnt vmcnt(3)" ::: "memory");
;       } else asm volatile("s_waitcnt vmcnt(0)" ::: "memory");
;       asm volatile("s_waitcnt lgkmcnt(0)" ::: "memory");
;       __builtin_amdgcn_s_barrier();
;       const u16* a_ = sbase + (kt % 3) * STG;
;       const u16* b_ = a_ + BM * 32;
;       bf16x8 bfr[4], afc[2], afn[2];
;       const u16* ap_ = a_ + (wr * (16 * MF) + fr) * 32 + fq * 8;
; #pragma unroll
;       for (int n = 0; n < 4; ++n) bfr[n] = rd_std(b_ + (wc * 64 + n * 16 + fr) * 32 + fq * 8);
;       afc[0] = rd_std(ap_); afc[1] = rd_std(ap_ + 16 * 32);
;       __builtin_amdgcn_sched_barrier(0);
;       if (kt + 2 < nk) GEMM_ISSUE(kt + 2);
;       __builtin_amdgcn_sched_barrier(0);
; #pragma unroll
;       for (int mh = 0; mh < MF / 2; ++mh) {
;         if (mh + 1 < MF / 2) {
;           afn[0] = rd_std(ap_ + ((mh + 1) * 2) * 16 * 32);
;           afn[1] = rd_std(ap_ + ((mh + 1) * 2 + 1) * 16 * 32);
;         }
;         __builtin_amdgcn_sched_barrier(0);
; #pragma unroll
;         for (int m = 0; m < 2; ++m)
; #pragma unroll
;           for (int n = 0; n < 4; ++n) acc[mh * 2 + m][n] = MFMA(bfr[n], afc[m], acc[mh * 2 + m][n]);
;         __builtin_amdgcn_sched_barrier(0);
;         afc[0] = afn[0]; afc[1] = afn[1];
;       }
.LBB0_1947:
	s_mul_i32 s12, s9, 0xab
	s_add_i32 s13, s12, 0xfeaa
	s_bfe_u32 s13, s13, 0x70009
	s_mul_i32 s13, s13, 3
	s_sub_i32 s13, s9, s13
	s_add_i32 s13, s13, 0xfffe
	s_and_b32 s13, s13, 0xff
	s_mulk_i32 s13, 0x6000
	v_add_u32_e32 v168, s13, v155
	v_add_u32_e32 v188, s13, v154
	s_bfe_u32 s12, s12, 0x70009
	s_mul_i32 s12, s12, 3
	s_sub_i32 s12, s9, s12
	s_and_b32 s12, s12, 0xff
	s_mulk_i32 s12, 0x6000
	v_add_u32_e32 v172, s12, v150
	v_lshl_add_u64 v[156:157], s[2:3], 1, v[148:149]
	v_readfirstlane_b32 s101, v172
	v_lshl_add_u64 v[158:159], v[156:157], 0, s[30:31]
	s_mov_b64 s[12:13], 0x162e0080
	v_lshl_add_u64 v[160:161], v[156:157], 0, s[12:13]
	s_mov_b64 s[12:13], 0x16300080
	v_lshl_add_u64 v[162:163], v[156:157], 0, s[12:13]
	s_mov_b64 s[12:13], 0x16320080
	v_lshl_add_u64 v[156:157], v[156:157], 0, s[12:13]
	v_lshl_add_u64 v[164:165], s[2:3], 1, v[146:147]
	v_lshl_add_u64 v[166:167], v[164:165], 0, s[74:75]
	v_lshl_add_u64 v[164:165], v[164:165], 0, s[92:93]
	s_waitcnt vmcnt(6)
	s_waitcnt lgkmcnt(0)
	s_barrier
	s_setprio 2
	s_mov_b32 m0, s101
	s_nop 0
	global_load_lds_dwordx4 v[158:159], off
	s_add_u32 m0, m0, 0x1000
	s_nop 0
	global_load_lds_dwordx4 v[160:161], off
	s_add_u32 m0, m0, 0x1000
	s_nop 0
	global_load_lds_dwordx4 v[162:163], off
	s_add_u32 m0, m0, 0x1000
	s_nop 0
	global_load_lds_dwordx4 v[156:157], off
	s_add_u32 m0, m0, 0x1000
	s_nop 0
	global_load_lds_dwordx4 v[166:167], off
	s_add_u32 m0, m0, 0x1000
	s_nop 0
	global_load_lds_dwordx4 v[164:165], off
	s_setprio 0
	ds_read_b128 v[156:159], v168 offset:16384
	ds_read_b128 v[160:163], v168 offset:17408
	ds_read_b128 v[164:167], v168 offset:18432
	ds_read_b128 v[168:171], v168 offset:19456
	ds_read_b128 v[172:175], v188
	ds_read_b128 v[176:179], v188 offset:1024
	ds_read_b128 v[180:183], v188 offset:2048
	ds_read_b128 v[184:187], v188 offset:3072
	s_waitcnt lgkmcnt(2)
	v_mfma_f32_16x16x32_bf16 v[126:129], v[156:159], v[172:175], v[126:129]
	v_mfma_f32_16x16x32_bf16 v[122:125], v[160:163], v[172:175], v[122:125]
	v_mfma_f32_16x16x32_bf16 v[118:121], v[164:167], v[172:175], v[118:121]
	v_mfma_f32_16x16x32_bf16 v[114:117], v[168:171], v[172:175], v[114:117]
	v_mfma_f32_16x16x32_bf16 v[110:113], v[156:159], v[176:179], v[110:113]
	v_mfma_f32_16x16x32_bf16 v[106:109], v[160:163], v[176:179], v[106:109]
	v_mfma_f32_16x16x32_bf16 v[102:105], v[164:167], v[176:179], v[102:105]
	v_mfma_f32_16x16x32_bf16 v[98:101], v[168:171], v[176:179], v[98:101]
	ds_read_b128 v[172:175], v188 offset:4096
	ds_read_b128 v[176:179], v188 offset:5120
	s_waitcnt lgkmcnt(2)
	v_mfma_f32_16x16x32_bf16 v[94:97], v[156:159], v[180:183], v[94:97]
	v_mfma_f32_16x16x32_bf16 v[90:93], v[160:163], v[180:183], v[90:93]
	v_mfma_f32_16x16x32_bf16 v[86:89], v[164:167], v[180:183], v[86:89]
	v_mfma_f32_16x16x32_bf16 v[82:85], v[168:171], v[180:183], v[82:85]
	v_mfma_f32_16x16x32_bf16 v[78:81], v[156:159], v[184:187], v[78:81]
	v_mfma_f32_16x16x32_bf16 v[74:77], v[160:163], v[184:187], v[74:77]
	v_mfma_f32_16x16x32_bf16 v[70:73], v[164:167], v[184:187], v[70:73]
	v_mfma_f32_16x16x32_bf16 v[66:69], v[168:171], v[184:187], v[66:69]
	ds_read_b128 v[180:183], v188 offset:6144
	ds_read_b128 v[184:187], v188 offset:7168
	s_waitcnt lgkmcnt(2)
	v_mfma_f32_16x16x32_bf16 v[62:65], v[156:159], v[172:175], v[62:65]
	v_mfma_f32_16x16x32_bf16 v[58:61], v[160:163], v[172:175], v[58:61]
	v_mfma_f32_16x16x32_bf16 v[54:57], v[164:167], v[172:175], v[54:57]
	v_mfma_f32_16x16x32_bf16 v[50:53], v[168:171], v[172:175], v[50:53]
	v_mfma_f32_16x16x32_bf16 v[46:49], v[156:159], v[176:179], v[46:49]
	v_mfma_f32_16x16x32_bf16 v[42:45], v[160:163], v[176:179], v[42:45]
	v_mfma_f32_16x16x32_bf16 v[38:41], v[164:167], v[176:179], v[38:41]
	v_mfma_f32_16x16x32_bf16 v[34:37], v[168:171], v[176:179], v[34:37]
	s_waitcnt lgkmcnt(0)
	v_mfma_f32_16x16x32_bf16 v[30:33], v[156:159], v[180:183], v[30:33]
	v_mfma_f32_16x16x32_bf16 v[26:29], v[160:163], v[180:183], v[26:29]
	v_mfma_f32_16x16x32_bf16 v[22:25], v[164:167], v[180:183], v[22:25]
	v_mfma_f32_16x16x32_bf16 v[18:21], v[168:171], v[180:183], v[18:21]
	v_mfma_f32_16x16x32_bf16 v[14:17], v[156:159], v[184:187], v[14:17]
	v_mfma_f32_16x16x32_bf16 v[10:13], v[160:163], v[184:187], v[10:13]
	v_mfma_f32_16x16x32_bf16 v[6:9], v[164:167], v[184:187], v[6:9]
	v_mfma_f32_16x16x32_bf16 v[2:5], v[168:171], v[184:187], v[2:5]
	s_add_u32 s2, s2, 64
	s_addc_u32 s3, s3, 0
	s_add_i32 s9, s9, 1
	s_cmpk_eq_i32 s2, 0x780
	s_cbranch_scc0 .LBB0_1947
	s_waitcnt vmcnt(6)
	s_waitcnt lgkmcnt(0)
	s_barrier
; #define MFMA(a, b, c) __builtin_amdgcn_mfma_f32_16x16x32_bf16((a), (b), (c), 0, 0, 0)
; template <int EPI, int MF>
; __device__ __forceinline__ void gemm_part(const u16* __restrict__ A, int lda, const u16* __restrict__ Bt, int K, int ntn, GemmEpi ep, char* smem,
;                                           int mbase, int mrows) {
;     ...
;     for (int kt = 0; kt < nk; ++kt) {
;       if (kt + 1 < nk) {
;         if (MF == 8) asm volatile("s_waitcnt vmcnt(6)" ::: "memory");
;         else asm volatile("s_waitcnt vmcnt(3)" ::: "memory");
;       } else asm volatile("s_waitcnt vmcnt(0)" ::: "memory");
;       asm volatile("s_waitcnt lgkmcnt(0)" ::: "memory");
;       __builtin_amdgcn_s_barrier();
;       const u16* a_ = sbase + (kt % 3) * STG;
;       const u16* b_ = a_ + BM * 32;
;       bf16x8 bfr[4], afc[2], afn[2];
;       const u16* ap_ = a_ + (wr * (16 * MF) + fr) * 32 + fq * 8;
; #pragma unroll
;       for (int n = 0; n < 4; ++n) bfr[n] = rd_std(b_ + (wc * 64 + n * 16 + fr) * 32 + fq * 8);
;       afc[0] = rd_std(ap_); afc[1] = rd_std(ap_ + 16 * 32);
;       __builtin_amdgcn_sched_barrier(0);
;       if (kt + 2 < nk) GEMM_ISSUE(kt + 2);
;       __builtin_amdgcn_sched_barrier(0);
; #pragma unroll
;       for (int mh = 0; mh < MF / 2; ++mh) {
;         if (mh + 1 < MF / 2) {
;           afn[0] = rd_std(ap_ + ((mh + 1) * 2) * 16 * 32);
;           afn[1] = rd_std(ap_ + ((mh + 1) * 2 + 1) * 16 * 32);
;         }
;         __builtin_amdgcn_sched_barrier(0);
; #pragma unroll
;         for (int m = 0; m < 2; ++m)
; #pragma unroll
;           for (int n = 0; n < 4; ++n) acc[mh * 2 + m][n] = MFMA(bfr[n], afc[m], acc[mh * 2 + m][n]);
;         __builtin_amdgcn_sched_barrier(0);
;         afc[0] = afn[0]; afc[1] = afn[1];
;       }
;     }
	ds_read_b128 v[146:149], v155 offset:16384
	ds_read_b128 v[156:159], v155 offset:17408
	ds_read_b128 v[160:163], v155 offset:18432
	ds_read_b128 v[164:167], v155 offset:19456
	ds_read_b128 v[168:171], v154
	ds_read_b128 v[172:175], v154 offset:1024
	ds_read_b128 v[176:179], v154 offset:2048
	ds_read_b128 v[180:183], v154 offset:3072
	s_waitcnt lgkmcnt(0)
	v_mfma_f32_16x16x32_bf16 v[126:129], v[146:149], v[168:171], v[126:129]
	v_mfma_f32_16x16x32_bf16 v[122:125], v[156:159], v[168:171], v[122:125]
	v_mfma_f32_16x16x32_bf16 v[184:187], v[160:163], v[168:171], v[118:121]
	v_mfma_f32_16x16x32_bf16 v[114:117], v[164:167], v[168:171], v[114:117]
	v_mfma_f32_16x16x32_bf16 v[110:113], v[146:149], v[172:175], v[110:113]
	v_mfma_f32_16x16x32_bf16 v[106:109], v[156:159], v[172:175], v[106:109]
	v_mfma_f32_16x16x32_bf16 v[168:171], v[160:163], v[172:175], v[102:105]
	v_mfma_f32_16x16x32_bf16 v[98:101], v[164:167], v[172:175], v[98:101]
	s_nop 1
	ds_read_b128 v[102:105], v154 offset:4096
	ds_read_b128 v[118:121], v154 offset:5120
	v_mfma_f32_16x16x32_bf16 v[94:97], v[146:149], v[176:179], v[94:97]
	v_mfma_f32_16x16x32_bf16 v[90:93], v[156:159], v[176:179], v[90:93]
	v_mfma_f32_16x16x32_bf16 v[172:175], v[160:163], v[176:179], v[86:89]
	v_mfma_f32_16x16x32_bf16 v[82:85], v[164:167], v[176:179], v[82:85]
	v_mfma_f32_16x16x32_bf16 v[78:81], v[146:149], v[180:183], v[78:81]
	v_mfma_f32_16x16x32_bf16 v[74:77], v[156:159], v[180:183], v[74:77]
	v_mfma_f32_16x16x32_bf16 v[176:179], v[160:163], v[180:183], v[70:73]
	v_mfma_f32_16x16x32_bf16 v[66:69], v[164:167], v[180:183], v[66:69]
	s_nop 1
	ds_read_b128 v[70:73], v154 offset:6144
	ds_read_b128 v[86:89], v154 offset:7168
	s_waitcnt lgkmcnt(0)
	v_mfma_f32_16x16x32_bf16 v[62:65], v[146:149], v[102:105], v[62:65]
	v_mfma_f32_16x16x32_bf16 v[58:61], v[156:159], v[102:105], v[58:61]
	v_mfma_f32_16x16x32_bf16 v[180:183], v[160:163], v[102:105], v[54:57]
	v_mfma_f32_16x16x32_bf16 v[50:53], v[164:167], v[102:105], v[50:53]
	v_mfma_f32_16x16x32_bf16 v[46:49], v[146:149], v[118:121], v[46:49]
	v_mfma_f32_16x16x32_bf16 v[42:45], v[156:159], v[118:121], v[42:45]
	v_mfma_f32_16x16x32_bf16 v[188:191], v[160:163], v[118:121], v[38:41]
	v_mfma_f32_16x16x32_bf16 v[34:37], v[164:167], v[118:121], v[34:37]
	v_mfma_f32_16x16x32_bf16 v[30:33], v[146:149], v[70:73], v[30:33]
	v_mfma_f32_16x16x32_bf16 v[26:29], v[156:159], v[70:73], v[26:29]
	v_mfma_f32_16x16x32_bf16 v[192:195], v[160:163], v[70:73], v[22:25]
	v_mfma_f32_16x16x32_bf16 v[18:21], v[164:167], v[70:73], v[18:21]
	v_mfma_f32_16x16x32_bf16 v[14:17], v[146:149], v[86:89], v[14:17]
	v_mfma_f32_16x16x32_bf16 v[10:13], v[156:159], v[86:89], v[10:13]
	v_mfma_f32_16x16x32_bf16 v[146:149], v[160:163], v[86:89], v[6:9]
	v_mfma_f32_16x16x32_bf16 v[2:5], v[164:167], v[86:89], v[2:5]
	s_waitcnt vmcnt(0)
	s_waitcnt lgkmcnt(0)
	s_barrier
	s_nop 0
	ds_read_b128 v[6:9], v155 offset:40960
	ds_read_b128 v[156:159], v155 offset:41984
	ds_read_b128 v[160:163], v155 offset:43008
	ds_read_b128 v[164:167], v155 offset:44032
	ds_read_b128 v[22:25], v154 offset:24576
	ds_read_b128 v[38:41], v154 offset:25600
	ds_read_b128 v[54:57], v154 offset:26624
	ds_read_b128 v[196:199], v154 offset:27648
	s_waitcnt lgkmcnt(0)
	v_mfma_f32_16x16x32_bf16 v[210:213], v[6:9], v[22:25], v[126:129]
	v_mfma_f32_16x16x32_bf16 v[118:121], v[156:159], v[22:25], v[122:125]
	v_mfma_f32_16x16x32_bf16 v[184:187], v[160:163], v[22:25], v[184:187]
	v_mfma_f32_16x16x32_bf16 v[114:117], v[164:167], v[22:25], v[114:117]
	v_mfma_f32_16x16x32_bf16 v[110:113], v[6:9], v[38:41], v[110:113]
	v_mfma_f32_16x16x32_bf16 v[102:105], v[156:159], v[38:41], v[106:109]
	v_mfma_f32_16x16x32_bf16 v[106:109], v[160:163], v[38:41], v[168:171]
	v_mfma_f32_16x16x32_bf16 v[98:101], v[164:167], v[38:41], v[98:101]
	ds_read_b128 v[22:25], v154 offset:28672
	ds_read_b128 v[122:125], v154 offset:29696
	v_mfma_f32_16x16x32_bf16 v[94:97], v[6:9], v[54:57], v[94:97]
	v_mfma_f32_16x16x32_bf16 v[86:89], v[156:159], v[54:57], v[90:93]
	v_mfma_f32_16x16x32_bf16 v[90:93], v[160:163], v[54:57], v[172:175]
	v_mfma_f32_16x16x32_bf16 v[82:85], v[164:167], v[54:57], v[82:85]
	v_mfma_f32_16x16x32_bf16 v[78:81], v[6:9], v[196:199], v[78:81]
	v_mfma_f32_16x16x32_bf16 v[70:73], v[156:159], v[196:199], v[74:77]
	v_mfma_f32_16x16x32_bf16 v[74:77], v[160:163], v[196:199], v[176:179]
	v_mfma_f32_16x16x32_bf16 v[66:69], v[164:167], v[196:199], v[66:69]
	ds_read_b128 v[126:129], v154 offset:30720
	ds_read_b128 v[168:171], v154 offset:31744
	s_waitcnt lgkmcnt(0)
	v_mfma_f32_16x16x32_bf16 v[62:65], v[6:9], v[22:25], v[62:65]
	v_mfma_f32_16x16x32_bf16 v[54:57], v[156:159], v[22:25], v[58:61]
	v_mfma_f32_16x16x32_bf16 v[58:61], v[160:163], v[22:25], v[180:183]
	v_mfma_f32_16x16x32_bf16 v[50:53], v[164:167], v[22:25], v[50:53]
	v_mfma_f32_16x16x32_bf16 v[46:49], v[6:9], v[122:125], v[46:49]
	v_mfma_f32_16x16x32_bf16 v[38:41], v[156:159], v[122:125], v[42:45]
	v_mfma_f32_16x16x32_bf16 v[42:45], v[160:163], v[122:125], v[188:191]
	v_mfma_f32_16x16x32_bf16 v[34:37], v[164:167], v[122:125], v[34:37]
	v_mfma_f32_16x16x32_bf16 v[30:33], v[6:9], v[126:129], v[30:33]
	v_mfma_f32_16x16x32_bf16 v[22:25], v[156:159], v[126:129], v[26:29]
	v_mfma_f32_16x16x32_bf16 v[26:29], v[160:163], v[126:129], v[192:195]
	v_mfma_f32_16x16x32_bf16 v[18:21], v[164:167], v[126:129], v[18:21]
	v_mfma_f32_16x16x32_bf16 v[14:17], v[6:9], v[168:171], v[14:17]
	v_mfma_f32_16x16x32_bf16 v[6:9], v[156:159], v[168:171], v[10:13]
	v_mfma_f32_16x16x32_bf16 v[10:13], v[160:163], v[168:171], v[146:149]
	v_mfma_f32_16x16x32_bf16 v[2:5], v[164:167], v[168:171], v[2:5]
	s_lshl_b32 s90, s5, 8
	s_waitcnt vmcnt(0)
	s_barrier
; __device__ __forceinline__ float siluf_(float x) { return x * __builtin_amdgcn_rcpf(1.f + __expf(-x)); }
; template <int EPI, int MF>
; __device__ __forceinline__ void gemm_part(const u16* __restrict__ A, int lda, const u16* __restrict__ Bt, int K, int ntn, GemmEpi ep, char* smem,
;                                           int mbase, int mrows) {
;     ...
;     for (int m = 0; m < MF; ++m) {
;       if (EPI == EPI_SWIGLU || (m & 1) == 0) __builtin_amdgcn_sched_barrier(0);
;       const int row = row0 + wr * (16 * MF) + m * 16 + fr;
;       const int cb = col0 + wc * 64 + 4 * fq;
;       float rstd = 1.f;
;       if (EPI != EPI_RESID) { if (ep.rss_in) rstd = rsqrtf(ep.rss_in[row] * (1.f / DM) + 1e-6f); }
;       if (EPI == EPI_SWIGLU) {
; #pragma unroll
;         for (int n = 0; n < 2; ++n) {
;           bf16x4 o;
; #pragma unroll
;           for (int jj = 0; jj < 4; ++jj) o[jj] = (short)f2bf(siluf_(acc[m][n][jj] * rstd) * (acc[m][n + 2][jj] * rstd));
;           *(bf16x4*)(ep.outb + (size_t)row * FF + (col0 >> 1) + wc * 32 + n * 16 + 4 * fq) = o;
;         }
	v_add_u32_e32 v124, s8, v152
	v_lshl_add_u64 v[122:123], v[136:137], 0, s[90:91]
	v_readlane_b32 s2, v252, 9
	v_ashrrev_i32_e32 v125, 31, v124
	v_readlane_b32 s3, v252, 10
	s_nop 1
	v_lshl_add_u64 v[126:127], v[124:125], 2, s[2:3]
	global_load_dword v125, v[126:127], off
	s_waitcnt vmcnt(0)
	v_fmamk_f32 v125, v125, 0x3a800000, v142
	v_cmp_gt_f32_e32 vcc, s69, v125
	v_mul_f32_e32 v128, 0x4b800000, v125
	s_nop 0
	v_cndmask_b32_e32 v125, v125, v128, vcc
	v_rsq_f32_e32 v125, v125
	s_nop 0
	v_mul_f32_e32 v128, 0x45800000, v125
	v_cndmask_b32_e32 v146, v125, v128, vcc
	v_pk_mul_f32 v[148:149], v[210:211], v[146:147] op_sel_hi:[1,0]
	v_pk_mul_f32 v[118:119], v[118:119], v[146:147] op_sel_hi:[1,0]
	v_mul_f32_e32 v125, 0xbfb8aa3b, v148
	v_exp_f32_e32 v125, v125
	v_mad_i64_i32 v[128:129], s[2:3], v124, s33, v[122:123]
	v_pk_mul_f32 v[114:115], v[114:115], v[146:147] op_sel_hi:[1,0]
	v_add_f32_e32 v125, 1.0, v125
	v_rcp_f32_e32 v156, v125
	v_mul_f32_e32 v125, 0xbfb8aa3b, v149
	v_exp_f32_e32 v125, v125
	v_pk_mul_f32 v[116:117], v[116:117], v[146:147] op_sel_hi:[1,0]
	v_add_f32_e32 v125, 1.0, v125
	v_rcp_f32_e32 v157, v125
	s_nop 0
	v_pk_mul_f32 v[148:149], v[148:149], v[156:157]
	v_pk_mul_f32 v[156:157], v[184:185], v[146:147] op_sel_hi:[1,0]
	s_nop 0
	v_pk_mul_f32 v[148:149], v[156:157], v[148:149]
	v_pk_mul_f32 v[156:157], v[212:213], v[146:147] op_sel_hi:[1,0]
	v_cvt_pk_bf16_f32 v148, v148, v149
	v_mul_f32_e32 v125, 0xbfb8aa3b, v156
	v_exp_f32_e32 v125, v125
	s_nop 0
	v_add_f32_e32 v125, 1.0, v125
	v_rcp_f32_e32 v158, v125
	v_mul_f32_e32 v125, 0xbfb8aa3b, v157
	v_exp_f32_e32 v125, v125
	s_nop 0
	v_add_f32_e32 v125, 1.0, v125
	v_rcp_f32_e32 v159, v125
	v_mul_f32_e32 v125, 0xbfb8aa3b, v118
	v_exp_f32_e32 v125, v125
	v_pk_mul_f32 v[156:157], v[156:157], v[158:159]
	v_pk_mul_f32 v[158:159], v[186:187], v[146:147] op_sel_hi:[1,0]
	v_add_f32_e32 v125, 1.0, v125
	v_pk_mul_f32 v[156:157], v[158:159], v[156:157]
	s_nop 0
	v_cvt_pk_bf16_f32 v149, v156, v157
	global_store_dwordx2 v[128:129], v[148:149], off
	v_rcp_f32_e32 v148, v125
	v_mul_f32_e32 v125, 0xbfb8aa3b, v119
	v_exp_f32_e32 v125, v125
	s_nop 0
	v_add_f32_e32 v125, 1.0, v125
	v_rcp_f32_e32 v149, v125
	s_nop 0
	v_pk_mul_f32 v[118:119], v[118:119], v[148:149]
	s_nop 0
	v_pk_mul_f32 v[114:115], v[114:115], v[118:119]
	v_pk_mul_f32 v[118:119], v[120:121], v[146:147] op_sel_hi:[1,0]
	v_cvt_pk_bf16_f32 v114, v114, v115
	v_mul_f32_e32 v115, 0xbfb8aa3b, v118
	v_exp_f32_e32 v115, v115
	s_nop 0
	v_add_f32_e32 v115, 1.0, v115
	v_rcp_f32_e32 v120, v115
	v_mul_f32_e32 v115, 0xbfb8aa3b, v119
	v_exp_f32_e32 v115, v115
	s_nop 0
	v_add_f32_e32 v115, 1.0, v115
	v_rcp_f32_e32 v121, v115
	s_nop 0
	v_pk_mul_f32 v[118:119], v[118:119], v[120:121]
	s_nop 0
	v_pk_mul_f32 v[116:117], v[116:117], v[118:119]
	s_nop 0
	v_cvt_pk_bf16_f32 v115, v116, v117
	global_store_dwordx2 v[128:129], v[114:115], off offset:32
	global_load_dword v115, v[126:127], off offset:64
	v_or_b32_e32 v114, 16, v124
	s_waitcnt vmcnt(0)
	v_fmamk_f32 v115, v115, 0x3a800000, v142
	v_cmp_gt_f32_e32 vcc, s69, v115
	v_mul_f32_e32 v116, 0x4b800000, v115
	s_nop 0
	v_cndmask_b32_e32 v115, v115, v116, vcc
	v_rsq_f32_e32 v115, v115
	s_nop 0
	v_mul_f32_e32 v116, 0x45800000, v115
	v_cndmask_b32_e32 v116, v115, v116, vcc
	v_pk_mul_f32 v[110:111], v[110:111], v[116:117] op_sel_hi:[1,0]
	v_mad_i64_i32 v[114:115], s[2:3], v114, s33, v[122:123]
	v_mul_f32_e32 v117, 0xbfb8aa3b, v110
	v_exp_f32_e32 v117, v117
	s_nop 0
	v_add_f32_e32 v117, 1.0, v117
	v_rcp_f32_e32 v118, v117
	v_mul_f32_e32 v117, 0xbfb8aa3b, v111
	v_exp_f32_e32 v117, v117
	s_nop 0
	v_add_f32_e32 v117, 1.0, v117
	v_rcp_f32_e32 v119, v117
	v_pk_mul_f32 v[106:107], v[106:107], v[116:117] op_sel_hi:[1,0]
	v_pk_mul_f32 v[108:109], v[108:109], v[116:117] op_sel_hi:[1,0]
	v_pk_mul_f32 v[102:103], v[102:103], v[116:117] op_sel_hi:[1,0]
	v_pk_mul_f32 v[110:111], v[110:111], v[118:119]
	v_pk_mul_f32 v[98:99], v[98:99], v[116:117] op_sel_hi:[1,0]
	v_pk_mul_f32 v[106:107], v[106:107], v[110:111]
	v_pk_mul_f32 v[110:111], v[112:113], v[116:117] op_sel_hi:[1,0]
	v_cvt_pk_bf16_f32 v106, v106, v107
	v_mul_f32_e32 v107, 0xbfb8aa3b, v110
	v_exp_f32_e32 v107, v107
	v_pk_mul_f32 v[100:101], v[100:101], v[116:117] op_sel_hi:[1,0]
	v_add_f32_e32 v107, 1.0, v107
	v_rcp_f32_e32 v112, v107
	v_mul_f32_e32 v107, 0xbfb8aa3b, v111
	v_exp_f32_e32 v107, v107
	s_nop 0
	v_add_f32_e32 v107, 1.0, v107
	v_rcp_f32_e32 v113, v107
	s_nop 0
	v_pk_mul_f32 v[110:111], v[110:111], v[112:113]
	s_nop 0
	v_pk_mul_f32 v[108:109], v[108:109], v[110:111]
	s_nop 0
	v_cvt_pk_bf16_f32 v107, v108, v109
	global_store_dwordx2 v[114:115], v[106:107], off
	v_mul_f32_e32 v106, 0xbfb8aa3b, v102
	v_mul_f32_e32 v107, 0xbfb8aa3b, v103
	v_exp_f32_e32 v106, v106
	v_exp_f32_e32 v107, v107
	v_add_f32_e32 v106, 1.0, v106
	v_add_f32_e32 v107, 1.0, v107
	v_rcp_f32_e32 v106, v106
	v_rcp_f32_e32 v107, v107
	s_nop 0
	v_pk_mul_f32 v[102:103], v[102:103], v[106:107]
	s_nop 0
	v_pk_mul_f32 v[98:99], v[98:99], v[102:103]
	v_pk_mul_f32 v[102:103], v[104:105], v[116:117] op_sel_hi:[1,0]
	v_cvt_pk_bf16_f32 v98, v98, v99
	v_mul_f32_e32 v99, 0xbfb8aa3b, v102
	v_exp_f32_e32 v99, v99
	s_nop 0
	v_add_f32_e32 v99, 1.0, v99
	v_rcp_f32_e32 v104, v99
	v_mul_f32_e32 v99, 0xbfb8aa3b, v103
	v_exp_f32_e32 v99, v99
	s_nop 0
	v_add_f32_e32 v99, 1.0, v99
	v_rcp_f32_e32 v105, v99
	s_nop 0
	v_pk_mul_f32 v[102:103], v[102:103], v[104:105]
	s_nop 0
	v_pk_mul_f32 v[100:101], v[100:101], v[102:103]
	s_nop 0
	v_cvt_pk_bf16_f32 v99, v100, v101
	global_store_dwordx2 v[114:115], v[98:99], off offset:32
	global_load_dword v99, v[126:127], off offset:128
	v_or_b32_e32 v98, 32, v124
	s_waitcnt vmcnt(0)
; __device__ __forceinline__ float siluf_(float x) { return x * __builtin_amdgcn_rcpf(1.f + __expf(-x)); }
; template <int EPI, int MF>
; __device__ __forceinline__ void gemm_part(const u16* __restrict__ A, int lda, const u16* __restrict__ Bt, int K, int ntn, GemmEpi ep, char* smem,
;                                           int mbase, int mrows) {
;     ...
;     for (int m = 0; m < MF; ++m) {
;       if (EPI == EPI_SWIGLU || (m & 1) == 0) __builtin_amdgcn_sched_barrier(0);
;       const int row = row0 + wr * (16 * MF) + m * 16 + fr;
;       const int cb = col0 + wc * 64 + 4 * fq;
;       float rstd = 1.f;
;       if (EPI != EPI_RESID) { if (ep.rss_in) rstd = rsqrtf(ep.rss_in[row] * (1.f / DM) + 1e-6f); }
;       if (EPI == EPI_SWIGLU) {
; #pragma unroll
;         for (int n = 0; n < 2; ++n) {
;           bf16x4 o;
; #pragma unroll
;           for (int jj = 0; jj < 4; ++jj) o[jj] = (short)f2bf(siluf_(acc[m][n][jj] * rstd) * (acc[m][n + 2][jj] * rstd));
;           *(bf16x4*)(ep.outb + (size_t)row * FF + (col0 >> 1) + wc * 32 + n * 16 + 4 * fq) = o;
;         }
	v_fmamk_f32 v99, v99, 0x3a800000, v142
	v_cmp_gt_f32_e32 vcc, s69, v99
	v_mul_f32_e32 v100, 0x4b800000, v99
	s_nop 0
	v_cndmask_b32_e32 v99, v99, v100, vcc
	v_rsq_f32_e32 v99, v99
	s_nop 0
	v_mul_f32_e32 v100, 0x45800000, v99
	v_cndmask_b32_e32 v100, v99, v100, vcc
	v_pk_mul_f32 v[94:95], v[94:95], v[100:101] op_sel_hi:[1,0]
	v_mad_i64_i32 v[98:99], s[2:3], v98, s33, v[122:123]
	v_mul_f32_e32 v101, 0xbfb8aa3b, v94
	v_exp_f32_e32 v101, v101
	s_nop 0
	v_add_f32_e32 v101, 1.0, v101
	v_rcp_f32_e32 v102, v101
	v_mul_f32_e32 v101, 0xbfb8aa3b, v95
	v_exp_f32_e32 v101, v101
	s_nop 0
	v_add_f32_e32 v101, 1.0, v101
	v_rcp_f32_e32 v103, v101
	v_pk_mul_f32 v[90:91], v[90:91], v[100:101] op_sel_hi:[1,0]
	v_pk_mul_f32 v[92:93], v[92:93], v[100:101] op_sel_hi:[1,0]
	v_pk_mul_f32 v[86:87], v[86:87], v[100:101] op_sel_hi:[1,0]
	v_pk_mul_f32 v[94:95], v[94:95], v[102:103]
	v_pk_mul_f32 v[82:83], v[82:83], v[100:101] op_sel_hi:[1,0]
	v_pk_mul_f32 v[90:91], v[90:91], v[94:95]
	v_pk_mul_f32 v[94:95], v[96:97], v[100:101] op_sel_hi:[1,0]
	v_cvt_pk_bf16_f32 v90, v90, v91
	v_mul_f32_e32 v91, 0xbfb8aa3b, v94
	v_exp_f32_e32 v91, v91
	v_pk_mul_f32 v[84:85], v[84:85], v[100:101] op_sel_hi:[1,0]
	v_add_f32_e32 v91, 1.0, v91
	v_rcp_f32_e32 v96, v91
	v_mul_f32_e32 v91, 0xbfb8aa3b, v95
	v_exp_f32_e32 v91, v91
	s_nop 0
	v_add_f32_e32 v91, 1.0, v91
	v_rcp_f32_e32 v97, v91
	s_nop 0
	v_pk_mul_f32 v[94:95], v[94:95], v[96:97]
	s_nop 0
	v_pk_mul_f32 v[92:93], v[92:93], v[94:95]
	s_nop 0
	v_cvt_pk_bf16_f32 v91, v92, v93
	global_store_dwordx2 v[98:99], v[90:91], off
	v_mul_f32_e32 v90, 0xbfb8aa3b, v86
	v_mul_f32_e32 v91, 0xbfb8aa3b, v87
	v_exp_f32_e32 v90, v90
	v_exp_f32_e32 v91, v91
	v_add_f32_e32 v90, 1.0, v90
	v_add_f32_e32 v91, 1.0, v91
	v_rcp_f32_e32 v90, v90
	v_rcp_f32_e32 v91, v91
	s_nop 0
	v_pk_mul_f32 v[86:87], v[86:87], v[90:91]
	s_nop 0
	v_pk_mul_f32 v[82:83], v[82:83], v[86:87]
	v_pk_mul_f32 v[86:87], v[88:89], v[100:101] op_sel_hi:[1,0]
	v_cvt_pk_bf16_f32 v82, v82, v83
	v_mul_f32_e32 v83, 0xbfb8aa3b, v86
	v_exp_f32_e32 v83, v83
	s_nop 0
	v_add_f32_e32 v83, 1.0, v83
	v_rcp_f32_e32 v88, v83
	v_mul_f32_e32 v83, 0xbfb8aa3b, v87
	v_exp_f32_e32 v83, v83
	s_nop 0
	v_add_f32_e32 v83, 1.0, v83
	v_rcp_f32_e32 v89, v83
	s_nop 0
	v_pk_mul_f32 v[86:87], v[86:87], v[88:89]
	s_nop 0
	v_pk_mul_f32 v[84:85], v[84:85], v[86:87]
	s_nop 0
	v_cvt_pk_bf16_f32 v83, v84, v85
	global_store_dwordx2 v[98:99], v[82:83], off offset:32
	global_load_dword v83, v[126:127], off offset:192
	v_or_b32_e32 v82, 48, v124
	s_waitcnt vmcnt(0)
	v_fmamk_f32 v83, v83, 0x3a800000, v142
	v_cmp_gt_f32_e32 vcc, s69, v83
	v_mul_f32_e32 v84, 0x4b800000, v83
	s_nop 0
	v_cndmask_b32_e32 v83, v83, v84, vcc
	v_rsq_f32_e32 v83, v83
	s_nop 0
	v_mul_f32_e32 v84, 0x45800000, v83
	v_cndmask_b32_e32 v84, v83, v84, vcc
	v_pk_mul_f32 v[78:79], v[78:79], v[84:85] op_sel_hi:[1,0]
	v_mad_i64_i32 v[82:83], s[2:3], v82, s33, v[122:123]
	v_mul_f32_e32 v85, 0xbfb8aa3b, v78
	v_exp_f32_e32 v85, v85
	s_nop 0
	v_add_f32_e32 v85, 1.0, v85
	v_rcp_f32_e32 v86, v85
	v_mul_f32_e32 v85, 0xbfb8aa3b, v79
	v_exp_f32_e32 v85, v85
	s_nop 0
	v_add_f32_e32 v85, 1.0, v85
	v_rcp_f32_e32 v87, v85
	v_pk_mul_f32 v[74:75], v[74:75], v[84:85] op_sel_hi:[1,0]
	v_pk_mul_f32 v[76:77], v[76:77], v[84:85] op_sel_hi:[1,0]
	v_pk_mul_f32 v[70:71], v[70:71], v[84:85] op_sel_hi:[1,0]
	v_pk_mul_f32 v[78:79], v[78:79], v[86:87]
	v_pk_mul_f32 v[66:67], v[66:67], v[84:85] op_sel_hi:[1,0]
	v_pk_mul_f32 v[74:75], v[74:75], v[78:79]
	v_pk_mul_f32 v[78:79], v[80:81], v[84:85] op_sel_hi:[1,0]
	v_cvt_pk_bf16_f32 v74, v74, v75
	v_mul_f32_e32 v75, 0xbfb8aa3b, v78
	v_exp_f32_e32 v75, v75
	v_pk_mul_f32 v[68:69], v[68:69], v[84:85] op_sel_hi:[1,0]
	v_add_f32_e32 v75, 1.0, v75
	v_rcp_f32_e32 v80, v75
	v_mul_f32_e32 v75, 0xbfb8aa3b, v79
	v_exp_f32_e32 v75, v75
	s_nop 0
	v_add_f32_e32 v75, 1.0, v75
	v_rcp_f32_e32 v81, v75
	s_nop 0
	v_pk_mul_f32 v[78:79], v[78:79], v[80:81]
	s_nop 0
	v_pk_mul_f32 v[76:77], v[76:77], v[78:79]
	s_nop 0
	v_cvt_pk_bf16_f32 v75, v76, v77
	global_store_dwordx2 v[82:83], v[74:75], off
	v_mul_f32_e32 v74, 0xbfb8aa3b, v70
	v_mul_f32_e32 v75, 0xbfb8aa3b, v71
	v_exp_f32_e32 v74, v74
	v_exp_f32_e32 v75, v75
	v_add_f32_e32 v74, 1.0, v74
	v_add_f32_e32 v75, 1.0, v75
	v_rcp_f32_e32 v74, v74
	v_rcp_f32_e32 v75, v75
	s_nop 0
	v_pk_mul_f32 v[70:71], v[70:71], v[74:75]
	s_nop 0
	v_pk_mul_f32 v[66:67], v[66:67], v[70:71]
	v_pk_mul_f32 v[70:71], v[72:73], v[84:85] op_sel_hi:[1,0]
	v_cvt_pk_bf16_f32 v66, v66, v67
	v_mul_f32_e32 v67, 0xbfb8aa3b, v70
	v_exp_f32_e32 v67, v67
	s_nop 0
	v_add_f32_e32 v67, 1.0, v67
	v_rcp_f32_e32 v72, v67
	v_mul_f32_e32 v67, 0xbfb8aa3b, v71
	v_exp_f32_e32 v67, v67
	s_nop 0
	v_add_f32_e32 v67, 1.0, v67
	v_rcp_f32_e32 v73, v67
	s_nop 0
	v_pk_mul_f32 v[70:71], v[70:71], v[72:73]
	s_nop 0
	v_pk_mul_f32 v[68:69], v[68:69], v[70:71]
	s_nop 0
	v_cvt_pk_bf16_f32 v67, v68, v69
	global_store_dwordx2 v[82:83], v[66:67], off offset:32
	global_load_dword v67, v[126:127], off offset:256
	v_or_b32_e32 v66, 64, v124
	s_waitcnt vmcnt(0)
; __device__ __forceinline__ float siluf_(float x) { return x * __builtin_amdgcn_rcpf(1.f + __expf(-x)); }
; template <int EPI, int MF>
; __device__ __forceinline__ void gemm_part(const u16* __restrict__ A, int lda, const u16* __restrict__ Bt, int K, int ntn, GemmEpi ep, char* smem,
;                                           int mbase, int mrows) {
;     ...
;     for (int m = 0; m < MF; ++m) {
;       if (EPI == EPI_SWIGLU || (m & 1) == 0) __builtin_amdgcn_sched_barrier(0);
;       const int row = row0 + wr * (16 * MF) + m * 16 + fr;
;       const int cb = col0 + wc * 64 + 4 * fq;
;       float rstd = 1.f;
;       if (EPI != EPI_RESID) { if (ep.rss_in) rstd = rsqrtf(ep.rss_in[row] * (1.f / DM) + 1e-6f); }
;       if (EPI == EPI_SWIGLU) {
; #pragma unroll
;         for (int n = 0; n < 2; ++n) {
;           bf16x4 o;
; #pragma unroll
;           for (int jj = 0; jj < 4; ++jj) o[jj] = (short)f2bf(siluf_(acc[m][n][jj] * rstd) * (acc[m][n + 2][jj] * rstd));
;           *(bf16x4*)(ep.outb + (size_t)row * FF + (col0 >> 1) + wc * 32 + n * 16 + 4 * fq) = o;
;         }
	v_fmamk_f32 v67, v67, 0x3a800000, v142
	v_cmp_gt_f32_e32 vcc, s69, v67
	v_mul_f32_e32 v68, 0x4b800000, v67
	s_nop 0
	v_cndmask_b32_e32 v67, v67, v68, vcc
	v_rsq_f32_e32 v67, v67
	s_nop 0
	v_mul_f32_e32 v68, 0x45800000, v67
	v_cndmask_b32_e32 v68, v67, v68, vcc
	v_pk_mul_f32 v[62:63], v[62:63], v[68:69] op_sel_hi:[1,0]
	v_mad_i64_i32 v[66:67], s[2:3], v66, s33, v[122:123]
	v_mul_f32_e32 v69, 0xbfb8aa3b, v62
	v_exp_f32_e32 v69, v69
	s_nop 0
	v_add_f32_e32 v69, 1.0, v69
	v_rcp_f32_e32 v70, v69
	v_mul_f32_e32 v69, 0xbfb8aa3b, v63
	v_exp_f32_e32 v69, v69
	s_nop 0
	v_add_f32_e32 v69, 1.0, v69
	v_rcp_f32_e32 v71, v69
	v_pk_mul_f32 v[58:59], v[58:59], v[68:69] op_sel_hi:[1,0]
	v_pk_mul_f32 v[60:61], v[60:61], v[68:69] op_sel_hi:[1,0]
	v_pk_mul_f32 v[54:55], v[54:55], v[68:69] op_sel_hi:[1,0]
	v_pk_mul_f32 v[62:63], v[62:63], v[70:71]
	v_pk_mul_f32 v[50:51], v[50:51], v[68:69] op_sel_hi:[1,0]
	v_pk_mul_f32 v[58:59], v[58:59], v[62:63]
	v_pk_mul_f32 v[62:63], v[64:65], v[68:69] op_sel_hi:[1,0]
	v_cvt_pk_bf16_f32 v58, v58, v59
	v_mul_f32_e32 v59, 0xbfb8aa3b, v62
	v_exp_f32_e32 v59, v59
	v_pk_mul_f32 v[52:53], v[52:53], v[68:69] op_sel_hi:[1,0]
	v_add_f32_e32 v59, 1.0, v59
	v_rcp_f32_e32 v64, v59
	v_mul_f32_e32 v59, 0xbfb8aa3b, v63
	v_exp_f32_e32 v59, v59
	s_nop 0
	v_add_f32_e32 v59, 1.0, v59
	v_rcp_f32_e32 v65, v59
	s_nop 0
	v_pk_mul_f32 v[62:63], v[62:63], v[64:65]
	s_nop 0
	v_pk_mul_f32 v[60:61], v[60:61], v[62:63]
	s_nop 0
	v_cvt_pk_bf16_f32 v59, v60, v61
	global_store_dwordx2 v[66:67], v[58:59], off
	v_mul_f32_e32 v58, 0xbfb8aa3b, v54
	v_mul_f32_e32 v59, 0xbfb8aa3b, v55
	v_exp_f32_e32 v58, v58
	v_exp_f32_e32 v59, v59
	v_add_f32_e32 v58, 1.0, v58
	v_add_f32_e32 v59, 1.0, v59
	v_rcp_f32_e32 v58, v58
	v_rcp_f32_e32 v59, v59
	s_nop 0
	v_pk_mul_f32 v[54:55], v[54:55], v[58:59]
	s_nop 0
	v_pk_mul_f32 v[50:51], v[50:51], v[54:55]
	v_pk_mul_f32 v[54:55], v[56:57], v[68:69] op_sel_hi:[1,0]
	v_cvt_pk_bf16_f32 v50, v50, v51
	v_mul_f32_e32 v51, 0xbfb8aa3b, v54
	v_exp_f32_e32 v51, v51
	s_nop 0
	v_add_f32_e32 v51, 1.0, v51
	v_rcp_f32_e32 v56, v51
	v_mul_f32_e32 v51, 0xbfb8aa3b, v55
	v_exp_f32_e32 v51, v51
	s_nop 0
	v_add_f32_e32 v51, 1.0, v51
	v_rcp_f32_e32 v57, v51
	s_nop 0
	v_pk_mul_f32 v[54:55], v[54:55], v[56:57]
	s_nop 0
	v_pk_mul_f32 v[52:53], v[52:53], v[54:55]
	s_nop 0
	v_cvt_pk_bf16_f32 v51, v52, v53
	global_store_dwordx2 v[66:67], v[50:51], off offset:32
	global_load_dword v51, v[126:127], off offset:320
	v_or_b32_e32 v50, 0x50, v124
	s_waitcnt vmcnt(0)
	v_fmamk_f32 v51, v51, 0x3a800000, v142
	v_cmp_gt_f32_e32 vcc, s69, v51
	v_mul_f32_e32 v52, 0x4b800000, v51
	s_nop 0
	v_cndmask_b32_e32 v51, v51, v52, vcc
	v_rsq_f32_e32 v51, v51
	s_nop 0
	v_mul_f32_e32 v52, 0x45800000, v51
	v_cndmask_b32_e32 v52, v51, v52, vcc
	v_pk_mul_f32 v[46:47], v[46:47], v[52:53] op_sel_hi:[1,0]
	v_mad_i64_i32 v[50:51], s[2:3], v50, s33, v[122:123]
	v_mul_f32_e32 v53, 0xbfb8aa3b, v46
	v_exp_f32_e32 v53, v53
	s_nop 0
	v_add_f32_e32 v53, 1.0, v53
	v_rcp_f32_e32 v54, v53
	v_mul_f32_e32 v53, 0xbfb8aa3b, v47
	v_exp_f32_e32 v53, v53
	s_nop 0
	v_add_f32_e32 v53, 1.0, v53
	v_rcp_f32_e32 v55, v53
	v_pk_mul_f32 v[42:43], v[42:43], v[52:53] op_sel_hi:[1,0]
	v_pk_mul_f32 v[44:45], v[44:45], v[52:53] op_sel_hi:[1,0]
	v_pk_mul_f32 v[38:39], v[38:39], v[52:53] op_sel_hi:[1,0]
	v_pk_mul_f32 v[46:47], v[46:47], v[54:55]
	v_pk_mul_f32 v[34:35], v[34:35], v[52:53] op_sel_hi:[1,0]
	v_pk_mul_f32 v[42:43], v[42:43], v[46:47]
	v_pk_mul_f32 v[46:47], v[48:49], v[52:53] op_sel_hi:[1,0]
	v_cvt_pk_bf16_f32 v42, v42, v43
	v_mul_f32_e32 v43, 0xbfb8aa3b, v46
	v_exp_f32_e32 v43, v43
	v_pk_mul_f32 v[36:37], v[36:37], v[52:53] op_sel_hi:[1,0]
	v_add_f32_e32 v43, 1.0, v43
	v_rcp_f32_e32 v48, v43
	v_mul_f32_e32 v43, 0xbfb8aa3b, v47
	v_exp_f32_e32 v43, v43
	s_nop 0
	v_add_f32_e32 v43, 1.0, v43
	v_rcp_f32_e32 v49, v43
	s_nop 0
	v_pk_mul_f32 v[46:47], v[46:47], v[48:49]
	s_nop 0
	v_pk_mul_f32 v[44:45], v[44:45], v[46:47]
	s_nop 0
	v_cvt_pk_bf16_f32 v43, v44, v45
	global_store_dwordx2 v[50:51], v[42:43], off
	v_mul_f32_e32 v42, 0xbfb8aa3b, v38
	v_mul_f32_e32 v43, 0xbfb8aa3b, v39
	v_exp_f32_e32 v42, v42
	v_exp_f32_e32 v43, v43
	v_add_f32_e32 v42, 1.0, v42
	v_add_f32_e32 v43, 1.0, v43
	v_rcp_f32_e32 v42, v42
	v_rcp_f32_e32 v43, v43
	s_nop 0
	v_pk_mul_f32 v[38:39], v[38:39], v[42:43]
	s_nop 0
	v_pk_mul_f32 v[34:35], v[34:35], v[38:39]
	v_pk_mul_f32 v[38:39], v[40:41], v[52:53] op_sel_hi:[1,0]
	v_cvt_pk_bf16_f32 v34, v34, v35
	v_mul_f32_e32 v35, 0xbfb8aa3b, v38
	v_exp_f32_e32 v35, v35
	s_nop 0
	v_add_f32_e32 v35, 1.0, v35
	v_rcp_f32_e32 v40, v35
	v_mul_f32_e32 v35, 0xbfb8aa3b, v39
	v_exp_f32_e32 v35, v35
	s_nop 0
	v_add_f32_e32 v35, 1.0, v35
	v_rcp_f32_e32 v41, v35
	s_nop 0
	v_pk_mul_f32 v[38:39], v[38:39], v[40:41]
	s_nop 0
	v_pk_mul_f32 v[36:37], v[36:37], v[38:39]
	s_nop 0
	v_cvt_pk_bf16_f32 v35, v36, v37
	global_store_dwordx2 v[50:51], v[34:35], off offset:32
	global_load_dword v35, v[126:127], off offset:384
	v_or_b32_e32 v34, 0x60, v124
	s_waitcnt vmcnt(0)
; __device__ __forceinline__ float siluf_(float x) { return x * __builtin_amdgcn_rcpf(1.f + __expf(-x)); }
; template <int EPI, int MF>
; __device__ __forceinline__ void gemm_part(const u16* __restrict__ A, int lda, const u16* __restrict__ Bt, int K, int ntn, GemmEpi ep, char* smem,
;                                           int mbase, int mrows) {
;     ...
;     for (int m = 0; m < MF; ++m) {
;       if (EPI == EPI_SWIGLU || (m & 1) == 0) __builtin_amdgcn_sched_barrier(0);
;       const int row = row0 + wr * (16 * MF) + m * 16 + fr;
;       const int cb = col0 + wc * 64 + 4 * fq;
;       float rstd = 1.f;
;       if (EPI != EPI_RESID) { if (ep.rss_in) rstd = rsqrtf(ep.rss_in[row] * (1.f / DM) + 1e-6f); }
;       if (EPI == EPI_SWIGLU) {
; #pragma unroll
;         for (int n = 0; n < 2; ++n) {
;           bf16x4 o;
; #pragma unroll
;           for (int jj = 0; jj < 4; ++jj) o[jj] = (short)f2bf(siluf_(acc[m][n][jj] * rstd) * (acc[m][n + 2][jj] * rstd));
;           *(bf16x4*)(ep.outb + (size_t)row * FF + (col0 >> 1) + wc * 32 + n * 16 + 4 * fq) = o;
;         }
	v_fmamk_f32 v35, v35, 0x3a800000, v142
	v_cmp_gt_f32_e32 vcc, s69, v35
	v_mul_f32_e32 v36, 0x4b800000, v35
	s_nop 0
	v_cndmask_b32_e32 v35, v35, v36, vcc
	v_rsq_f32_e32 v35, v35
	s_nop 0
	v_mul_f32_e32 v36, 0x45800000, v35
	v_cndmask_b32_e32 v36, v35, v36, vcc
	v_pk_mul_f32 v[30:31], v[30:31], v[36:37] op_sel_hi:[1,0]
	v_mad_i64_i32 v[34:35], s[2:3], v34, s33, v[122:123]
	v_mul_f32_e32 v37, 0xbfb8aa3b, v30
	v_exp_f32_e32 v37, v37
	s_nop 0
	v_add_f32_e32 v37, 1.0, v37
	v_rcp_f32_e32 v38, v37
	v_mul_f32_e32 v37, 0xbfb8aa3b, v31
	v_exp_f32_e32 v37, v37
	s_nop 0
	v_add_f32_e32 v37, 1.0, v37
	v_rcp_f32_e32 v39, v37
	v_pk_mul_f32 v[26:27], v[26:27], v[36:37] op_sel_hi:[1,0]
	v_pk_mul_f32 v[28:29], v[28:29], v[36:37] op_sel_hi:[1,0]
	v_pk_mul_f32 v[22:23], v[22:23], v[36:37] op_sel_hi:[1,0]
	v_pk_mul_f32 v[30:31], v[30:31], v[38:39]
	v_pk_mul_f32 v[18:19], v[18:19], v[36:37] op_sel_hi:[1,0]
	v_pk_mul_f32 v[26:27], v[26:27], v[30:31]
	v_pk_mul_f32 v[30:31], v[32:33], v[36:37] op_sel_hi:[1,0]
	v_cvt_pk_bf16_f32 v26, v26, v27
	v_mul_f32_e32 v27, 0xbfb8aa3b, v30
	v_exp_f32_e32 v27, v27
	v_pk_mul_f32 v[20:21], v[20:21], v[36:37] op_sel_hi:[1,0]
	v_add_f32_e32 v27, 1.0, v27
	v_rcp_f32_e32 v32, v27
	v_mul_f32_e32 v27, 0xbfb8aa3b, v31
	v_exp_f32_e32 v27, v27
	s_nop 0
	v_add_f32_e32 v27, 1.0, v27
	v_rcp_f32_e32 v33, v27
	s_nop 0
	v_pk_mul_f32 v[30:31], v[30:31], v[32:33]
	s_nop 0
	v_pk_mul_f32 v[28:29], v[28:29], v[30:31]
	s_nop 0
	v_cvt_pk_bf16_f32 v27, v28, v29
	global_store_dwordx2 v[34:35], v[26:27], off
	v_mul_f32_e32 v26, 0xbfb8aa3b, v22
	v_mul_f32_e32 v27, 0xbfb8aa3b, v23
	v_exp_f32_e32 v26, v26
	v_exp_f32_e32 v27, v27
	v_add_f32_e32 v26, 1.0, v26
	v_add_f32_e32 v27, 1.0, v27
	v_rcp_f32_e32 v26, v26
	v_rcp_f32_e32 v27, v27
	s_nop 0
	v_pk_mul_f32 v[22:23], v[22:23], v[26:27]
	s_nop 0
	v_pk_mul_f32 v[18:19], v[18:19], v[22:23]
	v_pk_mul_f32 v[22:23], v[24:25], v[36:37] op_sel_hi:[1,0]
	v_cvt_pk_bf16_f32 v18, v18, v19
	v_mul_f32_e32 v19, 0xbfb8aa3b, v22
	v_exp_f32_e32 v19, v19
	s_nop 0
	v_add_f32_e32 v19, 1.0, v19
	v_rcp_f32_e32 v24, v19
	v_mul_f32_e32 v19, 0xbfb8aa3b, v23
	v_exp_f32_e32 v19, v19
	s_nop 0
	v_add_f32_e32 v19, 1.0, v19
	v_rcp_f32_e32 v25, v19
	s_nop 0
	v_pk_mul_f32 v[22:23], v[22:23], v[24:25]
	s_nop 0
	v_pk_mul_f32 v[20:21], v[20:21], v[22:23]
	s_nop 0
	v_cvt_pk_bf16_f32 v19, v20, v21
	global_store_dwordx2 v[34:35], v[18:19], off offset:32
	global_load_dword v19, v[126:127], off offset:448
	v_or_b32_e32 v18, 0x70, v124
	s_waitcnt vmcnt(0)
	v_fmamk_f32 v19, v19, 0x3a800000, v142
	v_cmp_gt_f32_e32 vcc, s69, v19
	v_mul_f32_e32 v20, 0x4b800000, v19
	s_nop 0
	v_cndmask_b32_e32 v19, v19, v20, vcc
	v_rsq_f32_e32 v19, v19
	s_nop 0
	v_mul_f32_e32 v20, 0x45800000, v19
	v_cndmask_b32_e32 v20, v19, v20, vcc
	v_pk_mul_f32 v[14:15], v[14:15], v[20:21] op_sel_hi:[1,0]
	v_mad_i64_i32 v[18:19], s[2:3], v18, s33, v[122:123]
	v_mul_f32_e32 v21, 0xbfb8aa3b, v14
	v_exp_f32_e32 v21, v21
	s_nop 0
	v_add_f32_e32 v21, 1.0, v21
	v_rcp_f32_e32 v22, v21
	v_mul_f32_e32 v21, 0xbfb8aa3b, v15
	v_exp_f32_e32 v21, v21
	s_nop 0
	v_add_f32_e32 v21, 1.0, v21
	v_rcp_f32_e32 v23, v21
	v_pk_mul_f32 v[10:11], v[10:11], v[20:21] op_sel_hi:[1,0]
	v_pk_mul_f32 v[12:13], v[12:13], v[20:21] op_sel_hi:[1,0]
	v_pk_mul_f32 v[6:7], v[6:7], v[20:21] op_sel_hi:[1,0]
	v_pk_mul_f32 v[14:15], v[14:15], v[22:23]
	v_pk_mul_f32 v[2:3], v[2:3], v[20:21] op_sel_hi:[1,0]
	v_pk_mul_f32 v[10:11], v[10:11], v[14:15]
	v_pk_mul_f32 v[14:15], v[16:17], v[20:21] op_sel_hi:[1,0]
	v_cvt_pk_bf16_f32 v10, v10, v11
	v_mul_f32_e32 v11, 0xbfb8aa3b, v14
	v_exp_f32_e32 v11, v11
	v_pk_mul_f32 v[4:5], v[4:5], v[20:21] op_sel_hi:[1,0]
	v_add_f32_e32 v11, 1.0, v11
	v_rcp_f32_e32 v16, v11
	v_mul_f32_e32 v11, 0xbfb8aa3b, v15
	v_exp_f32_e32 v11, v11
	s_nop 0
	v_add_f32_e32 v11, 1.0, v11
	v_rcp_f32_e32 v17, v11
	s_nop 0
	v_pk_mul_f32 v[14:15], v[14:15], v[16:17]
	s_nop 0
	v_pk_mul_f32 v[12:13], v[12:13], v[14:15]
	s_nop 0
	v_cvt_pk_bf16_f32 v11, v12, v13
	global_store_dwordx2 v[18:19], v[10:11], off
	v_mul_f32_e32 v10, 0xbfb8aa3b, v6
	v_mul_f32_e32 v11, 0xbfb8aa3b, v7
	v_exp_f32_e32 v10, v10
	v_exp_f32_e32 v11, v11
	v_add_f32_e32 v10, 1.0, v10
	v_add_f32_e32 v11, 1.0, v11
	v_rcp_f32_e32 v10, v10
	v_rcp_f32_e32 v11, v11
	s_nop 0
	v_pk_mul_f32 v[6:7], v[6:7], v[10:11]
	s_nop 0
	v_pk_mul_f32 v[2:3], v[2:3], v[6:7]
	v_pk_mul_f32 v[6:7], v[8:9], v[20:21] op_sel_hi:[1,0]
	v_cvt_pk_bf16_f32 v2, v2, v3
	v_mul_f32_e32 v3, 0xbfb8aa3b, v6
	v_exp_f32_e32 v3, v3
	s_nop 0
	v_add_f32_e32 v3, 1.0, v3
	v_rcp_f32_e32 v8, v3
	v_mul_f32_e32 v3, 0xbfb8aa3b, v7
	v_exp_f32_e32 v3, v3
	s_nop 0
	v_add_f32_e32 v3, 1.0, v3
	v_rcp_f32_e32 v9, v3
	s_nop 0
	v_pk_mul_f32 v[6:7], v[6:7], v[8:9]
	s_nop 0
	v_pk_mul_f32 v[4:5], v[4:5], v[6:7]
	s_nop 0
	v_cvt_pk_bf16_f32 v3, v4, v5
	global_store_dwordx2 v[18:19], v[2:3], off offset:32
	s_branch .LBB0_1944

; #define MFMA(a, b, c) __builtin_amdgcn_mfma_f32_16x16x32_bf16((a), (b), (c), 0, 0, 0)
; template <int EPI, int MF>
; __device__ __forceinline__ void gemm_part(const u16* __restrict__ A, int lda, const u16* __restrict__ Bt, int K, int ntn, GemmEpi ep, char* smem,
;                                           int mbase, int mrows) {
;     ...
;     GEMM_ISSUE(0);
;     GEMM_ISSUE(1);
;     for (int kt = 0; kt < nk; ++kt) {
;       if (kt + 1 < nk) {
;         if (MF == 8) asm volatile("s_waitcnt vmcnt(6)" ::: "memory");
;         else asm volatile("s_waitcnt vmcnt(3)" ::: "memory");
;       } else asm volatile("s_waitcnt vmcnt(0)" ::: "memory");
;       asm volatile("s_waitcnt lgkmcnt(0)" ::: "memory");
;       __builtin_amdgcn_s_barrier();
;       const u16* a_ = sbase + (kt % 3) * STG;
;       const u16* b_ = a_ + BM * 32;
;       bf16x8 bfr[4], afc[2], afn[2];
;       const u16* ap_ = a_ + (wr * (16 * MF) + fr) * 32 + fq * 8;
; #pragma unroll
;       for (int n = 0; n < 4; ++n) bfr[n] = rd_std(b_ + (wc * 64 + n * 16 + fr) * 32 + fq * 8);
;       afc[0] = rd_std(ap_); afc[1] = rd_std(ap_ + 16 * 32);
;       __builtin_amdgcn_sched_barrier(0);
;       if (kt + 2 < nk) GEMM_ISSUE(kt + 2);
;       __builtin_amdgcn_sched_barrier(0);
; #pragma unroll
;       for (int mh = 0; mh < MF / 2; ++mh) {
;         if (mh + 1 < MF / 2) {
;           afn[0] = rd_std(ap_ + ((mh + 1) * 2) * 16 * 32);
;           afn[1] = rd_std(ap_ + ((mh + 1) * 2 + 1) * 16 * 32);
;         }
;         __builtin_amdgcn_sched_barrier(0);
; #pragma unroll
;         for (int m = 0; m < 2; ++m)
; #pragma unroll
;           for (int n = 0; n < 4; ++n) acc[mh * 2 + m][n] = MFMA(bfr[n], afc[m], acc[mh * 2 + m][n]);
;         __builtin_amdgcn_sched_barrier(0);
;         afc[0] = afn[0]; afc[1] = afn[1];
;       }
.LBB0_1998:
	s_mul_hi_u32 s21, s13, 0xaaaaaaab
	s_lshr_b32 s21, s21, 1
	s_mul_i32 s21, s21, 0x12000
	v_add_u32_e32 v146, s5, v161
	v_subrev_u32_e32 v147, s21, v164
	v_subrev_u32_e32 v148, s21, v160
	v_add_u32_e32 v170, v146, v147
	v_add_u32_e32 v190, v146, v148
	s_mul_hi_u32 s21, s12, 0xaaaaaaab
	s_add_i32 s13, s13, 1
	s_lshr_b32 s21, s21, 1
	s_mul_i32 s21, s21, 0x12000
	s_sub_i32 s21, s5, s21
	s_add_i32 s22, s21, 0xc000
	v_add_u32_e32 v178, s22, v154
	v_lshl_add_u64 v[150:151], v[136:137], 0, v[134:135]
	v_readfirstlane_b32 s101, v178
	v_lshl_add_u64 v[152:153], v[150:151], 0, s[74:75]
	v_lshl_add_u64 v[166:167], v[150:151], 0, s[56:57]
	v_lshl_add_u64 v[168:169], v[150:151], 0, s[58:59]
	v_lshl_add_u64 v[150:151], v[150:151], 0, s[86:87]
	v_lshl_add_u64 v[174:175], v[138:139], 0, v[134:135]
	v_lshl_add_u64 v[176:177], v[174:175], 0, s[74:75]
	v_lshl_add_u64 v[174:175], v[174:175], 0, s[56:57]
	s_waitcnt vmcnt(6)
	s_waitcnt lgkmcnt(0)
	s_barrier
	s_setprio 2
	s_mov_b32 m0, s101
	s_nop 0
	global_load_lds_dwordx4 v[152:153], off
	s_add_u32 m0, m0, 0x1000
	s_nop 0
	global_load_lds_dwordx4 v[166:167], off
	s_add_u32 m0, m0, 0x1000
	s_nop 0
	global_load_lds_dwordx4 v[168:169], off
	s_add_u32 m0, m0, 0x1000
	s_nop 0
	global_load_lds_dwordx4 v[150:151], off
	s_add_u32 m0, m0, 0x1000
	s_nop 0
	global_load_lds_dwordx4 v[176:177], off
	s_add_u32 m0, m0, 0x1000
	s_nop 0
	global_load_lds_dwordx4 v[174:175], off
	s_setprio 0
	ds_read_b128 v[146:149], v170 offset:16384
	ds_read_b128 v[150:153], v170 offset:17408
	ds_read_b128 v[166:169], v170 offset:18432
	ds_read_b128 v[170:173], v170 offset:19456
	ds_read_b128 v[174:177], v190
	ds_read_b128 v[178:181], v190 offset:1024
	ds_read_b128 v[182:185], v190 offset:3072
	ds_read_b128 v[186:189], v190 offset:2048
	s_waitcnt lgkmcnt(2)
	v_mfma_f32_16x16x32_bf16 v[126:129], v[146:149], v[174:177], v[126:129]
	v_mfma_f32_16x16x32_bf16 v[122:125], v[150:153], v[174:177], v[122:125]
	v_mfma_f32_16x16x32_bf16 v[118:121], v[166:169], v[174:177], v[118:121]
	v_mfma_f32_16x16x32_bf16 v[114:117], v[170:173], v[174:177], v[114:117]
	v_mfma_f32_16x16x32_bf16 v[110:113], v[146:149], v[178:181], v[110:113]
	v_mfma_f32_16x16x32_bf16 v[106:109], v[150:153], v[178:181], v[106:109]
	v_mfma_f32_16x16x32_bf16 v[102:105], v[166:169], v[178:181], v[102:105]
	v_mfma_f32_16x16x32_bf16 v[98:101], v[170:173], v[178:181], v[98:101]
	ds_read_b128 v[174:177], v190 offset:5120
	ds_read_b128 v[178:181], v190 offset:4096
	s_waitcnt lgkmcnt(2)
	v_mfma_f32_16x16x32_bf16 v[94:97], v[146:149], v[186:189], v[94:97]
	v_mfma_f32_16x16x32_bf16 v[90:93], v[150:153], v[186:189], v[90:93]
	v_mfma_f32_16x16x32_bf16 v[86:89], v[166:169], v[186:189], v[86:89]
	v_mfma_f32_16x16x32_bf16 v[82:85], v[170:173], v[186:189], v[82:85]
	v_mfma_f32_16x16x32_bf16 v[78:81], v[146:149], v[182:185], v[78:81]
	v_mfma_f32_16x16x32_bf16 v[74:77], v[150:153], v[182:185], v[74:77]
	v_mfma_f32_16x16x32_bf16 v[70:73], v[166:169], v[182:185], v[70:73]
	v_mfma_f32_16x16x32_bf16 v[66:69], v[170:173], v[182:185], v[66:69]
	ds_read_b128 v[182:185], v190 offset:7168
	ds_read_b128 v[186:189], v190 offset:6144
	s_waitcnt lgkmcnt(2)
	v_mfma_f32_16x16x32_bf16 v[62:65], v[146:149], v[178:181], v[62:65]
	v_mfma_f32_16x16x32_bf16 v[58:61], v[150:153], v[178:181], v[58:61]
	v_mfma_f32_16x16x32_bf16 v[54:57], v[166:169], v[178:181], v[54:57]
	v_mfma_f32_16x16x32_bf16 v[50:53], v[170:173], v[178:181], v[50:53]
	v_mfma_f32_16x16x32_bf16 v[46:49], v[146:149], v[174:177], v[46:49]
	v_mfma_f32_16x16x32_bf16 v[42:45], v[150:153], v[174:177], v[42:45]
	v_mfma_f32_16x16x32_bf16 v[38:41], v[166:169], v[174:177], v[38:41]
	v_mfma_f32_16x16x32_bf16 v[34:37], v[170:173], v[174:177], v[34:37]
	s_waitcnt lgkmcnt(0)
	v_mfma_f32_16x16x32_bf16 v[30:33], v[146:149], v[186:189], v[30:33]
	v_mfma_f32_16x16x32_bf16 v[26:29], v[150:153], v[186:189], v[26:29]
	v_mfma_f32_16x16x32_bf16 v[22:25], v[166:169], v[186:189], v[22:25]
	v_mfma_f32_16x16x32_bf16 v[18:21], v[170:173], v[186:189], v[18:21]
	v_mfma_f32_16x16x32_bf16 v[14:17], v[146:149], v[182:185], v[14:17]
	v_mfma_f32_16x16x32_bf16 v[10:13], v[150:153], v[182:185], v[10:13]
	v_mfma_f32_16x16x32_bf16 v[6:9], v[166:169], v[182:185], v[6:9]
	v_mfma_f32_16x16x32_bf16 v[2:5], v[170:173], v[182:185], v[2:5]
	s_addk_i32 s5, 0x6000
	s_add_i32 s11, s11, 1
	s_add_i32 s12, s12, 1
	v_lshl_add_u64 v[136:137], v[136:137], 0, 64
	v_lshl_add_u64 v[136:137], v[136:137], 0, 64
	s_cmp_eq_u32 s5, 0x204000
	v_lshl_add_u64 v[138:139], v[138:139], 0, 64
	v_lshl_add_u64 v[138:139], v[138:139], 0, 64
	s_cbranch_scc0 .LBB0_1998
	s_waitcnt vmcnt(6)
	s_waitcnt lgkmcnt(0)
	s_barrier
; #define MFMA(a, b, c) __builtin_amdgcn_mfma_f32_16x16x32_bf16((a), (b), (c), 0, 0, 0)
; template <int EPI, int MF>
; __device__ __forceinline__ void gemm_part(const u16* __restrict__ A, int lda, const u16* __restrict__ Bt, int K, int ntn, GemmEpi ep, char* smem,
;                                           int mbase, int mrows) {
;     ...
;     for (int kt = 0; kt < nk; ++kt) {
;       if (kt + 1 < nk) {
;         if (MF == 8) asm volatile("s_waitcnt vmcnt(6)" ::: "memory");
;         else asm volatile("s_waitcnt vmcnt(3)" ::: "memory");
;       } else asm volatile("s_waitcnt vmcnt(0)" ::: "memory");
;       asm volatile("s_waitcnt lgkmcnt(0)" ::: "memory");
;       __builtin_amdgcn_s_barrier();
;       const u16* a_ = sbase + (kt % 3) * STG;
;       const u16* b_ = a_ + BM * 32;
;       bf16x8 bfr[4], afc[2], afn[2];
;       const u16* ap_ = a_ + (wr * (16 * MF) + fr) * 32 + fq * 8;
; #pragma unroll
;       for (int n = 0; n < 4; ++n) bfr[n] = rd_std(b_ + (wc * 64 + n * 16 + fr) * 32 + fq * 8);
;       afc[0] = rd_std(ap_); afc[1] = rd_std(ap_ + 16 * 32);
;       __builtin_amdgcn_sched_barrier(0);
;       if (kt + 2 < nk) GEMM_ISSUE(kt + 2);
;       __builtin_amdgcn_sched_barrier(0);
; #pragma unroll
;       for (int mh = 0; mh < MF / 2; ++mh) {
;         if (mh + 1 < MF / 2) {
;           afn[0] = rd_std(ap_ + ((mh + 1) * 2) * 16 * 32);
;           afn[1] = rd_std(ap_ + ((mh + 1) * 2 + 1) * 16 * 32);
;         }
;         __builtin_amdgcn_sched_barrier(0);
; #pragma unroll
;         for (int m = 0; m < 2; ++m)
; #pragma unroll
;           for (int n = 0; n < 4; ++n) acc[mh * 2 + m][n] = MFMA(bfr[n], afc[m], acc[mh * 2 + m][n]);
;         __builtin_amdgcn_sched_barrier(0);
;         afc[0] = afn[0]; afc[1] = afn[1];
;       }
	ds_read_b128 v[136:139], v165
	ds_read_b128 v[146:149], v165 offset:1024
	ds_read_b128 v[150:153], v165 offset:2048
	ds_read_b128 v[166:169], v165 offset:3072
	ds_read_b128 v[170:173], v162 offset:49152
	ds_read_b128 v[174:177], v162 offset:50176
	s_mul_hi_u32 s11, s11, 0xaaaaaaab
	s_lshr_b32 s11, s11, 1
	s_mul_i32 s11, s11, 0x12000
	s_sub_i32 s5, s5, s11
	s_add_i32 s5, s5, 0
	s_addk_i32 s5, 0x6000
	ds_read_b128 v[178:181], v162 offset:52224
	ds_read_b128 v[182:185], v162 offset:51200
	s_waitcnt lgkmcnt(0)
	v_mfma_f32_16x16x32_bf16 v[126:129], v[136:139], v[170:173], v[126:129]
	v_mfma_f32_16x16x32_bf16 v[122:125], v[146:149], v[170:173], v[122:125]
	v_mfma_f32_16x16x32_bf16 v[118:121], v[150:153], v[170:173], v[118:121]
	v_mfma_f32_16x16x32_bf16 v[114:117], v[166:169], v[170:173], v[114:117]
	v_mfma_f32_16x16x32_bf16 v[110:113], v[136:139], v[174:177], v[110:113]
	v_mfma_f32_16x16x32_bf16 v[106:109], v[146:149], v[174:177], v[106:109]
	v_mfma_f32_16x16x32_bf16 v[102:105], v[150:153], v[174:177], v[102:105]
	v_mfma_f32_16x16x32_bf16 v[98:101], v[166:169], v[174:177], v[98:101]
	ds_read_b128 v[170:173], v162 offset:54272
	ds_read_b128 v[174:177], v162 offset:53248
	v_mfma_f32_16x16x32_bf16 v[94:97], v[136:139], v[182:185], v[94:97]
	v_mfma_f32_16x16x32_bf16 v[90:93], v[146:149], v[182:185], v[90:93]
	v_mfma_f32_16x16x32_bf16 v[86:89], v[150:153], v[182:185], v[86:89]
	v_mfma_f32_16x16x32_bf16 v[82:85], v[166:169], v[182:185], v[82:85]
	v_mfma_f32_16x16x32_bf16 v[78:81], v[136:139], v[178:181], v[78:81]
	v_mfma_f32_16x16x32_bf16 v[74:77], v[146:149], v[178:181], v[74:77]
	v_mfma_f32_16x16x32_bf16 v[70:73], v[150:153], v[178:181], v[70:73]
	v_mfma_f32_16x16x32_bf16 v[66:69], v[166:169], v[178:181], v[66:69]
	ds_read_b128 v[178:181], v162 offset:56320
	ds_read_b128 v[182:185], v162 offset:55296
	s_waitcnt lgkmcnt(0)
	v_mfma_f32_16x16x32_bf16 v[62:65], v[136:139], v[174:177], v[62:65]
	v_mfma_f32_16x16x32_bf16 v[58:61], v[146:149], v[174:177], v[58:61]
	v_mfma_f32_16x16x32_bf16 v[54:57], v[150:153], v[174:177], v[54:57]
	v_mfma_f32_16x16x32_bf16 v[50:53], v[166:169], v[174:177], v[50:53]
	v_mfma_f32_16x16x32_bf16 v[46:49], v[136:139], v[170:173], v[46:49]
	v_mfma_f32_16x16x32_bf16 v[42:45], v[146:149], v[170:173], v[42:45]
	v_mfma_f32_16x16x32_bf16 v[38:41], v[150:153], v[170:173], v[38:41]
	v_mfma_f32_16x16x32_bf16 v[34:37], v[166:169], v[170:173], v[34:37]
	v_mfma_f32_16x16x32_bf16 v[30:33], v[136:139], v[182:185], v[30:33]
	v_mfma_f32_16x16x32_bf16 v[26:29], v[146:149], v[182:185], v[26:29]
	v_mfma_f32_16x16x32_bf16 v[22:25], v[150:153], v[182:185], v[22:25]
	v_mfma_f32_16x16x32_bf16 v[18:21], v[166:169], v[182:185], v[18:21]
	v_mfma_f32_16x16x32_bf16 v[14:17], v[136:139], v[178:181], v[14:17]
	v_mfma_f32_16x16x32_bf16 v[10:13], v[146:149], v[178:181], v[10:13]
	v_mfma_f32_16x16x32_bf16 v[6:9], v[150:153], v[178:181], v[6:9]
	v_mfma_f32_16x16x32_bf16 v[2:5], v[166:169], v[178:181], v[2:5]
	v_add_u32_e32 v136, s5, v161
	s_waitcnt vmcnt(0)
	v_add3_u32 v166, v136, v158, v159
	s_waitcnt lgkmcnt(0)
	s_barrier
; #define MFMA(a, b, c) __builtin_amdgcn_mfma_f32_16x16x32_bf16((a), (b), (c), 0, 0, 0)
; template <int EPI, int MF>
; __device__ __forceinline__ void gemm_part(const u16* __restrict__ A, int lda, const u16* __restrict__ Bt, int K, int ntn, GemmEpi ep, char* smem,
;                                           int mbase, int mrows) {
;     ...
;     for (int kt = 0; kt < nk; ++kt) {
;       if (kt + 1 < nk) {
;         if (MF == 8) asm volatile("s_waitcnt vmcnt(6)" ::: "memory");
;         else asm volatile("s_waitcnt vmcnt(3)" ::: "memory");
;       } else asm volatile("s_waitcnt vmcnt(0)" ::: "memory");
;       asm volatile("s_waitcnt lgkmcnt(0)" ::: "memory");
;       __builtin_amdgcn_s_barrier();
;       const u16* a_ = sbase + (kt % 3) * STG;
;       const u16* b_ = a_ + BM * 32;
;       bf16x8 bfr[4], afc[2], afn[2];
;       const u16* ap_ = a_ + (wr * (16 * MF) + fr) * 32 + fq * 8;
; #pragma unroll
;       for (int n = 0; n < 4; ++n) bfr[n] = rd_std(b_ + (wc * 64 + n * 16 + fr) * 32 + fq * 8);
;       afc[0] = rd_std(ap_); afc[1] = rd_std(ap_ + 16 * 32);
;       __builtin_amdgcn_sched_barrier(0);
;       if (kt + 2 < nk) GEMM_ISSUE(kt + 2);
;       __builtin_amdgcn_sched_barrier(0);
; #pragma unroll
;       for (int mh = 0; mh < MF / 2; ++mh) {
;         if (mh + 1 < MF / 2) {
;           afn[0] = rd_std(ap_ + ((mh + 1) * 2) * 16 * 32);
;           afn[1] = rd_std(ap_ + ((mh + 1) * 2 + 1) * 16 * 32);
;         }
;         __builtin_amdgcn_sched_barrier(0);
; #pragma unroll
;         for (int m = 0; m < 2; ++m)
; #pragma unroll
;           for (int n = 0; n < 4; ++n) acc[mh * 2 + m][n] = MFMA(bfr[n], afc[m], acc[mh * 2 + m][n]);
;         __builtin_amdgcn_sched_barrier(0);
;         afc[0] = afn[0]; afc[1] = afn[1];
;       }
;     ...
;       } else if (EPI == EPI_RESID) {
;         const float* rp = (row < MP) ? ep.res0 + (size_t)row * DM : ep.res1 + (size_t)(row - MP) * DM;
;         float ssq = 0.f;
; #pragma unroll
;         for (int n = 0; n < 4; ++n) {
;           const int col = cb + n * 16;
;           const float4 r = *(const float4*)(rp + col);
;           float4 v;
;           v.x = r.x + ep.scale * acc[m][n][0]; v.y = r.y + ep.scale * acc[m][n][1];
;           v.z = r.z + ep.scale * acc[m][n][2]; v.w = r.w + ep.scale * acc[m][n][3];
;           *(float4*)(ep.outf + (size_t)row * DM + col) = v;
;           if (ep.xcopy) {
;             bf16x4 o;
	ds_read_b128 v[136:139], v166 offset:16384
	ds_read_b128 v[146:149], v166 offset:17408
	ds_read_b128 v[150:153], v166 offset:18432
	ds_read_b128 v[166:169], v166 offset:19456
	ds_read_b128 v[170:173], v162
	ds_read_b128 v[174:177], v162 offset:1024
	ds_read_b128 v[178:181], v162 offset:3072
	ds_read_b128 v[182:185], v162 offset:2048
	s_waitcnt lgkmcnt(0)
	v_mfma_f32_16x16x32_bf16 v[126:129], v[136:139], v[170:173], v[126:129]
	v_mfma_f32_16x16x32_bf16 v[122:125], v[146:149], v[170:173], v[122:125]
	v_mfma_f32_16x16x32_bf16 v[118:121], v[150:153], v[170:173], v[118:121]
	v_mfma_f32_16x16x32_bf16 v[114:117], v[166:169], v[170:173], v[114:117]
	v_mfma_f32_16x16x32_bf16 v[110:113], v[136:139], v[174:177], v[110:113]
	v_mfma_f32_16x16x32_bf16 v[106:109], v[146:149], v[174:177], v[106:109]
	v_mfma_f32_16x16x32_bf16 v[102:105], v[150:153], v[174:177], v[102:105]
	v_mfma_f32_16x16x32_bf16 v[98:101], v[166:169], v[174:177], v[98:101]
	ds_read_b128 v[170:173], v162 offset:5120
	ds_read_b128 v[174:177], v162 offset:4096
	v_mfma_f32_16x16x32_bf16 v[94:97], v[136:139], v[182:185], v[94:97]
	v_mfma_f32_16x16x32_bf16 v[90:93], v[146:149], v[182:185], v[90:93]
	v_mfma_f32_16x16x32_bf16 v[86:89], v[150:153], v[182:185], v[86:89]
	v_mfma_f32_16x16x32_bf16 v[82:85], v[166:169], v[182:185], v[82:85]
	v_mfma_f32_16x16x32_bf16 v[78:81], v[136:139], v[178:181], v[78:81]
	v_mfma_f32_16x16x32_bf16 v[74:77], v[146:149], v[178:181], v[74:77]
	v_mfma_f32_16x16x32_bf16 v[70:73], v[150:153], v[178:181], v[70:73]
	v_mfma_f32_16x16x32_bf16 v[66:69], v[166:169], v[178:181], v[66:69]
	ds_read_b128 v[178:181], v162 offset:7168
	ds_read_b128 v[182:185], v162 offset:6144
	s_waitcnt lgkmcnt(0)
	v_mfma_f32_16x16x32_bf16 v[62:65], v[136:139], v[174:177], v[62:65]
	v_mfma_f32_16x16x32_bf16 v[58:61], v[146:149], v[174:177], v[58:61]
	v_mfma_f32_16x16x32_bf16 v[54:57], v[150:153], v[174:177], v[54:57]
	v_mfma_f32_16x16x32_bf16 v[50:53], v[166:169], v[174:177], v[50:53]
	v_mfma_f32_16x16x32_bf16 v[46:49], v[136:139], v[170:173], v[46:49]
	v_mfma_f32_16x16x32_bf16 v[42:45], v[146:149], v[170:173], v[42:45]
	v_mfma_f32_16x16x32_bf16 v[38:41], v[150:153], v[170:173], v[38:41]
	v_mfma_f32_16x16x32_bf16 v[34:37], v[166:169], v[170:173], v[34:37]
	v_mfma_f32_16x16x32_bf16 v[30:33], v[136:139], v[182:185], v[30:33]
	v_mfma_f32_16x16x32_bf16 v[26:29], v[146:149], v[182:185], v[26:29]
	v_mfma_f32_16x16x32_bf16 v[22:25], v[150:153], v[182:185], v[22:25]
	v_mfma_f32_16x16x32_bf16 v[18:21], v[166:169], v[182:185], v[18:21]
	v_mfma_f32_16x16x32_bf16 v[14:17], v[136:139], v[178:181], v[14:17]
	v_mfma_f32_16x16x32_bf16 v[10:13], v[146:149], v[178:181], v[10:13]
	v_mfma_f32_16x16x32_bf16 v[6:9], v[150:153], v[178:181], v[6:9]
	v_mfma_f32_16x16x32_bf16 v[2:5], v[166:169], v[178:181], v[2:5]
	v_add_u32_e32 v138, s4, v156
	s_waitcnt vmcnt(0)
	s_barrier
	s_mov_b32 s4, 0xffff
	v_cmp_lt_i32_e32 vcc, s4, v138
	s_and_saveexec_b64 s[4:5], vcc
	s_xor_b64 s[4:5], exec, s[4:5]
	v_add_u32_e32 v136, 0xffff0000, v138
	v_mov_b32_e32 v137, v0
	v_lshlrev_b64 v[136:137], 12, v[136:137]
	v_lshl_add_u64 v[136:137], s[72:73], 0, v[136:137]
	v_mov_b32_e32 v139, v0
	s_andn2_saveexec_b64 s[4:5], s[4:5]
	v_ashrrev_i32_e32 v139, 31, v138
	v_lshlrev_b64 v[136:137], 12, v[138:139]
	v_lshl_add_u64 v[136:137], s[26:27], 0, v[136:137]
	s_or_b64 exec, exec, s[4:5]
	v_lshlrev_b64 v[146:147], 12, v[138:139]
	v_or_b32_e32 v170, s10, v157
	v_lshl_add_u64 v[150:151], s[26:27], 0, v[146:147]
	v_lshlrev_b64 v[146:147], 11, v[138:139]
	v_lshl_add_u64 v[148:149], s[14:15], 0, v[146:147]
	v_lshlrev_b32_e32 v146, 2, v170
	v_mov_b32_e32 v147, v0
	v_lshl_add_u64 v[152:153], v[136:137], 0, v[146:147]
	global_load_dwordx4 v[166:169], v[152:153], off
	global_load_dwordx4 v[172:175], v[152:153], off offset:64
	global_load_dwordx4 v[176:179], v[152:153], off offset:128
	global_load_dwordx4 v[180:183], v[152:153], off offset:192
	v_cndmask_b32_e64 v136, 0, 1, s[2:3]
	v_lshl_add_u64 v[150:151], v[150:151], 0, v[146:147]
	v_cmp_ne_u32_e64 s[10:11], 1, v136
	s_andn2_b64 vcc, exec, s[2:3]
	v_lshlrev_b32_e32 v136, 1, v170
	s_waitcnt vmcnt(0)
	v_pk_fma_f32 v[126:127], v[126:127], 0.5, v[166:167] op_sel_hi:[1,0,1]
	v_pk_fma_f32 v[128:129], v[128:129], 0.5, v[168:169] op_sel_hi:[1,0,1]
	global_store_dwordx4 v[150:151], v[126:129], off
	s_cbranch_vccnz .LBB0_2005
	v_mov_b32_e32 v137, v0
	v_cvt_pk_bf16_f32 v166, v126, v127
	v_cvt_pk_bf16_f32 v167, v128, v129
	v_lshl_add_u64 v[168:169], v[148:149], 0, v[136:137]
	v_lshlrev_b32_e32 v184, 1, v168
	v_bfi_b32 v184, s100, v184, v168
	v_lshrrev_b32_e32 v185, 5, v168
	v_bfi_b32 v184, 64, v185, v184
	v_mov_b32_e32 v185, v169
	global_store_dwordx2 v[184:185], v[166:167], off
